# GEMM K loops: per-phase s_setprio flips removed, waves 4-7 run at a static priority 1 set once per tile; code addresses unchanged
# speedup vs baseline: 1.0059x; 1.0052x over previous
; #define PG8_STAGE(bufoff, gbase, voff) do { _Pragma("unroll") for (int _i = 0; _i < 2; ++_i) \
;         __builtin_amdgcn_global_load_lds((const unsigned*)((const char*)(gbase) + (voff)[_i]), (PG8_LAS unsigned*)(lds + (bufoff) + ldsw + _i * 8192), 16, 0, 0); } while (0)
; #define PG8_LDA(dst, b, h) do { _Pragma("unroll") for (int m = 0; m < 4; ++m) _Pragma("unroll") for (int k = 0; k < 2; ++k) dst[m][k] = *(const PG8_LAS bf16x8*)(lds + PG8_SA(b, h) + aoff + m * 2048 + k * 1024); } while (0)
; #define PG8_LDB(dst, b, h) do { _Pragma("unroll") for (int n = 0; n < 2; ++n) _Pragma("unroll") for (int k = 0; k < 2; ++k) dst[n][k] = *(const PG8_LAS bf16x8*)(lds + PG8_SB(b, h) + boff + n * 2048 + k * 1024); } while (0)
; #define PG8_MMA(ai, bj, At, Bt) do { __builtin_amdgcn_s_setprio(1); _Pragma("unroll") for (int m = 0; m < 4; ++m) _Pragma("unroll") for (int n = 0; n < 2; ++n) _Pragma("unroll") for (int k = 0; k < 2; ++k) \
;         acc[ai][bj][m][n] = __builtin_amdgcn_mfma_f32_16x16x32_bf16(Bt[n][k], At[m][k], acc[ai][bj][m][n], 0, 0, 0); __builtin_amdgcn_s_setprio(0); } while (0)
; #define PG8_WAIT_L(n) asm volatile("s_waitcnt lgkmcnt(" #n ")" ::: "memory")
; #define PG8_BAR __builtin_amdgcn_s_barrier()
; #define PG8_SCHED __builtin_amdgcn_sched_barrier(0)
; template <class Epi, class Sched>
; __device__ __forceinline__ void gemm_phase(PG8_LAS unsigned char* lds, const Gemm g, const Sched& S, const Epi& E, const int tid) {
;     ...
;     f32x4 acc[2][2][4][2];
; #pragma unroll
;     for (int a = 0; a < 2; ++a)
; #pragma unroll
;         for (int b = 0; b < 2; ++b)
; #pragma unroll
;             for (int m = 0; m < 4; ++m)
; #pragma unroll
;                 for (int n = 0; n < 2; ++n) acc[a][b][m][n] = (f32x4){0.f, 0.f, 0.f, 0.f};
;     ...
;         for (int t = 0; t < nt; t += 2) {
;             const bool last = (t == nt - 2);
;             const char* a1 = cA + (size_t)(t + 1) * kstep;
;             const char* a2 = last ? nA : cA + (size_t)(t + 2) * kstep; const char* b2 = last ? nB : cB + (size_t)(t + 2) * kstep;
;             const char* a3 = a2 + kstep; const char* b3 = b2 + kstep;
;             if (last && has_next) S.a_ready(nxt);
;             PG8_LDB(B0, 0, 0); PG8_SCHED; PG8_LDA(At, 0, 0); PG8_STAGE(PG8_SA(1, 1), a1 + hstep, voffA);
;             PG8_WAIT_L(8); PG8_BAR; PG8_WAIT_L(0); PG8_MMA(0, 0, At, B0); PG8_BAR; PG8_SCHED;
.LBB0_36:
	s_ashr_i32 s19, s18, 31
	s_lshl_b64 s[34:35], s[18:19], 19
	s_add_u32 s72, s45, s34
	s_addc_u32 s73, s64, s35
	s_and_b64 s[6:7], s[6:7], exec
	s_cselect_b32 s9, s73, s11
	s_cselect_b32 s19, s72, s10
	s_add_u32 s6, s76, 0x40080
	s_addc_u32 s7, s77, 0
	s_add_u32 s34, s10, 0x100
	v_mov_b32_e32 v2, 0
	s_addc_u32 s35, s11, 0
	s_mov_b32 s63, -2
	v_mov_b32_e32 v3, v2
	v_mov_b32_e32 v4, v2
	v_mov_b32_e32 v5, v2
	v_mov_b32_e32 v6, v2
	v_mov_b32_e32 v7, v2
	v_mov_b32_e32 v8, v2
	v_mov_b32_e32 v9, v2
	v_mov_b32_e32 v18, v2
	v_mov_b32_e32 v19, v2
	v_mov_b32_e32 v20, v2
	v_mov_b32_e32 v21, v2
	v_mov_b32_e32 v22, v2
	v_mov_b32_e32 v23, v2
	v_mov_b32_e32 v24, v2
	v_mov_b32_e32 v25, v2
	v_mov_b32_e32 v34, v2
	v_mov_b32_e32 v35, v2
	v_mov_b32_e32 v36, v2
	v_mov_b32_e32 v37, v2
	v_mov_b32_e32 v38, v2
	v_mov_b32_e32 v39, v2
	v_mov_b32_e32 v40, v2
	v_mov_b32_e32 v41, v2
	v_mov_b32_e32 v50, v2
	v_mov_b32_e32 v51, v2
	v_mov_b32_e32 v52, v2
	v_mov_b32_e32 v53, v2
	v_mov_b32_e32 v54, v2
	v_mov_b32_e32 v55, v2
	v_mov_b32_e32 v56, v2
	v_mov_b32_e32 v57, v2
	v_mov_b32_e32 v10, v2
	v_mov_b32_e32 v11, v2
	v_mov_b32_e32 v12, v2
	v_mov_b32_e32 v13, v2
	v_mov_b32_e32 v14, v2
	v_mov_b32_e32 v15, v2
	s_waitcnt lgkmcnt(0)
	v_mov_b32_e32 v16, v2
	v_mov_b32_e32 v17, v2
	v_mov_b32_e32 v26, v2
	v_mov_b32_e32 v27, v2
	v_mov_b32_e32 v28, v2
	v_mov_b32_e32 v29, v2
	v_mov_b32_e32 v30, v2
	v_mov_b32_e32 v31, v2
	v_mov_b32_e32 v32, v2
	v_mov_b32_e32 v33, v2
	v_mov_b32_e32 v42, v2
	v_mov_b32_e32 v43, v2
	v_mov_b32_e32 v44, v2
	v_mov_b32_e32 v45, v2
	v_mov_b32_e32 v46, v2
	v_mov_b32_e32 v47, v2
	v_mov_b32_e32 v48, v2
	v_mov_b32_e32 v49, v2
	v_mov_b32_e32 v58, v2
	v_mov_b32_e32 v59, v2
	v_mov_b32_e32 v60, v2
	v_mov_b32_e32 v61, v2
	v_mov_b32_e32 v62, v2
	v_mov_b32_e32 v63, v2
	v_mov_b32_e32 v64, v2
	v_mov_b32_e32 v65, v2
	v_mov_b32_e32 v66, v2
	v_mov_b32_e32 v67, v2
	v_mov_b32_e32 v68, v2
	v_mov_b32_e32 v69, v2
	v_mov_b32_e32 v70, v2
	v_mov_b32_e32 v71, v2
	v_mov_b32_e32 v72, v2
	v_mov_b32_e32 v73, v2
	v_mov_b32_e32 v82, v2
	v_mov_b32_e32 v83, v2
	v_mov_b32_e32 v84, v2
	v_mov_b32_e32 v85, v2
	v_mov_b32_e32 v86, v2
	v_mov_b32_e32 v87, v2
	v_mov_b32_e32 v88, v2
	v_mov_b32_e32 v89, v2
	v_mov_b32_e32 v98, v2
	v_mov_b32_e32 v99, v2
	v_mov_b32_e32 v100, v2
	v_mov_b32_e32 v101, v2
	v_mov_b32_e32 v102, v2
	v_mov_b32_e32 v103, v2
	v_mov_b32_e32 v104, v2
	v_mov_b32_e32 v105, v2
	v_mov_b32_e32 v114, v2
	v_mov_b32_e32 v115, v2
	v_mov_b32_e32 v116, v2
	v_mov_b32_e32 v117, v2
	v_mov_b32_e32 v118, v2
	v_mov_b32_e32 v119, v2
	v_mov_b32_e32 v120, v2
	v_mov_b32_e32 v121, v2
	v_mov_b32_e32 v74, v2
	v_mov_b32_e32 v75, v2
	v_mov_b32_e32 v76, v2
	v_mov_b32_e32 v77, v2
	v_mov_b32_e32 v78, v2
	v_mov_b32_e32 v79, v2
	v_mov_b32_e32 v80, v2
	v_mov_b32_e32 v81, v2
	v_mov_b32_e32 v90, v2
	v_mov_b32_e32 v91, v2
	v_mov_b32_e32 v92, v2
	v_mov_b32_e32 v93, v2
	v_mov_b32_e32 v94, v2
	v_mov_b32_e32 v95, v2
	v_mov_b32_e32 v96, v2
	v_mov_b32_e32 v97, v2
	v_mov_b32_e32 v106, v2
	v_mov_b32_e32 v107, v2
	v_mov_b32_e32 v108, v2
	v_mov_b32_e32 v109, v2
	v_mov_b32_e32 v110, v2
	v_mov_b32_e32 v111, v2
	v_mov_b32_e32 v112, v2
	v_mov_b32_e32 v113, v2
	v_mov_b32_e32 v122, v2
	v_mov_b32_e32 v123, v2
	v_mov_b32_e32 v124, v2
	v_mov_b32_e32 v125, v2
	v_mov_b32_e32 v126, v2
	v_mov_b32_e32 v127, v2
	v_mov_b32_e32 v128, v2
	v_mov_b32_e32 v129, v2
	v_readlane_b32 s101, v254, 14
	s_bitcmp1_b32 s101, 0
	s_cbranch_scc0 .Lprio_skip0
	s_setprio 1
.Lprio_skip0:
	s_nop 0
	s_nop 0
	s_nop 0
	s_nop 0
	s_nop 0
	s_nop 0
	s_nop 0
	s_nop 0
	s_nop 0
	s_nop 0
	s_nop 0
.LBB0_37:
	s_add_u32 s10, s6, 0xfffc0080
	s_addc_u32 s11, s7, -1
	s_add_i32 s76, 0, 0x10000
	v_add_u32_e32 v0, s76, v141
	ds_read_b128 v[162:165], v0
	ds_read_b128 v[168:171], v0 offset:1024
	ds_read_b128 v[172:175], v0 offset:2048
	ds_read_b128 v[176:179], v0 offset:3072
	s_cmp_eq_u32 s63, 12
	s_cselect_b32 s57, s69, s11
	s_cselect_b32 s56, s68, s10
	s_cselect_b32 s11, s9, s35
	s_cselect_b32 s10, s19, s34
	v_lshl_add_u64 v[196:197], s[6:7], 0, v[158:159]
	s_add_i32 m0, s90, 0xc000
	ds_read_b128 v[180:183], v166
	ds_read_b128 v[184:187], v166 offset:1024
	ds_read_b128 v[188:191], v166 offset:2048
	ds_read_b128 v[192:195], v166 offset:3072
	ds_read_b128 v[200:203], v166 offset:4096
	ds_read_b128 v[216:219], v166 offset:5120
	ds_read_b128 v[220:223], v166 offset:6144
	ds_read_b128 v[224:227], v166 offset:7168
	global_load_lds_dwordx4 v[196:197], off
	v_lshl_add_u64 v[196:197], s[6:7], 0, v[160:161]
	s_add_i32 m0, s90, 0xe000
	s_nop 0
	global_load_lds_dwordx4 v[196:197], off
	s_waitcnt lgkmcnt(8)
	s_barrier
	s_waitcnt lgkmcnt(0)
	s_waitcnt lgkmcnt(0)
	v_mfma_f32_16x16x32_bf16 v[126:129], v[162:165], v[180:183], v[126:129]
	v_mfma_f32_16x16x32_bf16 v[122:125], v[172:175], v[180:183], v[122:125]
	v_mfma_f32_16x16x32_bf16 v[110:113], v[162:165], v[188:191], v[110:113]
	v_mfma_f32_16x16x32_bf16 v[106:109], v[172:175], v[188:191], v[106:109]
	v_mfma_f32_16x16x32_bf16 v[94:97], v[162:165], v[200:203], v[94:97]
	v_mfma_f32_16x16x32_bf16 v[90:93], v[172:175], v[200:203], v[90:93]
	v_mfma_f32_16x16x32_bf16 v[78:81], v[162:165], v[220:223], v[78:81]
	v_mfma_f32_16x16x32_bf16 v[74:77], v[172:175], v[220:223], v[74:77]
	v_mfma_f32_16x16x32_bf16 v[126:129], v[168:171], v[184:187], v[126:129]
	v_mfma_f32_16x16x32_bf16 v[122:125], v[176:179], v[184:187], v[122:125]
	v_mfma_f32_16x16x32_bf16 v[110:113], v[168:171], v[192:195], v[110:113]
	v_mfma_f32_16x16x32_bf16 v[106:109], v[176:179], v[192:195], v[106:109]
	v_mfma_f32_16x16x32_bf16 v[94:97], v[168:171], v[216:219], v[94:97]
	v_mfma_f32_16x16x32_bf16 v[90:93], v[176:179], v[216:219], v[90:93]
	v_mfma_f32_16x16x32_bf16 v[78:81], v[168:171], v[224:227], v[78:81]
	v_mfma_f32_16x16x32_bf16 v[74:77], v[176:179], v[224:227], v[74:77]
	s_barrier
; #define PG8_STAGE(bufoff, gbase, voff) do { _Pragma("unroll") for (int _i = 0; _i < 2; ++_i) \
;         __builtin_amdgcn_global_load_lds((const unsigned*)((const char*)(gbase) + (voff)[_i]), (PG8_LAS unsigned*)(lds + (bufoff) + ldsw + _i * 8192), 16, 0, 0); } while (0)
; #define PG8_LDA(dst, b, h) do { _Pragma("unroll") for (int m = 0; m < 4; ++m) _Pragma("unroll") for (int k = 0; k < 2; ++k) dst[m][k] = *(const PG8_LAS bf16x8*)(lds + PG8_SA(b, h) + aoff + m * 2048 + k * 1024); } while (0)
; #define PG8_LDB(dst, b, h) do { _Pragma("unroll") for (int n = 0; n < 2; ++n) _Pragma("unroll") for (int k = 0; k < 2; ++k) dst[n][k] = *(const PG8_LAS bf16x8*)(lds + PG8_SB(b, h) + boff + n * 2048 + k * 1024); } while (0)
; #define PG8_MMA(ai, bj, At, Bt) do { __builtin_amdgcn_s_setprio(1); _Pragma("unroll") for (int m = 0; m < 4; ++m) _Pragma("unroll") for (int n = 0; n < 2; ++n) _Pragma("unroll") for (int k = 0; k < 2; ++k) \
;         acc[ai][bj][m][n] = __builtin_amdgcn_mfma_f32_16x16x32_bf16(Bt[n][k], At[m][k], acc[ai][bj][m][n], 0, 0, 0); __builtin_amdgcn_s_setprio(0); } while (0)
; #define PG8_WAIT_V(n) asm volatile("s_waitcnt vmcnt(" #n ")" ::: "memory")
; #define PG8_WAIT_L(n) asm volatile("s_waitcnt lgkmcnt(" #n ")" ::: "memory")
; #define PG8_BAR __builtin_amdgcn_s_barrier()
; #define PG8_SCHED __builtin_amdgcn_sched_barrier(0)
; template <class Epi, class Sched>
; __device__ __forceinline__ void gemm_phase(PG8_LAS unsigned char* lds, const Gemm g, const Sched& S, const Epi& E, const int tid) {
;     ...
;             PG8_LDB(B1, 0, 1); PG8_STAGE(PG8_SB(0, 0), b2, voffB);
;             PG8_BAR; PG8_WAIT_L(0); PG8_MMA(0, 1, At, B1); PG8_BAR;
;             PG8_LDA(At, 0, 1); PG8_STAGE(PG8_SA(0, 0), a2, voffA);
;             PG8_BAR; PG8_WAIT_L(0); PG8_MMA(1, 0, At, B0); PG8_BAR; PG8_SCHED;
;             PG8_STAGE(PG8_SB(0, 1), b2 + hstep, voffB);
;             PG8_WAIT_V(6); PG8_BAR; PG8_MMA(1, 1, At, B1); PG8_BAR;
;             PG8_LDB(B0, 1, 0); PG8_SCHED; PG8_LDA(At, 1, 0); PG8_STAGE(PG8_SA(0, 1), a2 + hstep, voffA);
;             PG8_WAIT_L(8); PG8_BAR; PG8_WAIT_L(0); PG8_MMA(0, 0, At, B0); PG8_BAR; PG8_SCHED;
	s_add_i32 s84, 0, 0x14000
	s_add_i32 s76, s76, s65
	v_add_u32_e32 v0, s84, v141
	v_lshl_add_u64 v[196:197], s[10:11], 0, v[134:135]
	s_mov_b32 m0, s76
	ds_read_b128 v[228:231], v0
	ds_read_b128 v[232:235], v0 offset:1024
	ds_read_b128 v[236:239], v0 offset:2048
	ds_read_b128 v[246:249], v0 offset:3072
	global_load_lds_dwordx4 v[196:197], off
	v_lshl_add_u64 v[198:199], s[10:11], 0, v[130:131]
	s_add_i32 m0, s76, 0x2000
	s_nop 0
	global_load_lds_dwordx4 v[198:199], off
	s_barrier
	s_waitcnt lgkmcnt(0)
	s_waitcnt lgkmcnt(0)
	v_mfma_f32_16x16x32_bf16 v[118:121], v[228:231], v[180:183], v[118:121]
	v_mfma_f32_16x16x32_bf16 v[114:117], v[236:239], v[180:183], v[114:117]
	v_mfma_f32_16x16x32_bf16 v[102:105], v[228:231], v[188:191], v[102:105]
	v_mfma_f32_16x16x32_bf16 v[98:101], v[236:239], v[188:191], v[98:101]
	v_mfma_f32_16x16x32_bf16 v[86:89], v[228:231], v[200:203], v[86:89]
	v_mfma_f32_16x16x32_bf16 v[82:85], v[236:239], v[200:203], v[82:85]
	v_mfma_f32_16x16x32_bf16 v[70:73], v[228:231], v[220:223], v[70:73]
	v_mfma_f32_16x16x32_bf16 v[66:69], v[236:239], v[220:223], v[66:69]
	v_mfma_f32_16x16x32_bf16 v[118:121], v[232:235], v[184:187], v[118:121]
	v_mfma_f32_16x16x32_bf16 v[114:117], v[246:249], v[184:187], v[114:117]
	v_mfma_f32_16x16x32_bf16 v[102:105], v[232:235], v[192:195], v[102:105]
	v_mfma_f32_16x16x32_bf16 v[98:101], v[246:249], v[192:195], v[98:101]
	v_mfma_f32_16x16x32_bf16 v[86:89], v[232:235], v[216:219], v[86:89]
	v_mfma_f32_16x16x32_bf16 v[82:85], v[246:249], v[216:219], v[82:85]
	v_mfma_f32_16x16x32_bf16 v[70:73], v[232:235], v[224:227], v[70:73]
	v_mfma_f32_16x16x32_bf16 v[66:69], v[246:249], v[224:227], v[66:69]
	s_mov_b32 m0, s90
	v_lshl_add_u64 v[240:241], s[56:57], 0, v[136:137]
	s_barrier
	ds_read_b128 v[180:183], v166 offset:16384
	ds_read_b128 v[184:187], v166 offset:17408
	ds_read_b128 v[188:191], v166 offset:18432
	ds_read_b128 v[192:195], v166 offset:19456
	ds_read_b128 v[200:203], v166 offset:20480
	ds_read_b128 v[216:219], v166 offset:21504
	ds_read_b128 v[220:223], v166 offset:22528
	ds_read_b128 v[224:227], v166 offset:23552
	global_load_lds_dwordx4 v[240:241], off
	v_lshl_add_u64 v[250:251], s[56:57], 0, v[132:133]
	s_mov_b32 m0, s91
	s_nop 0
	global_load_lds_dwordx4 v[250:251], off
	s_barrier
	s_waitcnt lgkmcnt(0)
	s_waitcnt lgkmcnt(0)
	v_mfma_f32_16x16x32_bf16 v[62:65], v[162:165], v[180:183], v[62:65]
	v_mfma_f32_16x16x32_bf16 v[58:61], v[172:175], v[180:183], v[58:61]
	v_mfma_f32_16x16x32_bf16 v[46:49], v[162:165], v[188:191], v[46:49]
	v_mfma_f32_16x16x32_bf16 v[42:45], v[172:175], v[188:191], v[42:45]
	v_mfma_f32_16x16x32_bf16 v[30:33], v[162:165], v[200:203], v[30:33]
	v_mfma_f32_16x16x32_bf16 v[26:29], v[172:175], v[200:203], v[26:29]
	v_mfma_f32_16x16x32_bf16 v[14:17], v[162:165], v[220:223], v[14:17]
	v_mfma_f32_16x16x32_bf16 v[10:13], v[172:175], v[220:223], v[10:13]
	v_mfma_f32_16x16x32_bf16 v[62:65], v[168:171], v[184:187], v[62:65]
	v_mfma_f32_16x16x32_bf16 v[58:61], v[176:179], v[184:187], v[58:61]
	v_mfma_f32_16x16x32_bf16 v[46:49], v[168:171], v[192:195], v[46:49]
	v_mfma_f32_16x16x32_bf16 v[42:45], v[176:179], v[192:195], v[42:45]
	v_mfma_f32_16x16x32_bf16 v[30:33], v[168:171], v[216:219], v[30:33]
	v_mfma_f32_16x16x32_bf16 v[26:29], v[176:179], v[216:219], v[26:29]
	v_mfma_f32_16x16x32_bf16 v[14:17], v[168:171], v[224:227], v[14:17]
	v_mfma_f32_16x16x32_bf16 v[10:13], v[176:179], v[224:227], v[10:13]
	s_barrier
	s_add_u32 s76, s10, 0x40000
	s_addc_u32 s77, s11, 0
	s_add_i32 s84, s84, s65
	v_lshl_add_u64 v[162:163], s[76:77], 0, v[134:135]
	s_mov_b32 m0, s84
	s_nop 0
	global_load_lds_dwordx4 v[162:163], off
	v_lshl_add_u64 v[162:163], s[76:77], 0, v[130:131]
	s_add_i32 m0, s84, 0x2000
	s_nop 0
	global_load_lds_dwordx4 v[162:163], off
	s_waitcnt vmcnt(6)
	s_barrier
	v_mfma_f32_16x16x32_bf16 v[54:57], v[228:231], v[180:183], v[54:57]
	v_mfma_f32_16x16x32_bf16 v[50:53], v[236:239], v[180:183], v[50:53]
	v_mfma_f32_16x16x32_bf16 v[38:41], v[228:231], v[188:191], v[38:41]
	v_mfma_f32_16x16x32_bf16 v[34:37], v[236:239], v[188:191], v[34:37]
	v_mfma_f32_16x16x32_bf16 v[22:25], v[228:231], v[200:203], v[22:25]
	v_mfma_f32_16x16x32_bf16 v[18:21], v[236:239], v[200:203], v[18:21]
	v_mfma_f32_16x16x32_bf16 v[6:9], v[228:231], v[220:223], v[6:9]
	v_mfma_f32_16x16x32_bf16 v[2:5], v[236:239], v[220:223], v[2:5]
	v_mfma_f32_16x16x32_bf16 v[54:57], v[232:235], v[184:187], v[54:57]
	v_mfma_f32_16x16x32_bf16 v[50:53], v[246:249], v[184:187], v[50:53]
	v_mfma_f32_16x16x32_bf16 v[38:41], v[232:235], v[192:195], v[38:41]
	v_mfma_f32_16x16x32_bf16 v[34:37], v[246:249], v[192:195], v[34:37]
	v_mfma_f32_16x16x32_bf16 v[22:25], v[232:235], v[216:219], v[22:25]
	v_mfma_f32_16x16x32_bf16 v[18:21], v[246:249], v[216:219], v[18:21]
	v_mfma_f32_16x16x32_bf16 v[6:9], v[232:235], v[224:227], v[6:9]
	v_mfma_f32_16x16x32_bf16 v[2:5], v[246:249], v[224:227], v[2:5]
	s_add_i32 s76, 0, 0x18000
	v_add_u32_e32 v0, s76, v141
	s_barrier
	ds_read_b128 v[162:165], v0
	ds_read_b128 v[168:171], v0 offset:1024
	ds_read_b128 v[172:175], v0 offset:2048
	ds_read_b128 v[176:179], v0 offset:3072
	s_add_u32 s56, s56, 0x40000
	s_addc_u32 s57, s57, 0
	s_mov_b32 m0, s97
	v_lshl_add_u64 v[228:229], s[56:57], 0, v[136:137]
	ds_read_b128 v[180:183], v166 offset:32768
	ds_read_b128 v[184:187], v166 offset:33792
	ds_read_b128 v[188:191], v166 offset:34816
	ds_read_b128 v[192:195], v166 offset:35840
	ds_read_b128 v[200:203], v166 offset:36864
	ds_read_b128 v[216:219], v166 offset:37888
	ds_read_b128 v[220:223], v166 offset:38912
	ds_read_b128 v[224:227], v166 offset:39936
	global_load_lds_dwordx4 v[228:229], off
	v_lshl_add_u64 v[228:229], s[56:57], 0, v[132:133]
	s_mov_b32 m0, s44
	s_nop 0
	global_load_lds_dwordx4 v[228:229], off
	s_waitcnt lgkmcnt(8)
	s_barrier
; __device__ __forceinline__ unsigned cvt_pk_bf16(float lo, float hi) { unsigned r; asm volatile("v_cvt_pk_bf16_f32 %0, %1, %2" : "=v"(r) : "v"(lo), "v"(hi)); return r; }
; #define PG8_STAGE(bufoff, gbase, voff) do { _Pragma("unroll") for (int _i = 0; _i < 2; ++_i) \
;         __builtin_amdgcn_global_load_lds((const unsigned*)((const char*)(gbase) + (voff)[_i]), (PG8_LAS unsigned*)(lds + (bufoff) + ldsw + _i * 8192), 16, 0, 0); } while (0)
; #define PG8_LDA(dst, b, h) do { _Pragma("unroll") for (int m = 0; m < 4; ++m) _Pragma("unroll") for (int k = 0; k < 2; ++k) dst[m][k] = *(const PG8_LAS bf16x8*)(lds + PG8_SA(b, h) + aoff + m * 2048 + k * 1024); } while (0)
; #define PG8_BAR __builtin_amdgcn_s_barrier()
; template <class Epi, class Sched>
; __device__ __forceinline__ void gemm_phase(PG8_LAS unsigned char* lds, const Gemm g, const Sched& S, const Epi& E, const int tid) {
;     ...
;             PG8_LDB(B1, 1, 1); PG8_STAGE(PG8_SB(1, 0), b3, voffB);
;             PG8_BAR; PG8_WAIT_L(0); PG8_MMA(0, 1, At, B1); PG8_BAR;
;             PG8_LDA(At, 1, 1); PG8_STAGE(PG8_SA(1, 0), a3, voffA);
;             PG8_BAR; PG8_WAIT_L(0); PG8_MMA(1, 0, At, B0); PG8_BAR; PG8_SCHED;
;             PG8_STAGE(PG8_SB(1, 1), b3 + hstep, voffB);
;             PG8_WAIT_V(6); PG8_BAR; PG8_MMA(1, 1, At, B1); PG8_BAR;
;         }
;     __device__ __forceinline__ void operator()(const f32x4 (&acc)[2][2][4][2], const Unit& u, int wr, int wc, int fr, int fq) const {
;         const int rl0 = wr * 64 + fr, cl0 = wc * 32 + 8 * fq;
;         const size_t crow0 = (size_t)u.pm * 256, arow0 = (size_t)(u.pm >> 3) * 4096 + (size_t)half * 2048 + (size_t)(u.pm & 7) * 256;
; #pragma unroll
;         for (int ai = 0; ai < 2; ++ai)
; #pragma unroll
;             for (int m = 0; m < 4; ++m) { const int rl = rl0 + ai * HALF + m * 16;
; #pragma unroll
;                 for (int bj = 0; bj < 2; ++bj) { const f32x4 v0 = acc[ai][bj][m][0], v1 = acc[ai][bj][m][1]; const int cl = cl0 + bj * HALF;
;                     if (u.pn < 16) {
;                         u32x4 w; w.x = cvt_pk_bf16(v0[0], v0[1]); w.y = cvt_pk_bf16(v0[2], v0[3]); w.z = cvt_pk_bf16(v1[0], v1[1]); w.w = cvt_pk_bf16(v1[2], v1[3]);
;                         if (u.pn < 12) *(u32x4*)(Q + (crow0 + rl) * 3072 + u.pn * 256 + cl) = w;
;                         else *(u32x4*)(G + (arow0 + rl) * 1024 + (u.pn - 12) * 256 + cl) = w;
	s_waitcnt lgkmcnt(0)
	s_waitcnt lgkmcnt(0)
	v_mfma_f32_16x16x32_bf16 v[126:129], v[162:165], v[180:183], v[126:129]
	v_mfma_f32_16x16x32_bf16 v[122:125], v[172:175], v[180:183], v[122:125]
	v_mfma_f32_16x16x32_bf16 v[110:113], v[162:165], v[188:191], v[110:113]
	v_mfma_f32_16x16x32_bf16 v[106:109], v[172:175], v[188:191], v[106:109]
	v_mfma_f32_16x16x32_bf16 v[94:97], v[162:165], v[200:203], v[94:97]
	v_mfma_f32_16x16x32_bf16 v[90:93], v[172:175], v[200:203], v[90:93]
	v_mfma_f32_16x16x32_bf16 v[78:81], v[162:165], v[220:223], v[78:81]
	v_mfma_f32_16x16x32_bf16 v[74:77], v[172:175], v[220:223], v[74:77]
	v_mfma_f32_16x16x32_bf16 v[126:129], v[168:171], v[184:187], v[126:129]
	v_mfma_f32_16x16x32_bf16 v[122:125], v[176:179], v[184:187], v[122:125]
	v_mfma_f32_16x16x32_bf16 v[110:113], v[168:171], v[192:195], v[110:113]
	v_mfma_f32_16x16x32_bf16 v[106:109], v[176:179], v[192:195], v[106:109]
	v_mfma_f32_16x16x32_bf16 v[94:97], v[168:171], v[216:219], v[94:97]
	v_mfma_f32_16x16x32_bf16 v[90:93], v[176:179], v[216:219], v[90:93]
	v_mfma_f32_16x16x32_bf16 v[78:81], v[168:171], v[224:227], v[78:81]
	v_mfma_f32_16x16x32_bf16 v[74:77], v[176:179], v[224:227], v[74:77]
	s_barrier
	s_add_i32 s56, 0, 0x1c000
	s_add_i32 s57, s76, s65
	v_add_u32_e32 v0, s56, v141
	v_lshl_add_u64 v[196:197], v[196:197], 0, s[92:93]
	s_mov_b32 m0, s57
	ds_read_b128 v[228:231], v0
	ds_read_b128 v[232:235], v0 offset:1024
	ds_read_b128 v[236:239], v0 offset:2048
	ds_read_b128 v[246:249], v0 offset:3072
	global_load_lds_dwordx4 v[196:197], off
	v_lshl_add_u64 v[196:197], v[198:199], 0, s[92:93]
	s_add_i32 m0, s57, 0x2000
	s_nop 0
	global_load_lds_dwordx4 v[196:197], off
	s_barrier
	s_waitcnt lgkmcnt(0)
	s_waitcnt lgkmcnt(0)
	v_mfma_f32_16x16x32_bf16 v[118:121], v[228:231], v[180:183], v[118:121]
	v_mfma_f32_16x16x32_bf16 v[114:117], v[236:239], v[180:183], v[114:117]
	v_mfma_f32_16x16x32_bf16 v[102:105], v[228:231], v[188:191], v[102:105]
	v_mfma_f32_16x16x32_bf16 v[98:101], v[236:239], v[188:191], v[98:101]
	v_mfma_f32_16x16x32_bf16 v[86:89], v[228:231], v[200:203], v[86:89]
	v_mfma_f32_16x16x32_bf16 v[82:85], v[236:239], v[200:203], v[82:85]
	v_mfma_f32_16x16x32_bf16 v[70:73], v[228:231], v[220:223], v[70:73]
	v_mfma_f32_16x16x32_bf16 v[66:69], v[236:239], v[220:223], v[66:69]
	v_mfma_f32_16x16x32_bf16 v[118:121], v[232:235], v[184:187], v[118:121]
	v_mfma_f32_16x16x32_bf16 v[114:117], v[246:249], v[184:187], v[114:117]
	v_mfma_f32_16x16x32_bf16 v[102:105], v[232:235], v[192:195], v[102:105]
	v_mfma_f32_16x16x32_bf16 v[98:101], v[246:249], v[192:195], v[98:101]
	v_mfma_f32_16x16x32_bf16 v[86:89], v[232:235], v[216:219], v[86:89]
	v_mfma_f32_16x16x32_bf16 v[82:85], v[246:249], v[216:219], v[82:85]
	v_mfma_f32_16x16x32_bf16 v[70:73], v[232:235], v[224:227], v[70:73]
	v_mfma_f32_16x16x32_bf16 v[66:69], v[246:249], v[224:227], v[66:69]
	s_mov_b32 m0, s12
	v_lshl_add_u64 v[196:197], v[240:241], 0, s[92:93]
	s_barrier
	ds_read_b128 v[180:183], v166 offset:49152
	ds_read_b128 v[184:187], v166 offset:50176
	ds_read_b128 v[188:191], v166 offset:51200
	ds_read_b128 v[192:195], v166 offset:52224
	ds_read_b128 v[200:203], v166 offset:53248
	ds_read_b128 v[216:219], v166 offset:54272
	ds_read_b128 v[220:223], v166 offset:55296
	ds_read_b128 v[224:227], v166 offset:56320
	global_load_lds_dwordx4 v[196:197], off
	v_lshl_add_u64 v[196:197], v[250:251], 0, s[92:93]
	s_mov_b32 m0, s0
	s_nop 0
	global_load_lds_dwordx4 v[196:197], off
	s_barrier
	s_waitcnt lgkmcnt(0)
	s_waitcnt lgkmcnt(0)
	v_mfma_f32_16x16x32_bf16 v[62:65], v[162:165], v[180:183], v[62:65]
	v_mfma_f32_16x16x32_bf16 v[58:61], v[172:175], v[180:183], v[58:61]
	v_mfma_f32_16x16x32_bf16 v[46:49], v[162:165], v[188:191], v[46:49]
	v_mfma_f32_16x16x32_bf16 v[42:45], v[172:175], v[188:191], v[42:45]
	v_mfma_f32_16x16x32_bf16 v[30:33], v[162:165], v[200:203], v[30:33]
	v_mfma_f32_16x16x32_bf16 v[26:29], v[172:175], v[200:203], v[26:29]
	v_mfma_f32_16x16x32_bf16 v[14:17], v[162:165], v[220:223], v[14:17]
	v_mfma_f32_16x16x32_bf16 v[10:13], v[172:175], v[220:223], v[10:13]
	v_mfma_f32_16x16x32_bf16 v[62:65], v[168:171], v[184:187], v[62:65]
	v_mfma_f32_16x16x32_bf16 v[58:61], v[176:179], v[184:187], v[58:61]
	v_mfma_f32_16x16x32_bf16 v[46:49], v[168:171], v[192:195], v[46:49]
	v_mfma_f32_16x16x32_bf16 v[42:45], v[176:179], v[192:195], v[42:45]
	v_mfma_f32_16x16x32_bf16 v[30:33], v[168:171], v[216:219], v[30:33]
	v_mfma_f32_16x16x32_bf16 v[26:29], v[176:179], v[216:219], v[26:29]
	v_mfma_f32_16x16x32_bf16 v[14:17], v[168:171], v[224:227], v[14:17]
	v_mfma_f32_16x16x32_bf16 v[10:13], v[176:179], v[224:227], v[10:13]
	s_barrier
	s_add_u32 s10, s10, 0x40080
	s_addc_u32 s11, s11, 0
	s_add_i32 s56, s56, s65
	v_lshl_add_u64 v[162:163], s[10:11], 0, v[134:135]
	s_mov_b32 m0, s56
	s_nop 0
	global_load_lds_dwordx4 v[162:163], off
	v_lshl_add_u64 v[162:163], s[10:11], 0, v[130:131]
	s_add_i32 m0, s56, 0x2000
	s_nop 0
	global_load_lds_dwordx4 v[162:163], off
	s_waitcnt vmcnt(6)
	s_barrier
	v_mfma_f32_16x16x32_bf16 v[54:57], v[228:231], v[180:183], v[54:57]
	v_mfma_f32_16x16x32_bf16 v[50:53], v[236:239], v[180:183], v[50:53]
	v_mfma_f32_16x16x32_bf16 v[38:41], v[228:231], v[188:191], v[38:41]
	v_mfma_f32_16x16x32_bf16 v[34:37], v[236:239], v[188:191], v[34:37]
	v_mfma_f32_16x16x32_bf16 v[22:25], v[228:231], v[200:203], v[22:25]
	v_mfma_f32_16x16x32_bf16 v[18:21], v[236:239], v[200:203], v[18:21]
	v_mfma_f32_16x16x32_bf16 v[6:9], v[228:231], v[220:223], v[6:9]
	v_mfma_f32_16x16x32_bf16 v[2:5], v[236:239], v[220:223], v[2:5]
	v_mfma_f32_16x16x32_bf16 v[54:57], v[232:235], v[184:187], v[54:57]
	v_mfma_f32_16x16x32_bf16 v[50:53], v[246:249], v[184:187], v[50:53]
	v_mfma_f32_16x16x32_bf16 v[38:41], v[232:235], v[192:195], v[38:41]
	v_mfma_f32_16x16x32_bf16 v[34:37], v[246:249], v[192:195], v[34:37]
	v_mfma_f32_16x16x32_bf16 v[22:25], v[232:235], v[216:219], v[22:25]
	v_mfma_f32_16x16x32_bf16 v[18:21], v[246:249], v[216:219], v[18:21]
	v_mfma_f32_16x16x32_bf16 v[6:9], v[232:235], v[224:227], v[6:9]
	v_mfma_f32_16x16x32_bf16 v[2:5], v[246:249], v[224:227], v[2:5]
	s_add_i32 s63, s63, 2
	s_add_u32 s6, s6, 0x100
	s_addc_u32 s7, s7, 0
	s_add_u32 s34, s34, 0x100
	s_addc_u32 s35, s35, 0
	s_cmp_gt_u32 s63, 13
	s_barrier
	s_cbranch_scc0 .LBB0_37
	s_ashr_i32 s6, s8, 3
	s_ashr_i32 s7, s6, 31
	s_lshl_b64 s[88:89], s[6:7], 12
	s_lshl_b32 s6, s8, 8
	s_and_b32 s6, s6, 0x700
	s_or_b32 s6, s88, s6
	s_or_b32 s88, s6, 0x800
	s_cmp_lt_i32 s62, 16
	s_cselect_b64 s[6:7], -1, 0
	s_cmp_gt_i32 s62, 15
	s_cselect_b64 s[56:57], -1, 0
	s_cmp_gt_i32 s62, 11
	s_cselect_b64 s[10:11], -1, 0
	v_lshl_add_u64 v[162:163], s[88:89], 0, v[138:139]
	s_mov_b64 s[34:35], -1
	s_and_b64 vcc, exec, s[56:57]
	s_cbranch_vccz .LBB0_42
	s_and_saveexec_b64 s[34:35], s[2:3]
	s_cbranch_execz .LBB0_41
	v_lshlrev_b64 v[164:165], 6, v[162:163]
	v_lshl_add_u64 v[164:165], v[156:157], 0, v[164:165]
	global_store_dwordx4 v[164:165], v[126:129], off
	global_store_dwordx4 v[164:165], v[122:125], off offset:16

; template <class Epi, class Sched>
; __device__ __forceinline__ void gemm_phase(PG8_LAS unsigned char* lds, const Gemm g, const Sched& S, const Epi& E, const int tid) {
;     ...
;         const bool has_next = S.next(ui + 1, nxt);
;         const char* nA = has_next ? (const char*)g.A + a_tile_row(g, nxt.pm) * (size_t)K * 2 : cA; const char* nB = has_next ? (const char*)g.Bt + (size_t)nxt.pn * tstep : cB;
;         for (int t = 0; t < nt; t += 2) {
;             const bool last = (t == nt - 2);
;             const char* a1 = cA + (size_t)(t + 1) * kstep;
;             const char* a2 = last ? nA : cA + (size_t)(t + 2) * kstep; const char* b2 = last ? nB : cB + (size_t)(t + 2) * kstep;
;     ...
; #pragma unroll
;         for (int a = 0; a < 2; ++a)
; #pragma unroll
;             for (int b = 0; b < 2; ++b)
; #pragma unroll
;                 for (int m = 0; m < 4; ++m)
; #pragma unroll
;                     for (int n = 0; n < 2; ++n) acc[a][b][m][n] = (f32x4){0.f, 0.f, 0.f, 0.f};
.LBB0_198:
	v_mov_b64_e32 v[2:3], 0x800
	s_ashr_i32 s7, s6, 31
	v_cmp_lt_i64_e32 vcc, s[8:9], v[2:3]
	s_lshl_b64 s[8:9], s[6:7], 19
	s_add_u32 s8, s82, s8
	s_addc_u32 s9, s83, s9
	s_and_b64 s[10:11], vcc, exec
	s_cselect_b32 s7, s9, s15
	s_cselect_b32 s69, s8, s14
	s_ashr_i32 s5, s4, 31
	s_lshl_b64 s[10:11], s[4:5], 19
	s_add_u32 s10, s1, s10
	s_addc_u32 s11, s12, s11
	s_and_b64 s[56:57], vcc, exec
	s_cselect_b32 s5, s11, s19
	s_cselect_b32 s72, s10, s18
	s_add_u32 s14, s14, 0x40080
	s_addc_u32 s15, s15, 0
	s_add_u32 s73, s18, 0x100
	v_mov_b32_e32 v2, 0
	s_addc_u32 s76, s19, 0
	s_mov_b32 s77, -2
	v_mov_b32_e32 v3, v2
	v_mov_b32_e32 v4, v2
	v_mov_b32_e32 v5, v2
	v_mov_b32_e32 v6, v2
	v_mov_b32_e32 v7, v2
	v_mov_b32_e32 v8, v2
	v_mov_b32_e32 v9, v2
	v_mov_b32_e32 v18, v2
	v_mov_b32_e32 v19, v2
	v_mov_b32_e32 v20, v2
	v_mov_b32_e32 v21, v2
	v_mov_b32_e32 v22, v2
	v_mov_b32_e32 v23, v2
	v_mov_b32_e32 v24, v2
	v_mov_b32_e32 v25, v2
	v_mov_b32_e32 v34, v2
	v_mov_b32_e32 v35, v2
	v_mov_b32_e32 v36, v2
	v_mov_b32_e32 v37, v2
	v_mov_b32_e32 v38, v2
	v_mov_b32_e32 v39, v2
	v_mov_b32_e32 v40, v2
	v_mov_b32_e32 v41, v2
	v_mov_b32_e32 v50, v2
	v_mov_b32_e32 v51, v2
	v_mov_b32_e32 v52, v2
	v_mov_b32_e32 v53, v2
	v_mov_b32_e32 v54, v2
	v_mov_b32_e32 v55, v2
	v_mov_b32_e32 v56, v2
	v_mov_b32_e32 v57, v2
	v_mov_b32_e32 v10, v2
	v_mov_b32_e32 v11, v2
	v_mov_b32_e32 v12, v2
	v_mov_b32_e32 v13, v2
	v_mov_b32_e32 v14, v2
	v_mov_b32_e32 v15, v2
	v_mov_b32_e32 v16, v2
	v_mov_b32_e32 v17, v2
	v_mov_b32_e32 v26, v2
	v_mov_b32_e32 v27, v2
	v_mov_b32_e32 v28, v2
	v_mov_b32_e32 v29, v2
	v_mov_b32_e32 v30, v2
	v_mov_b32_e32 v31, v2
	v_mov_b32_e32 v32, v2
	v_mov_b32_e32 v33, v2
	v_mov_b32_e32 v42, v2
	v_mov_b32_e32 v43, v2
	v_mov_b32_e32 v44, v2
	v_mov_b32_e32 v45, v2
	v_mov_b32_e32 v46, v2
	v_mov_b32_e32 v47, v2
	v_mov_b32_e32 v48, v2
	v_mov_b32_e32 v49, v2
	v_mov_b32_e32 v58, v2
	v_mov_b32_e32 v59, v2
	v_mov_b32_e32 v60, v2
	v_mov_b32_e32 v61, v2
	v_mov_b32_e32 v62, v2
	v_mov_b32_e32 v63, v2
	v_mov_b32_e32 v64, v2
	v_mov_b32_e32 v65, v2
	v_mov_b32_e32 v66, v2
	v_mov_b32_e32 v67, v2
	v_mov_b32_e32 v68, v2
	v_mov_b32_e32 v69, v2
	v_mov_b32_e32 v70, v2
	v_mov_b32_e32 v71, v2
	v_mov_b32_e32 v72, v2
	v_mov_b32_e32 v73, v2
	v_mov_b32_e32 v82, v2
	v_mov_b32_e32 v83, v2
	v_mov_b32_e32 v84, v2
	v_mov_b32_e32 v85, v2
	v_mov_b32_e32 v86, v2
	v_mov_b32_e32 v87, v2
	v_mov_b32_e32 v88, v2
	v_mov_b32_e32 v89, v2
	v_mov_b32_e32 v98, v2
	v_mov_b32_e32 v99, v2
	v_mov_b32_e32 v100, v2
	v_mov_b32_e32 v101, v2
	v_mov_b32_e32 v102, v2
	v_mov_b32_e32 v103, v2
	v_mov_b32_e32 v104, v2
	v_mov_b32_e32 v105, v2
	v_mov_b32_e32 v114, v2
	v_mov_b32_e32 v115, v2
	v_mov_b32_e32 v116, v2
	v_mov_b32_e32 v117, v2
	v_mov_b32_e32 v118, v2
	v_mov_b32_e32 v119, v2
	v_mov_b32_e32 v120, v2
	v_mov_b32_e32 v121, v2
	v_mov_b32_e32 v74, v2
	v_mov_b32_e32 v75, v2
	v_mov_b32_e32 v76, v2
	v_mov_b32_e32 v77, v2
	v_mov_b32_e32 v78, v2
	v_mov_b32_e32 v79, v2
	v_mov_b32_e32 v80, v2
	v_mov_b32_e32 v81, v2
	v_mov_b32_e32 v90, v2
	v_mov_b32_e32 v91, v2
	v_mov_b32_e32 v92, v2
	v_mov_b32_e32 v93, v2
	v_mov_b32_e32 v94, v2
	v_mov_b32_e32 v95, v2
	v_mov_b32_e32 v96, v2
	v_mov_b32_e32 v97, v2
	v_mov_b32_e32 v106, v2
	v_mov_b32_e32 v107, v2
	v_mov_b32_e32 v108, v2
	v_mov_b32_e32 v109, v2
	v_mov_b32_e32 v110, v2
	v_mov_b32_e32 v111, v2
	v_mov_b32_e32 v112, v2
	v_mov_b32_e32 v113, v2
	v_mov_b32_e32 v122, v2
	v_mov_b32_e32 v123, v2
	v_mov_b32_e32 v124, v2
	v_mov_b32_e32 v125, v2
	v_mov_b32_e32 v126, v2
	v_mov_b32_e32 v127, v2
	v_mov_b32_e32 v128, v2
	v_mov_b32_e32 v129, v2
	v_readlane_b32 s101, v254, 14
	s_bitcmp1_b32 s101, 0
	s_cbranch_scc0 .Lprio_skip1
	s_setprio 1

; #define PG8_STAGE(bufoff, gbase, voff) do { _Pragma("unroll") for (int _i = 0; _i < 2; ++_i) \
;         __builtin_amdgcn_global_load_lds((const unsigned*)((const char*)(gbase) + (voff)[_i]), (PG8_LAS unsigned*)(lds + (bufoff) + ldsw + _i * 8192), 16, 0, 0); } while (0)
; #define PG8_LDA(dst, b, h) do { _Pragma("unroll") for (int m = 0; m < 4; ++m) _Pragma("unroll") for (int k = 0; k < 2; ++k) dst[m][k] = *(const PG8_LAS bf16x8*)(lds + PG8_SA(b, h) + aoff + m * 2048 + k * 1024); } while (0)
; #define PG8_LDB(dst, b, h) do { _Pragma("unroll") for (int n = 0; n < 2; ++n) _Pragma("unroll") for (int k = 0; k < 2; ++k) dst[n][k] = *(const PG8_LAS bf16x8*)(lds + PG8_SB(b, h) + boff + n * 2048 + k * 1024); } while (0)
; #define PG8_MMA(ai, bj, At, Bt) do { __builtin_amdgcn_s_setprio(1); _Pragma("unroll") for (int m = 0; m < 4; ++m) _Pragma("unroll") for (int n = 0; n < 2; ++n) _Pragma("unroll") for (int k = 0; k < 2; ++k) \
;         acc[ai][bj][m][n] = __builtin_amdgcn_mfma_f32_16x16x32_bf16(Bt[n][k], At[m][k], acc[ai][bj][m][n], 0, 0, 0); __builtin_amdgcn_s_setprio(0); } while (0)
; #define PG8_WAIT_V(n) asm volatile("s_waitcnt vmcnt(" #n ")" ::: "memory")
; #define PG8_WAIT_L(n) asm volatile("s_waitcnt lgkmcnt(" #n ")" ::: "memory")
; #define PG8_BAR __builtin_amdgcn_s_barrier()
; #define PG8_SCHED __builtin_amdgcn_sched_barrier(0)
; template <class Epi, class Sched>
; __device__ __forceinline__ void gemm_phase(PG8_LAS unsigned char* lds, const Gemm g, const Sched& S, const Epi& E, const int tid) {
;     ...
;             PG8_LDB(B0, 0, 0); PG8_SCHED; PG8_LDA(At, 0, 0); PG8_STAGE(PG8_SA(1, 1), a1 + hstep, voffA);
;             PG8_WAIT_L(8); PG8_BAR; PG8_WAIT_L(0); PG8_MMA(0, 0, At, B0); PG8_BAR; PG8_SCHED;
;             PG8_LDB(B1, 0, 1); PG8_STAGE(PG8_SB(0, 0), b2, voffB);
;             PG8_BAR; PG8_WAIT_L(0); PG8_MMA(0, 1, At, B1); PG8_BAR;
;             PG8_LDA(At, 0, 1); PG8_STAGE(PG8_SA(0, 0), a2, voffA);
;             PG8_BAR; PG8_WAIT_L(0); PG8_MMA(1, 0, At, B0); PG8_BAR; PG8_SCHED;
;             PG8_STAGE(PG8_SB(0, 1), b2 + hstep, voffB);
;             PG8_WAIT_V(6); PG8_BAR; PG8_MMA(1, 1, At, B1); PG8_BAR;
.LBB0_199:
	s_add_u32 s18, s14, 0xfffc0080
	s_addc_u32 s19, s15, -1
	s_add_i32 s88, 0, 0x10000
	v_add_u32_e32 v140, s88, v143
	ds_read_b128 v[146:149], v140
	ds_read_b128 v[150:153], v140 offset:1024
	ds_read_b128 v[154:157], v140 offset:2048
	ds_read_b128 v[158:161], v140 offset:3072
	s_cmp_eq_u32 s77, 12
	s_cselect_b32 s57, s7, s19
	s_cselect_b32 s56, s69, s18
	s_cselect_b32 s19, s5, s76
	s_cselect_b32 s18, s72, s73
	v_lshl_add_u64 v[140:141], s[14:15], 0, v[136:137]
	s_add_i32 m0, s34, 0xc000
	ds_read_b128 v[162:165], v145
	ds_read_b128 v[166:169], v145 offset:1024
	ds_read_b128 v[170:173], v145 offset:2048
	ds_read_b128 v[174:177], v145 offset:3072
	ds_read_b128 v[178:181], v145 offset:4096
	ds_read_b128 v[182:185], v145 offset:5120
	ds_read_b128 v[186:189], v145 offset:6144
	ds_read_b128 v[190:193], v145 offset:7168
	global_load_lds_dwordx4 v[140:141], off
	v_lshl_add_u64 v[140:141], s[14:15], 0, v[138:139]
	s_add_i32 m0, s34, 0xe000
	s_nop 0
	global_load_lds_dwordx4 v[140:141], off
	s_waitcnt lgkmcnt(8)
	s_barrier
	s_waitcnt lgkmcnt(0)
	s_waitcnt lgkmcnt(0)
	v_mfma_f32_16x16x32_bf16 v[126:129], v[146:149], v[162:165], v[126:129]
	v_mfma_f32_16x16x32_bf16 v[122:125], v[154:157], v[162:165], v[122:125]
	v_mfma_f32_16x16x32_bf16 v[110:113], v[146:149], v[170:173], v[110:113]
	v_mfma_f32_16x16x32_bf16 v[106:109], v[154:157], v[170:173], v[106:109]
	v_mfma_f32_16x16x32_bf16 v[94:97], v[146:149], v[178:181], v[94:97]
	v_mfma_f32_16x16x32_bf16 v[90:93], v[154:157], v[178:181], v[90:93]
	v_mfma_f32_16x16x32_bf16 v[78:81], v[146:149], v[186:189], v[78:81]
	v_mfma_f32_16x16x32_bf16 v[74:77], v[154:157], v[186:189], v[74:77]
	v_mfma_f32_16x16x32_bf16 v[126:129], v[150:153], v[166:169], v[126:129]
	v_mfma_f32_16x16x32_bf16 v[122:125], v[158:161], v[166:169], v[122:125]
	v_mfma_f32_16x16x32_bf16 v[110:113], v[150:153], v[174:177], v[110:113]
	v_mfma_f32_16x16x32_bf16 v[106:109], v[158:161], v[174:177], v[106:109]
	v_mfma_f32_16x16x32_bf16 v[94:97], v[150:153], v[182:185], v[94:97]
	v_mfma_f32_16x16x32_bf16 v[90:93], v[158:161], v[182:185], v[90:93]
	v_mfma_f32_16x16x32_bf16 v[78:81], v[150:153], v[190:193], v[78:81]
	v_mfma_f32_16x16x32_bf16 v[74:77], v[158:161], v[190:193], v[74:77]
	s_barrier
	s_add_i32 s90, 0, 0x14000
	v_add_u32_e32 v140, s90, v143
	s_add_i32 s88, s88, s13
	ds_read_b128 v[200:203], v140
	ds_read_b128 v[216:219], v140 offset:1024
	ds_read_b128 v[220:223], v140 offset:2048
	ds_read_b128 v[224:227], v140 offset:3072
	v_lshl_add_u64 v[140:141], s[18:19], 0, v[0:1]
	s_mov_b32 m0, s88
	v_lshl_add_u64 v[194:195], s[18:19], 0, v[130:131]
	global_load_lds_dwordx4 v[140:141], off
	s_add_i32 m0, s88, 0x2000
	s_nop 0
	global_load_lds_dwordx4 v[194:195], off
	s_barrier
	s_waitcnt lgkmcnt(0)
	s_waitcnt lgkmcnt(0)
	v_mfma_f32_16x16x32_bf16 v[118:121], v[200:203], v[162:165], v[118:121]
	v_mfma_f32_16x16x32_bf16 v[114:117], v[220:223], v[162:165], v[114:117]
	v_mfma_f32_16x16x32_bf16 v[102:105], v[200:203], v[170:173], v[102:105]
	v_mfma_f32_16x16x32_bf16 v[98:101], v[220:223], v[170:173], v[98:101]
	v_mfma_f32_16x16x32_bf16 v[86:89], v[200:203], v[178:181], v[86:89]
	v_mfma_f32_16x16x32_bf16 v[82:85], v[220:223], v[178:181], v[82:85]
	v_mfma_f32_16x16x32_bf16 v[70:73], v[200:203], v[186:189], v[70:73]
	v_mfma_f32_16x16x32_bf16 v[66:69], v[220:223], v[186:189], v[66:69]
	v_mfma_f32_16x16x32_bf16 v[118:121], v[216:219], v[166:169], v[118:121]
	v_mfma_f32_16x16x32_bf16 v[114:117], v[224:227], v[166:169], v[114:117]
	v_mfma_f32_16x16x32_bf16 v[102:105], v[216:219], v[174:177], v[102:105]
	v_mfma_f32_16x16x32_bf16 v[98:101], v[224:227], v[174:177], v[98:101]
	v_mfma_f32_16x16x32_bf16 v[86:89], v[216:219], v[182:185], v[86:89]
	v_mfma_f32_16x16x32_bf16 v[82:85], v[224:227], v[182:185], v[82:85]
	v_mfma_f32_16x16x32_bf16 v[70:73], v[216:219], v[190:193], v[70:73]
	v_mfma_f32_16x16x32_bf16 v[66:69], v[224:227], v[190:193], v[66:69]
	s_mov_b32 m0, s34
	v_lshl_add_u64 v[196:197], s[56:57], 0, v[134:135]
	s_barrier
	ds_read_b128 v[162:165], v145 offset:16384
	ds_read_b128 v[166:169], v145 offset:17408
	ds_read_b128 v[170:173], v145 offset:18432
	ds_read_b128 v[174:177], v145 offset:19456
	ds_read_b128 v[178:181], v145 offset:20480
	ds_read_b128 v[182:185], v145 offset:21504
	ds_read_b128 v[186:189], v145 offset:22528
	ds_read_b128 v[190:193], v145 offset:23552
	global_load_lds_dwordx4 v[196:197], off
	v_lshl_add_u64 v[198:199], s[56:57], 0, v[132:133]
	s_mov_b32 m0, s35
	s_nop 0
	global_load_lds_dwordx4 v[198:199], off
	s_barrier
	s_waitcnt lgkmcnt(0)
	s_waitcnt lgkmcnt(0)
	v_mfma_f32_16x16x32_bf16 v[62:65], v[146:149], v[162:165], v[62:65]
	v_mfma_f32_16x16x32_bf16 v[58:61], v[154:157], v[162:165], v[58:61]
	v_mfma_f32_16x16x32_bf16 v[46:49], v[146:149], v[170:173], v[46:49]
	v_mfma_f32_16x16x32_bf16 v[42:45], v[154:157], v[170:173], v[42:45]
	v_mfma_f32_16x16x32_bf16 v[30:33], v[146:149], v[178:181], v[30:33]
	v_mfma_f32_16x16x32_bf16 v[26:29], v[154:157], v[178:181], v[26:29]
	v_mfma_f32_16x16x32_bf16 v[14:17], v[146:149], v[186:189], v[14:17]
	v_mfma_f32_16x16x32_bf16 v[10:13], v[154:157], v[186:189], v[10:13]
	v_mfma_f32_16x16x32_bf16 v[62:65], v[150:153], v[166:169], v[62:65]
	v_mfma_f32_16x16x32_bf16 v[58:61], v[158:161], v[166:169], v[58:61]
	v_mfma_f32_16x16x32_bf16 v[46:49], v[150:153], v[174:177], v[46:49]
	v_mfma_f32_16x16x32_bf16 v[42:45], v[158:161], v[174:177], v[42:45]
	v_mfma_f32_16x16x32_bf16 v[30:33], v[150:153], v[182:185], v[30:33]
	v_mfma_f32_16x16x32_bf16 v[26:29], v[158:161], v[182:185], v[26:29]
	v_mfma_f32_16x16x32_bf16 v[14:17], v[150:153], v[190:193], v[14:17]
	v_mfma_f32_16x16x32_bf16 v[10:13], v[158:161], v[190:193], v[10:13]
	s_barrier
; #define PG8_STAGE(bufoff, gbase, voff) do { _Pragma("unroll") for (int _i = 0; _i < 2; ++_i) \
;         __builtin_amdgcn_global_load_lds((const unsigned*)((const char*)(gbase) + (voff)[_i]), (PG8_LAS unsigned*)(lds + (bufoff) + ldsw + _i * 8192), 16, 0, 0); } while (0)
; #define PG8_LDA(dst, b, h) do { _Pragma("unroll") for (int m = 0; m < 4; ++m) _Pragma("unroll") for (int k = 0; k < 2; ++k) dst[m][k] = *(const PG8_LAS bf16x8*)(lds + PG8_SA(b, h) + aoff + m * 2048 + k * 1024); } while (0)
; #define PG8_LDB(dst, b, h) do { _Pragma("unroll") for (int n = 0; n < 2; ++n) _Pragma("unroll") for (int k = 0; k < 2; ++k) dst[n][k] = *(const PG8_LAS bf16x8*)(lds + PG8_SB(b, h) + boff + n * 2048 + k * 1024); } while (0)
; #define PG8_MMA(ai, bj, At, Bt) do { __builtin_amdgcn_s_setprio(1); _Pragma("unroll") for (int m = 0; m < 4; ++m) _Pragma("unroll") for (int n = 0; n < 2; ++n) _Pragma("unroll") for (int k = 0; k < 2; ++k) \
;         acc[ai][bj][m][n] = __builtin_amdgcn_mfma_f32_16x16x32_bf16(Bt[n][k], At[m][k], acc[ai][bj][m][n], 0, 0, 0); __builtin_amdgcn_s_setprio(0); } while (0)
; #define PG8_WAIT_V(n) asm volatile("s_waitcnt vmcnt(" #n ")" ::: "memory")
; #define PG8_WAIT_L(n) asm volatile("s_waitcnt lgkmcnt(" #n ")" ::: "memory")
; #define PG8_BAR __builtin_amdgcn_s_barrier()
; #define PG8_SCHED __builtin_amdgcn_sched_barrier(0)
; template <class Epi, class Sched>
; __device__ __forceinline__ void gemm_phase(PG8_LAS unsigned char* lds, const Gemm g, const Sched& S, const Epi& E, const int tid) {
;     ...
;             PG8_WAIT_V(6); PG8_BAR; PG8_MMA(1, 1, At, B1); PG8_BAR;
;             PG8_LDB(B0, 1, 0); PG8_SCHED; PG8_LDA(At, 1, 0); PG8_STAGE(PG8_SA(0, 1), a2 + hstep, voffA);
;             PG8_WAIT_L(8); PG8_BAR; PG8_WAIT_L(0); PG8_MMA(0, 0, At, B0); PG8_BAR; PG8_SCHED;
;             PG8_LDB(B1, 1, 1); PG8_STAGE(PG8_SB(1, 0), b3, voffB);
;             PG8_BAR; PG8_WAIT_L(0); PG8_MMA(0, 1, At, B1); PG8_BAR;
;             PG8_LDA(At, 1, 1); PG8_STAGE(PG8_SA(1, 0), a3, voffA);
;             PG8_BAR; PG8_WAIT_L(0); PG8_MMA(1, 0, At, B0); PG8_BAR; PG8_SCHED;
	s_add_u32 s88, s18, 0x40000
	s_addc_u32 s89, s19, 0
	s_add_i32 s90, s90, s13
	v_lshl_add_u64 v[146:147], s[88:89], 0, v[0:1]
	s_mov_b32 m0, s90
	s_nop 0
	global_load_lds_dwordx4 v[146:147], off
	v_lshl_add_u64 v[146:147], s[88:89], 0, v[130:131]
	s_add_i32 m0, s90, 0x2000
	s_nop 0
	global_load_lds_dwordx4 v[146:147], off
	s_waitcnt vmcnt(6)
	s_barrier
	v_mfma_f32_16x16x32_bf16 v[54:57], v[200:203], v[162:165], v[54:57]
	v_mfma_f32_16x16x32_bf16 v[50:53], v[220:223], v[162:165], v[50:53]
	v_mfma_f32_16x16x32_bf16 v[38:41], v[200:203], v[170:173], v[38:41]
	v_mfma_f32_16x16x32_bf16 v[34:37], v[220:223], v[170:173], v[34:37]
	v_mfma_f32_16x16x32_bf16 v[22:25], v[200:203], v[178:181], v[22:25]
	v_mfma_f32_16x16x32_bf16 v[18:21], v[220:223], v[178:181], v[18:21]
	v_mfma_f32_16x16x32_bf16 v[6:9], v[200:203], v[186:189], v[6:9]
	v_mfma_f32_16x16x32_bf16 v[2:5], v[220:223], v[186:189], v[2:5]
	v_mfma_f32_16x16x32_bf16 v[54:57], v[216:219], v[166:169], v[54:57]
	v_mfma_f32_16x16x32_bf16 v[50:53], v[224:227], v[166:169], v[50:53]
	v_mfma_f32_16x16x32_bf16 v[38:41], v[216:219], v[174:177], v[38:41]
	v_mfma_f32_16x16x32_bf16 v[34:37], v[224:227], v[174:177], v[34:37]
	v_mfma_f32_16x16x32_bf16 v[22:25], v[216:219], v[182:185], v[22:25]
	v_mfma_f32_16x16x32_bf16 v[18:21], v[224:227], v[182:185], v[18:21]
	v_mfma_f32_16x16x32_bf16 v[6:9], v[216:219], v[190:193], v[6:9]
	v_mfma_f32_16x16x32_bf16 v[2:5], v[224:227], v[190:193], v[2:5]
	s_add_i32 s88, 0, 0x18000
	v_add_u32_e32 v158, s88, v143
	s_barrier
	ds_read_b128 v[146:149], v158
	ds_read_b128 v[150:153], v158 offset:1024
	ds_read_b128 v[154:157], v158 offset:2048
	ds_read_b128 v[158:161], v158 offset:3072
	s_add_u32 s56, s56, 0x40000
	s_addc_u32 s57, s57, 0
	s_mov_b32 m0, s44
	v_lshl_add_u64 v[200:201], s[56:57], 0, v[134:135]
	ds_read_b128 v[162:165], v145 offset:32768
	ds_read_b128 v[166:169], v145 offset:33792
	ds_read_b128 v[170:173], v145 offset:34816
	ds_read_b128 v[174:177], v145 offset:35840
	ds_read_b128 v[178:181], v145 offset:36864
	ds_read_b128 v[182:185], v145 offset:37888
	ds_read_b128 v[186:189], v145 offset:38912
	ds_read_b128 v[190:193], v145 offset:39936
	global_load_lds_dwordx4 v[200:201], off
	v_lshl_add_u64 v[200:201], s[56:57], 0, v[132:133]
	s_mov_b32 m0, s45
	s_nop 0
	global_load_lds_dwordx4 v[200:201], off
	s_waitcnt lgkmcnt(8)
	s_barrier
	s_waitcnt lgkmcnt(0)
	s_waitcnt lgkmcnt(0)
	v_mfma_f32_16x16x32_bf16 v[126:129], v[146:149], v[162:165], v[126:129]
	v_mfma_f32_16x16x32_bf16 v[122:125], v[154:157], v[162:165], v[122:125]
	v_mfma_f32_16x16x32_bf16 v[110:113], v[146:149], v[170:173], v[110:113]
	v_mfma_f32_16x16x32_bf16 v[106:109], v[154:157], v[170:173], v[106:109]
	v_mfma_f32_16x16x32_bf16 v[94:97], v[146:149], v[178:181], v[94:97]
	v_mfma_f32_16x16x32_bf16 v[90:93], v[154:157], v[178:181], v[90:93]
	v_mfma_f32_16x16x32_bf16 v[78:81], v[146:149], v[186:189], v[78:81]
	v_mfma_f32_16x16x32_bf16 v[74:77], v[154:157], v[186:189], v[74:77]
	v_mfma_f32_16x16x32_bf16 v[126:129], v[150:153], v[166:169], v[126:129]
	v_mfma_f32_16x16x32_bf16 v[122:125], v[158:161], v[166:169], v[122:125]
	v_mfma_f32_16x16x32_bf16 v[110:113], v[150:153], v[174:177], v[110:113]
	v_mfma_f32_16x16x32_bf16 v[106:109], v[158:161], v[174:177], v[106:109]
	v_mfma_f32_16x16x32_bf16 v[94:97], v[150:153], v[182:185], v[94:97]
	v_mfma_f32_16x16x32_bf16 v[90:93], v[158:161], v[182:185], v[90:93]
	v_mfma_f32_16x16x32_bf16 v[78:81], v[150:153], v[190:193], v[78:81]
	v_mfma_f32_16x16x32_bf16 v[74:77], v[158:161], v[190:193], v[74:77]
	s_barrier
	s_add_i32 s56, 0, 0x1c000
	s_add_i32 s57, s88, s13
	v_add_u32_e32 v209, s56, v143
	v_lshl_add_u64 v[140:141], v[140:141], 0, s[92:93]
	s_mov_b32 m0, s57
	ds_read_b128 v[200:203], v209
	ds_read_b128 v[216:219], v209 offset:1024
	ds_read_b128 v[220:223], v209 offset:2048
	ds_read_b128 v[224:227], v209 offset:3072
	global_load_lds_dwordx4 v[140:141], off
	v_lshl_add_u64 v[140:141], v[194:195], 0, s[92:93]
	s_add_i32 m0, s57, 0x2000
	s_nop 0
	global_load_lds_dwordx4 v[140:141], off
	s_barrier
	s_waitcnt lgkmcnt(0)
	s_waitcnt lgkmcnt(0)
	v_mfma_f32_16x16x32_bf16 v[118:121], v[200:203], v[162:165], v[118:121]
	v_mfma_f32_16x16x32_bf16 v[114:117], v[220:223], v[162:165], v[114:117]
	v_mfma_f32_16x16x32_bf16 v[102:105], v[200:203], v[170:173], v[102:105]
	v_mfma_f32_16x16x32_bf16 v[98:101], v[220:223], v[170:173], v[98:101]
	v_mfma_f32_16x16x32_bf16 v[86:89], v[200:203], v[178:181], v[86:89]
	v_mfma_f32_16x16x32_bf16 v[82:85], v[220:223], v[178:181], v[82:85]
	v_mfma_f32_16x16x32_bf16 v[70:73], v[200:203], v[186:189], v[70:73]
	v_mfma_f32_16x16x32_bf16 v[66:69], v[220:223], v[186:189], v[66:69]
	v_mfma_f32_16x16x32_bf16 v[118:121], v[216:219], v[166:169], v[118:121]
	v_mfma_f32_16x16x32_bf16 v[114:117], v[224:227], v[166:169], v[114:117]
	v_mfma_f32_16x16x32_bf16 v[102:105], v[216:219], v[174:177], v[102:105]
	v_mfma_f32_16x16x32_bf16 v[98:101], v[224:227], v[174:177], v[98:101]
	v_mfma_f32_16x16x32_bf16 v[86:89], v[216:219], v[182:185], v[86:89]
	v_mfma_f32_16x16x32_bf16 v[82:85], v[224:227], v[182:185], v[82:85]
	v_mfma_f32_16x16x32_bf16 v[70:73], v[216:219], v[190:193], v[70:73]
	v_mfma_f32_16x16x32_bf16 v[66:69], v[224:227], v[190:193], v[66:69]
	s_mov_b32 m0, s62
	v_lshl_add_u64 v[140:141], v[196:197], 0, s[92:93]
	s_barrier
	ds_read_b128 v[162:165], v145 offset:49152
	ds_read_b128 v[166:169], v145 offset:50176
	ds_read_b128 v[170:173], v145 offset:51200
	ds_read_b128 v[174:177], v145 offset:52224
	ds_read_b128 v[178:181], v145 offset:53248
	ds_read_b128 v[182:185], v145 offset:54272
	ds_read_b128 v[186:189], v145 offset:55296
	ds_read_b128 v[190:193], v145 offset:56320
	global_load_lds_dwordx4 v[140:141], off
	v_lshl_add_u64 v[140:141], v[198:199], 0, s[92:93]
	s_mov_b32 m0, s63
	s_nop 0
	global_load_lds_dwordx4 v[140:141], off
	s_barrier
; __device__ __forceinline__ unsigned cvt_pk_bf16(float lo, float hi) { unsigned r; asm volatile("v_cvt_pk_bf16_f32 %0, %1, %2" : "=v"(r) : "v"(lo), "v"(hi)); return r; }
; #define PG8_STAGE(bufoff, gbase, voff) do { _Pragma("unroll") for (int _i = 0; _i < 2; ++_i) \
;         __builtin_amdgcn_global_load_lds((const unsigned*)((const char*)(gbase) + (voff)[_i]), (PG8_LAS unsigned*)(lds + (bufoff) + ldsw + _i * 8192), 16, 0, 0); } while (0)
; #define PG8_MMA(ai, bj, At, Bt) do { __builtin_amdgcn_s_setprio(1); _Pragma("unroll") for (int m = 0; m < 4; ++m) _Pragma("unroll") for (int n = 0; n < 2; ++n) _Pragma("unroll") for (int k = 0; k < 2; ++k) \
;         acc[ai][bj][m][n] = __builtin_amdgcn_mfma_f32_16x16x32_bf16(Bt[n][k], At[m][k], acc[ai][bj][m][n], 0, 0, 0); __builtin_amdgcn_s_setprio(0); } while (0)
; #define PG8_WAIT_V(n) asm volatile("s_waitcnt vmcnt(" #n ")" ::: "memory")
; #define PG8_WAIT_L(n) asm volatile("s_waitcnt lgkmcnt(" #n ")" ::: "memory")
; #define PG8_BAR __builtin_amdgcn_s_barrier()
; template <class Epi, class Sched>
; __device__ __forceinline__ void gemm_phase(PG8_LAS unsigned char* lds, const Gemm g, const Sched& S, const Epi& E, const int tid) {
;     ...
;             PG8_BAR; PG8_WAIT_L(0); PG8_MMA(1, 0, At, B0); PG8_BAR; PG8_SCHED;
;             PG8_STAGE(PG8_SB(1, 1), b3 + hstep, voffB);
;             PG8_WAIT_V(6); PG8_BAR; PG8_MMA(1, 1, At, B1); PG8_BAR;
;     __device__ __forceinline__ void operator()(const f32x4 (&acc)[2][2][4][2], const Unit& u, int wr, int wc, int fr, int fq) const {
;         const int row0 = u.pm * BM + wr * 64 + fr, col0 = u.pn * BM + wc * 32 + 8 * fq;
; #pragma unroll
;         for (int ai = 0; ai < 2; ++ai)
; #pragma unroll
;             for (int m = 0; m < 4; ++m) { bf16_t* rowp = O + (size_t)(row0 + ai * HALF + m * 16) * ldc + col0;
; #pragma unroll
;                 for (int bj = 0; bj < 2; ++bj) { f32x4 v0 = acc[ai][bj][m][0], v1 = acc[ai][bj][m][1];
;                     if (ACT == 1) {
; #pragma unroll
;                         for (int j = 0; j < 4; ++j) { float a = v0[j] > 0.f ? v0[j] : 0.f, b = v1[j] > 0.f ? v1[j] : 0.f; v0[j] = a * a; v1[j] = b * b; } }
;                     u32x4 w; w.x = cvt_pk_bf16(v0[0], v0[1]); w.y = cvt_pk_bf16(v0[2], v0[3]); w.z = cvt_pk_bf16(v1[0], v1[1]); w.w = cvt_pk_bf16(v1[2], v1[3]);
;                     *(u32x4*)(rowp + bj * HALF) = w; } }
	s_waitcnt lgkmcnt(0)
	s_waitcnt lgkmcnt(0)
	v_mfma_f32_16x16x32_bf16 v[62:65], v[146:149], v[162:165], v[62:65]
	v_mfma_f32_16x16x32_bf16 v[58:61], v[154:157], v[162:165], v[58:61]
	v_mfma_f32_16x16x32_bf16 v[46:49], v[146:149], v[170:173], v[46:49]
	v_mfma_f32_16x16x32_bf16 v[42:45], v[154:157], v[170:173], v[42:45]
	v_mfma_f32_16x16x32_bf16 v[30:33], v[146:149], v[178:181], v[30:33]
	v_mfma_f32_16x16x32_bf16 v[26:29], v[154:157], v[178:181], v[26:29]
	v_mfma_f32_16x16x32_bf16 v[14:17], v[146:149], v[186:189], v[14:17]
	v_mfma_f32_16x16x32_bf16 v[10:13], v[154:157], v[186:189], v[10:13]
	v_mfma_f32_16x16x32_bf16 v[62:65], v[150:153], v[166:169], v[62:65]
	v_mfma_f32_16x16x32_bf16 v[58:61], v[158:161], v[166:169], v[58:61]
	v_mfma_f32_16x16x32_bf16 v[46:49], v[150:153], v[174:177], v[46:49]
	v_mfma_f32_16x16x32_bf16 v[42:45], v[158:161], v[174:177], v[42:45]
	v_mfma_f32_16x16x32_bf16 v[30:33], v[150:153], v[182:185], v[30:33]
	v_mfma_f32_16x16x32_bf16 v[26:29], v[158:161], v[182:185], v[26:29]
	v_mfma_f32_16x16x32_bf16 v[14:17], v[150:153], v[190:193], v[14:17]
	v_mfma_f32_16x16x32_bf16 v[10:13], v[158:161], v[190:193], v[10:13]
	s_barrier
	s_add_u32 s18, s18, 0x40080
	s_addc_u32 s19, s19, 0
	s_add_i32 s56, s56, s13
	v_lshl_add_u64 v[140:141], s[18:19], 0, v[0:1]
	s_mov_b32 m0, s56
	s_nop 0
	global_load_lds_dwordx4 v[140:141], off
	v_lshl_add_u64 v[140:141], s[18:19], 0, v[130:131]
	s_add_i32 m0, s56, 0x2000
	s_nop 0
	global_load_lds_dwordx4 v[140:141], off
	s_waitcnt vmcnt(6)
	s_barrier
	v_mfma_f32_16x16x32_bf16 v[54:57], v[200:203], v[162:165], v[54:57]
	v_mfma_f32_16x16x32_bf16 v[50:53], v[220:223], v[162:165], v[50:53]
	v_mfma_f32_16x16x32_bf16 v[38:41], v[200:203], v[170:173], v[38:41]
	v_mfma_f32_16x16x32_bf16 v[34:37], v[220:223], v[170:173], v[34:37]
	v_mfma_f32_16x16x32_bf16 v[22:25], v[200:203], v[178:181], v[22:25]
	v_mfma_f32_16x16x32_bf16 v[18:21], v[220:223], v[178:181], v[18:21]
	v_mfma_f32_16x16x32_bf16 v[6:9], v[200:203], v[186:189], v[6:9]
	v_mfma_f32_16x16x32_bf16 v[2:5], v[220:223], v[186:189], v[2:5]
	v_mfma_f32_16x16x32_bf16 v[54:57], v[216:219], v[166:169], v[54:57]
	v_mfma_f32_16x16x32_bf16 v[50:53], v[224:227], v[166:169], v[50:53]
	v_mfma_f32_16x16x32_bf16 v[38:41], v[216:219], v[174:177], v[38:41]
	v_mfma_f32_16x16x32_bf16 v[34:37], v[224:227], v[174:177], v[34:37]
	v_mfma_f32_16x16x32_bf16 v[22:25], v[216:219], v[182:185], v[22:25]
	v_mfma_f32_16x16x32_bf16 v[18:21], v[224:227], v[182:185], v[18:21]
	v_mfma_f32_16x16x32_bf16 v[6:9], v[216:219], v[190:193], v[6:9]
	v_mfma_f32_16x16x32_bf16 v[2:5], v[224:227], v[190:193], v[2:5]
	s_add_i32 s77, s77, 2
	s_add_u32 s14, s14, 0x100
	s_addc_u32 s15, s15, 0
	s_add_u32 s73, s73, 0x100
	s_addc_u32 s76, s76, 0
	s_cmp_gt_u32 s77, 13
	s_barrier
	s_cbranch_scc0 .LBB0_199
	v_lshl_add_u32 v146, s68, 8, v142
	v_max_f32_e32 v122, v122, v122
	v_ashrrev_i32_e32 v147, 31, v146
	v_max_f32_e32 v122, 0, v122
	v_max_f32_e32 v123, v123, v123
	v_max_f32_e32 v124, v124, v124
	v_lshl_or_b32 v140, s65, 8, v144
	v_lshlrev_b64 v[148:149], 13, v[146:147]
	v_mul_f32_e32 v147, v122, v122
	v_max_f32_e32 v122, v127, v127
	v_max_f32_e32 v123, 0, v123
	v_max_f32_e32 v124, 0, v124
	v_ashrrev_i32_e32 v141, 31, v140
	v_max_f32_e32 v126, v126, v126
	v_max_f32_e32 v122, 0, v122
	v_mul_f32_e32 v127, v123, v123
	v_max_f32_e32 v123, v128, v128
	v_mul_f32_e32 v128, v124, v124
	v_max_f32_e32 v124, v129, v129
	v_max_f32_e32 v125, v125, v125
	v_lshl_add_u64 v[148:149], s[86:87], 0, v[148:149]
	v_lshlrev_b64 v[150:151], 1, v[140:141]
	v_max_f32_e32 v126, 0, v126
	v_mul_f32_e32 v122, v122, v122
	v_max_f32_e32 v123, 0, v123
	v_max_f32_e32 v124, 0, v124
	v_max_f32_e32 v125, 0, v125
	v_max_f32_e32 v114, v114, v114
	v_lshl_add_u64 v[140:141], v[148:149], 0, v[150:151]
	v_mul_f32_e32 v126, v126, v126
	v_mul_f32_e32 v123, v123, v123
	v_mul_f32_e32 v124, v124, v124
	v_mul_f32_e32 v125, v125, v125
	v_cvt_pk_bf16_f32 v122, v126, v122
	v_max_f32_e32 v114, 0, v114
	v_max_f32_e32 v115, v115, v115
	v_max_f32_e32 v116, v116, v116
	v_cvt_pk_bf16_f32 v123, v123, v124
	v_cvt_pk_bf16_f32 v124, v147, v127
	v_cvt_pk_bf16_f32 v125, v128, v125
	global_store_dwordx4 v[140:141], v[122:125], off
	v_max_f32_e32 v115, 0, v115
	v_max_f32_e32 v116, 0, v116
	v_mul_f32_e32 v122, v114, v114
	v_max_f32_e32 v114, v119, v119
	v_max_f32_e32 v118, v118, v118
	v_max_f32_e32 v114, 0, v114
	v_mul_f32_e32 v119, v115, v115
	v_max_f32_e32 v115, v120, v120
	v_mul_f32_e32 v120, v116, v116
	v_max_f32_e32 v116, v121, v121
	v_max_f32_e32 v117, v117, v117
	v_max_f32_e32 v118, 0, v118
	v_mul_f32_e32 v114, v114, v114
	v_max_f32_e32 v115, 0, v115
	v_max_f32_e32 v116, 0, v116
	v_max_f32_e32 v117, 0, v117
	v_mul_f32_e32 v118, v118, v118
	v_mul_f32_e32 v115, v115, v115
	v_mul_f32_e32 v116, v116, v116
	v_mul_f32_e32 v117, v117, v117
	v_cvt_pk_bf16_f32 v114, v118, v114
	v_max_f32_e32 v106, v106, v106
	v_cvt_pk_bf16_f32 v115, v115, v116
	v_cvt_pk_bf16_f32 v116, v122, v119
	v_cvt_pk_bf16_f32 v117, v120, v117
	global_store_dwordx4 v[140:141], v[114:117], off offset:256
	v_max_f32_e32 v106, 0, v106
	v_max_f32_e32 v107, v107, v107
	v_or_b32_e32 v114, 16, v146
	v_max_f32_e32 v108, v108, v108
	v_ashrrev_i32_e32 v115, 31, v114
	v_mul_f32_e32 v116, v106, v106
	v_max_f32_e32 v106, v111, v111
	v_max_f32_e32 v107, 0, v107
	v_max_f32_e32 v108, 0, v108
	v_lshlrev_b64 v[114:115], 13, v[114:115]
	v_max_f32_e32 v110, v110, v110
	v_max_f32_e32 v106, 0, v106
	v_mul_f32_e32 v111, v107, v107
	v_max_f32_e32 v107, v112, v112
	v_mul_f32_e32 v112, v108, v108
	v_max_f32_e32 v108, v113, v113
	v_max_f32_e32 v109, v109, v109
	v_lshl_add_u64 v[114:115], s[86:87], 0, v[114:115]
	v_max_f32_e32 v110, 0, v110
; __device__ __forceinline__ unsigned cvt_pk_bf16(float lo, float hi) { unsigned r; asm volatile("v_cvt_pk_bf16_f32 %0, %1, %2" : "=v"(r) : "v"(lo), "v"(hi)); return r; }
;     __device__ __forceinline__ void operator()(const f32x4 (&acc)[2][2][4][2], const Unit& u, int wr, int wc, int fr, int fq) const {
;         const int row0 = u.pm * BM + wr * 64 + fr, col0 = u.pn * BM + wc * 32 + 8 * fq;
; #pragma unroll
;         for (int ai = 0; ai < 2; ++ai)
; #pragma unroll
;             for (int m = 0; m < 4; ++m) { bf16_t* rowp = O + (size_t)(row0 + ai * HALF + m * 16) * ldc + col0;
; #pragma unroll
;                 for (int bj = 0; bj < 2; ++bj) { f32x4 v0 = acc[ai][bj][m][0], v1 = acc[ai][bj][m][1];
;                     if (ACT == 1) {
; #pragma unroll
;                         for (int j = 0; j < 4; ++j) { float a = v0[j] > 0.f ? v0[j] : 0.f, b = v1[j] > 0.f ? v1[j] : 0.f; v0[j] = a * a; v1[j] = b * b; } }
;                     u32x4 w; w.x = cvt_pk_bf16(v0[0], v0[1]); w.y = cvt_pk_bf16(v0[2], v0[3]); w.z = cvt_pk_bf16(v1[0], v1[1]); w.w = cvt_pk_bf16(v1[2], v1[3]);
;                     *(u32x4*)(rowp + bj * HALF) = w; } }
	v_mul_f32_e32 v106, v106, v106
	v_max_f32_e32 v107, 0, v107
	v_max_f32_e32 v108, 0, v108
	v_max_f32_e32 v109, 0, v109
	v_max_f32_e32 v98, v98, v98
	v_lshl_add_u64 v[114:115], v[114:115], 0, v[150:151]
	v_mul_f32_e32 v110, v110, v110
	v_mul_f32_e32 v107, v107, v107
	v_mul_f32_e32 v108, v108, v108
	v_mul_f32_e32 v109, v109, v109
	v_cvt_pk_bf16_f32 v106, v110, v106
	v_max_f32_e32 v98, 0, v98
	v_max_f32_e32 v99, v99, v99
	v_max_f32_e32 v100, v100, v100
	v_cvt_pk_bf16_f32 v107, v107, v108
	v_cvt_pk_bf16_f32 v108, v116, v111
	v_cvt_pk_bf16_f32 v109, v112, v109
	global_store_dwordx4 v[114:115], v[106:109], off
	v_max_f32_e32 v99, 0, v99
	v_max_f32_e32 v100, 0, v100
	v_mul_f32_e32 v106, v98, v98
	v_max_f32_e32 v98, v103, v103
	v_max_f32_e32 v102, v102, v102
	v_max_f32_e32 v98, 0, v98
	v_mul_f32_e32 v103, v99, v99
	v_max_f32_e32 v99, v104, v104
	v_mul_f32_e32 v104, v100, v100
	v_max_f32_e32 v100, v105, v105
	v_max_f32_e32 v101, v101, v101
	v_max_f32_e32 v102, 0, v102
	v_mul_f32_e32 v98, v98, v98
	v_max_f32_e32 v99, 0, v99
	v_max_f32_e32 v100, 0, v100
	v_max_f32_e32 v101, 0, v101
	v_mul_f32_e32 v102, v102, v102
	v_mul_f32_e32 v99, v99, v99
	v_mul_f32_e32 v100, v100, v100
	v_mul_f32_e32 v101, v101, v101
	v_cvt_pk_bf16_f32 v98, v102, v98
	v_max_f32_e32 v90, v90, v90
	v_cvt_pk_bf16_f32 v99, v99, v100
	v_cvt_pk_bf16_f32 v100, v106, v103
	v_cvt_pk_bf16_f32 v101, v104, v101
	global_store_dwordx4 v[114:115], v[98:101], off offset:256
	v_max_f32_e32 v90, 0, v90
	v_max_f32_e32 v91, v91, v91
	v_or_b32_e32 v98, 32, v146
	v_max_f32_e32 v92, v92, v92
	v_ashrrev_i32_e32 v99, 31, v98
	v_mul_f32_e32 v100, v90, v90
	v_max_f32_e32 v90, v95, v95
	v_max_f32_e32 v91, 0, v91
	v_max_f32_e32 v92, 0, v92
	v_lshlrev_b64 v[98:99], 13, v[98:99]
	v_max_f32_e32 v94, v94, v94
	v_max_f32_e32 v90, 0, v90
	v_mul_f32_e32 v95, v91, v91
	v_max_f32_e32 v91, v96, v96
	v_mul_f32_e32 v96, v92, v92
	v_max_f32_e32 v92, v97, v97
	v_max_f32_e32 v93, v93, v93
	v_lshl_add_u64 v[98:99], s[86:87], 0, v[98:99]
	v_max_f32_e32 v94, 0, v94
	v_mul_f32_e32 v90, v90, v90
	v_max_f32_e32 v91, 0, v91
	v_max_f32_e32 v92, 0, v92
	v_max_f32_e32 v93, 0, v93
	v_max_f32_e32 v82, v82, v82
	v_lshl_add_u64 v[98:99], v[98:99], 0, v[150:151]
	v_mul_f32_e32 v94, v94, v94
	v_mul_f32_e32 v91, v91, v91
	v_mul_f32_e32 v92, v92, v92
	v_mul_f32_e32 v93, v93, v93
	v_cvt_pk_bf16_f32 v90, v94, v90
	v_max_f32_e32 v82, 0, v82
	v_max_f32_e32 v83, v83, v83
	v_max_f32_e32 v84, v84, v84
	v_cvt_pk_bf16_f32 v91, v91, v92
	v_cvt_pk_bf16_f32 v92, v100, v95
	v_cvt_pk_bf16_f32 v93, v96, v93
	global_store_dwordx4 v[98:99], v[90:93], off
	v_max_f32_e32 v83, 0, v83
	v_max_f32_e32 v84, 0, v84
	v_mul_f32_e32 v90, v82, v82
	v_max_f32_e32 v82, v87, v87
	v_max_f32_e32 v86, v86, v86
	v_max_f32_e32 v82, 0, v82
	v_mul_f32_e32 v87, v83, v83
	v_max_f32_e32 v83, v88, v88
	v_mul_f32_e32 v88, v84, v84
	v_max_f32_e32 v84, v89, v89
	v_max_f32_e32 v85, v85, v85
	v_max_f32_e32 v86, 0, v86
	v_mul_f32_e32 v82, v82, v82
	v_max_f32_e32 v83, 0, v83
	v_max_f32_e32 v84, 0, v84
	v_max_f32_e32 v85, 0, v85
	v_mul_f32_e32 v86, v86, v86
	v_mul_f32_e32 v83, v83, v83
	v_mul_f32_e32 v84, v84, v84
	v_mul_f32_e32 v85, v85, v85
	v_cvt_pk_bf16_f32 v82, v86, v82
	v_max_f32_e32 v74, v74, v74
	v_cvt_pk_bf16_f32 v83, v83, v84
	v_cvt_pk_bf16_f32 v84, v90, v87
	v_cvt_pk_bf16_f32 v85, v88, v85
	global_store_dwordx4 v[98:99], v[82:85], off offset:256
	v_max_f32_e32 v74, 0, v74
	v_max_f32_e32 v75, v75, v75
	v_or_b32_e32 v82, 48, v146
	v_max_f32_e32 v76, v76, v76
	v_ashrrev_i32_e32 v83, 31, v82
	v_mul_f32_e32 v84, v74, v74
	v_max_f32_e32 v74, v79, v79
	v_max_f32_e32 v75, 0, v75
	v_max_f32_e32 v76, 0, v76
	v_lshlrev_b64 v[82:83], 13, v[82:83]
	v_max_f32_e32 v78, v78, v78
	v_max_f32_e32 v74, 0, v74
	v_mul_f32_e32 v79, v75, v75
	v_max_f32_e32 v75, v80, v80
	v_mul_f32_e32 v80, v76, v76
	v_max_f32_e32 v76, v81, v81
	v_max_f32_e32 v77, v77, v77
	v_lshl_add_u64 v[82:83], s[86:87], 0, v[82:83]
	v_max_f32_e32 v78, 0, v78
	v_mul_f32_e32 v74, v74, v74
	v_max_f32_e32 v75, 0, v75
	v_max_f32_e32 v76, 0, v76
	v_max_f32_e32 v77, 0, v77
	v_max_f32_e32 v66, v66, v66
	v_max_f32_e32 v67, v67, v67
	v_max_f32_e32 v68, v68, v68
	v_lshl_add_u64 v[82:83], v[82:83], 0, v[150:151]
	v_mul_f32_e32 v78, v78, v78
	v_mul_f32_e32 v75, v75, v75
	v_mul_f32_e32 v76, v76, v76
	v_mul_f32_e32 v77, v77, v77
	v_cvt_pk_bf16_f32 v74, v78, v74
	v_max_f32_e32 v66, 0, v66
	v_max_f32_e32 v67, 0, v67
	v_max_f32_e32 v68, 0, v68
	v_cvt_pk_bf16_f32 v75, v75, v76
	v_cvt_pk_bf16_f32 v76, v84, v79
	v_cvt_pk_bf16_f32 v77, v80, v77
	global_store_dwordx4 v[82:83], v[74:77], off
	v_max_f32_e32 v70, v70, v70
	v_max_f32_e32 v69, v69, v69
	v_mul_f32_e32 v74, v66, v66
	v_max_f32_e32 v66, v71, v71
	v_mul_f32_e32 v71, v67, v67
	v_max_f32_e32 v67, v72, v72
	v_mul_f32_e32 v72, v68, v68
	v_max_f32_e32 v68, v73, v73
	v_max_f32_e32 v66, 0, v66
	v_max_f32_e32 v67, 0, v67
	v_max_f32_e32 v68, 0, v68
	v_max_f32_e32 v70, 0, v70
	v_mul_f32_e32 v66, v66, v66
	v_mul_f32_e32 v67, v67, v67
	v_max_f32_e32 v69, 0, v69
	v_mul_f32_e32 v68, v68, v68
	v_max_f32_e32 v58, v58, v58
	v_mul_f32_e32 v70, v70, v70
	v_mul_f32_e32 v69, v69, v69
	v_cvt_pk_bf16_f32 v66, v70, v66
	v_cvt_pk_bf16_f32 v67, v67, v68
	v_cvt_pk_bf16_f32 v68, v74, v71
	v_max_f32_e32 v58, 0, v58
	v_max_f32_e32 v59, v59, v59
	v_max_f32_e32 v60, v60, v60
	v_cvt_pk_bf16_f32 v69, v72, v69
	global_store_dwordx4 v[82:83], v[66:69], off offset:256
	v_max_f32_e32 v62, v62, v62
	v_max_f32_e32 v59, 0, v59
	v_mul_f32_e32 v68, v58, v58
	v_max_f32_e32 v58, v63, v63
	v_max_f32_e32 v60, 0, v60
	v_max_f32_e32 v62, 0, v62
	v_max_f32_e32 v58, 0, v58
	v_mul_f32_e32 v63, v59, v59
	v_max_f32_e32 v59, v64, v64
; __device__ __forceinline__ unsigned cvt_pk_bf16(float lo, float hi) { unsigned r; asm volatile("v_cvt_pk_bf16_f32 %0, %1, %2" : "=v"(r) : "v"(lo), "v"(hi)); return r; }
;     __device__ __forceinline__ void operator()(const f32x4 (&acc)[2][2][4][2], const Unit& u, int wr, int wc, int fr, int fq) const {
;         const int row0 = u.pm * BM + wr * 64 + fr, col0 = u.pn * BM + wc * 32 + 8 * fq;
; #pragma unroll
;         for (int ai = 0; ai < 2; ++ai)
; #pragma unroll
;             for (int m = 0; m < 4; ++m) { bf16_t* rowp = O + (size_t)(row0 + ai * HALF + m * 16) * ldc + col0;
; #pragma unroll
;                 for (int bj = 0; bj < 2; ++bj) { f32x4 v0 = acc[ai][bj][m][0], v1 = acc[ai][bj][m][1];
;                     if (ACT == 1) {
; #pragma unroll
;                         for (int j = 0; j < 4; ++j) { float a = v0[j] > 0.f ? v0[j] : 0.f, b = v1[j] > 0.f ? v1[j] : 0.f; v0[j] = a * a; v1[j] = b * b; } }
;                     u32x4 w; w.x = cvt_pk_bf16(v0[0], v0[1]); w.y = cvt_pk_bf16(v0[2], v0[3]); w.z = cvt_pk_bf16(v1[0], v1[1]); w.w = cvt_pk_bf16(v1[2], v1[3]);
;                     *(u32x4*)(rowp + bj * HALF) = w; } }
	v_mul_f32_e32 v64, v60, v60
	v_max_f32_e32 v60, v65, v65
	v_mul_f32_e32 v62, v62, v62
	v_mul_f32_e32 v58, v58, v58
	v_max_f32_e32 v59, 0, v59
	v_max_f32_e32 v60, 0, v60
	v_max_f32_e32 v61, v61, v61
	v_mul_f32_e32 v59, v59, v59
	v_max_f32_e32 v61, 0, v61
	v_mul_f32_e32 v60, v60, v60
	v_cvt_pk_bf16_f32 v58, v62, v58
	v_add_co_u32_e32 v62, vcc, s38, v140
	v_max_f32_e32 v50, v50, v50
	v_max_f32_e32 v51, v51, v51
	v_max_f32_e32 v52, v52, v52
	v_mul_f32_e32 v61, v61, v61
	v_cvt_pk_bf16_f32 v59, v59, v60
	v_cvt_pk_bf16_f32 v60, v68, v63
	v_addc_co_u32_e32 v63, vcc, 0, v141, vcc
	v_max_f32_e32 v50, 0, v50
	v_max_f32_e32 v51, 0, v51
	v_max_f32_e32 v52, 0, v52
	v_cvt_pk_bf16_f32 v61, v64, v61
	global_store_dwordx4 v[62:63], v[58:61], off
	v_max_f32_e32 v54, v54, v54
	v_max_f32_e32 v53, v53, v53
	v_mul_f32_e32 v58, v50, v50
	v_max_f32_e32 v50, v55, v55
	v_mul_f32_e32 v55, v51, v51
	v_max_f32_e32 v51, v56, v56
	v_mul_f32_e32 v56, v52, v52
	v_max_f32_e32 v52, v57, v57
	v_max_f32_e32 v50, 0, v50
	v_max_f32_e32 v51, 0, v51
	v_max_f32_e32 v52, 0, v52
	s_mov_b64 s[14:15], 0x100000
	v_max_f32_e32 v54, 0, v54
	v_mul_f32_e32 v50, v50, v50
	v_mul_f32_e32 v51, v51, v51
	v_max_f32_e32 v53, 0, v53
	v_mul_f32_e32 v52, v52, v52
	v_max_f32_e32 v42, v42, v42
	v_lshl_add_u64 v[66:67], v[140:141], 0, s[14:15]
	v_mul_f32_e32 v54, v54, v54
	v_mul_f32_e32 v53, v53, v53
	v_cvt_pk_bf16_f32 v50, v54, v50
	v_cvt_pk_bf16_f32 v51, v51, v52
	v_cvt_pk_bf16_f32 v52, v58, v55
	v_max_f32_e32 v42, 0, v42
	v_max_f32_e32 v43, v43, v43
	v_max_f32_e32 v44, v44, v44
	v_cvt_pk_bf16_f32 v53, v56, v53
	global_store_dwordx4 v[66:67], v[50:53], off offset:256
	v_max_f32_e32 v46, v46, v46
	v_max_f32_e32 v43, 0, v43
	v_mul_f32_e32 v52, v42, v42
	v_max_f32_e32 v42, v47, v47
	v_max_f32_e32 v44, 0, v44
	v_max_f32_e32 v46, 0, v46
	v_max_f32_e32 v42, 0, v42
	v_mul_f32_e32 v47, v43, v43
	v_max_f32_e32 v43, v48, v48
	v_mul_f32_e32 v48, v44, v44
	v_max_f32_e32 v44, v49, v49
	v_mul_f32_e32 v46, v46, v46
	v_mul_f32_e32 v42, v42, v42
	v_max_f32_e32 v43, 0, v43
	v_max_f32_e32 v44, 0, v44
	v_max_f32_e32 v45, v45, v45
	s_mov_b32 s5, 0x120000
	v_mul_f32_e32 v43, v43, v43
	v_max_f32_e32 v45, 0, v45
	v_mul_f32_e32 v44, v44, v44
	v_cvt_pk_bf16_f32 v42, v46, v42
	v_add_co_u32_e32 v46, vcc, s5, v140
	v_max_f32_e32 v34, v34, v34
	v_max_f32_e32 v35, v35, v35
	v_max_f32_e32 v36, v36, v36
	v_mul_f32_e32 v45, v45, v45
	v_cvt_pk_bf16_f32 v43, v43, v44
	v_cvt_pk_bf16_f32 v44, v52, v47
	v_addc_co_u32_e32 v47, vcc, 0, v141, vcc
	v_max_f32_e32 v34, 0, v34
	v_max_f32_e32 v35, 0, v35
	v_max_f32_e32 v36, 0, v36
	v_cvt_pk_bf16_f32 v45, v48, v45
	global_store_dwordx4 v[46:47], v[42:45], off
	v_max_f32_e32 v38, v38, v38
	v_max_f32_e32 v37, v37, v37
	v_mul_f32_e32 v42, v34, v34
	v_max_f32_e32 v34, v39, v39
	v_mul_f32_e32 v39, v35, v35
	v_max_f32_e32 v35, v40, v40
	v_mul_f32_e32 v40, v36, v36
	v_max_f32_e32 v36, v41, v41
	v_max_f32_e32 v34, 0, v34
	v_max_f32_e32 v35, 0, v35
	v_max_f32_e32 v36, 0, v36
	s_mov_b64 s[14:15], 0x120000
	v_max_f32_e32 v38, 0, v38
	v_mul_f32_e32 v34, v34, v34
	v_mul_f32_e32 v35, v35, v35
	v_max_f32_e32 v37, 0, v37
	v_mul_f32_e32 v36, v36, v36
	v_max_f32_e32 v26, v26, v26
	v_lshl_add_u64 v[50:51], v[140:141], 0, s[14:15]
	v_mul_f32_e32 v38, v38, v38
	v_mul_f32_e32 v37, v37, v37
	v_cvt_pk_bf16_f32 v34, v38, v34
	v_cvt_pk_bf16_f32 v35, v35, v36
	v_cvt_pk_bf16_f32 v36, v42, v39
	v_max_f32_e32 v26, 0, v26
	v_max_f32_e32 v27, v27, v27
	v_max_f32_e32 v28, v28, v28
	v_cvt_pk_bf16_f32 v37, v40, v37
	global_store_dwordx4 v[50:51], v[34:37], off offset:256
	v_max_f32_e32 v30, v30, v30
	v_max_f32_e32 v27, 0, v27
	v_mul_f32_e32 v36, v26, v26
	v_max_f32_e32 v26, v31, v31
	v_max_f32_e32 v28, 0, v28
	v_max_f32_e32 v30, 0, v30
; __device__ __forceinline__ unsigned cvt_pk_bf16(float lo, float hi) { unsigned r; asm volatile("v_cvt_pk_bf16_f32 %0, %1, %2" : "=v"(r) : "v"(lo), "v"(hi)); return r; }
; #define PG8_WAIT_V(n) asm volatile("s_waitcnt vmcnt(" #n ")" ::: "memory")
; #define PG8_BAR __builtin_amdgcn_s_barrier()
; template <class Epi, class Sched>
; __device__ __forceinline__ void gemm_phase(PG8_LAS unsigned char* lds, const Gemm g, const Sched& S, const Epi& E, const int tid) {
;     ...
;         if (!has_next) break;
;     ...
;     PG8_WAIT_V(0);
;     if (wr == 0) PG8_BAR;
;     PG8_BAR;
;     __device__ __forceinline__ void operator()(const f32x4 (&acc)[2][2][4][2], const Unit& u, int wr, int wc, int fr, int fq) const {
;         const int row0 = u.pm * BM + wr * 64 + fr, col0 = u.pn * BM + wc * 32 + 8 * fq;
; #pragma unroll
;         for (int ai = 0; ai < 2; ++ai)
; #pragma unroll
;             for (int m = 0; m < 4; ++m) { bf16_t* rowp = O + (size_t)(row0 + ai * HALF + m * 16) * ldc + col0;
; #pragma unroll
;                 for (int bj = 0; bj < 2; ++bj) { f32x4 v0 = acc[ai][bj][m][0], v1 = acc[ai][bj][m][1];
;                     if (ACT == 1) {
; #pragma unroll
;                         for (int j = 0; j < 4; ++j) { float a = v0[j] > 0.f ? v0[j] : 0.f, b = v1[j] > 0.f ? v1[j] : 0.f; v0[j] = a * a; v1[j] = b * b; } }
;                     u32x4 w; w.x = cvt_pk_bf16(v0[0], v0[1]); w.y = cvt_pk_bf16(v0[2], v0[3]); w.z = cvt_pk_bf16(v1[0], v1[1]); w.w = cvt_pk_bf16(v1[2], v1[3]);
;                     *(u32x4*)(rowp + bj * HALF) = w; } }
	v_max_f32_e32 v26, 0, v26
	v_mul_f32_e32 v31, v27, v27
	v_max_f32_e32 v27, v32, v32
	v_mul_f32_e32 v32, v28, v28
	v_max_f32_e32 v28, v33, v33
	v_mul_f32_e32 v30, v30, v30
	v_mul_f32_e32 v26, v26, v26
	v_max_f32_e32 v27, 0, v27
	v_max_f32_e32 v28, 0, v28
	v_max_f32_e32 v29, v29, v29
	s_mov_b32 s5, 0x140000
	v_mul_f32_e32 v27, v27, v27
	v_max_f32_e32 v29, 0, v29
	v_mul_f32_e32 v28, v28, v28
	v_cvt_pk_bf16_f32 v26, v30, v26
	v_add_co_u32_e32 v30, vcc, s5, v140
	v_max_f32_e32 v18, v18, v18
	v_max_f32_e32 v19, v19, v19
	v_max_f32_e32 v20, v20, v20
	v_mul_f32_e32 v29, v29, v29
	v_cvt_pk_bf16_f32 v27, v27, v28
	v_cvt_pk_bf16_f32 v28, v36, v31
	v_addc_co_u32_e32 v31, vcc, 0, v141, vcc
	v_max_f32_e32 v18, 0, v18
	v_max_f32_e32 v19, 0, v19
	v_max_f32_e32 v20, 0, v20
	v_cvt_pk_bf16_f32 v29, v32, v29
	global_store_dwordx4 v[30:31], v[26:29], off
	v_max_f32_e32 v22, v22, v22
	v_max_f32_e32 v21, v21, v21
	v_mul_f32_e32 v26, v18, v18
	v_max_f32_e32 v18, v23, v23
	v_mul_f32_e32 v23, v19, v19
	v_max_f32_e32 v19, v24, v24
	v_mul_f32_e32 v24, v20, v20
	v_max_f32_e32 v20, v25, v25
	v_max_f32_e32 v18, 0, v18
	v_max_f32_e32 v19, 0, v19
	v_max_f32_e32 v20, 0, v20
	s_mov_b64 s[14:15], 0x140000
	v_max_f32_e32 v22, 0, v22
	v_mul_f32_e32 v18, v18, v18
	v_mul_f32_e32 v19, v19, v19
	v_max_f32_e32 v21, 0, v21
	v_mul_f32_e32 v20, v20, v20
	v_max_f32_e32 v10, v10, v10
	v_lshl_add_u64 v[34:35], v[140:141], 0, s[14:15]
	v_mul_f32_e32 v22, v22, v22
	v_mul_f32_e32 v21, v21, v21
	v_cvt_pk_bf16_f32 v18, v22, v18
	v_cvt_pk_bf16_f32 v19, v19, v20
	v_cvt_pk_bf16_f32 v20, v26, v23
	v_max_f32_e32 v10, 0, v10
	v_max_f32_e32 v11, v11, v11
	v_max_f32_e32 v12, v12, v12
	v_cvt_pk_bf16_f32 v21, v24, v21
	global_store_dwordx4 v[34:35], v[18:21], off offset:256
	v_max_f32_e32 v14, v14, v14
	v_max_f32_e32 v11, 0, v11
	v_mul_f32_e32 v20, v10, v10
	v_max_f32_e32 v10, v15, v15
	v_max_f32_e32 v12, 0, v12
	v_max_f32_e32 v14, 0, v14
	v_max_f32_e32 v10, 0, v10
	v_mul_f32_e32 v15, v11, v11
	v_max_f32_e32 v11, v16, v16
	v_mul_f32_e32 v16, v12, v12
	v_max_f32_e32 v12, v17, v17
	v_mul_f32_e32 v14, v14, v14
	v_mul_f32_e32 v10, v10, v10
	v_max_f32_e32 v11, 0, v11
	v_max_f32_e32 v12, 0, v12
	v_max_f32_e32 v13, v13, v13
	s_mov_b32 s5, 0x160000
	v_mul_f32_e32 v11, v11, v11
	v_max_f32_e32 v13, 0, v13
	v_mul_f32_e32 v12, v12, v12
	v_cvt_pk_bf16_f32 v10, v14, v10
	v_add_co_u32_e32 v14, vcc, s5, v140
	v_max_f32_e32 v2, v2, v2
	v_max_f32_e32 v3, v3, v3
	v_max_f32_e32 v4, v4, v4
	v_mul_f32_e32 v13, v13, v13
	v_cvt_pk_bf16_f32 v11, v11, v12
	v_cvt_pk_bf16_f32 v12, v20, v15
	v_addc_co_u32_e32 v15, vcc, 0, v141, vcc
	v_max_f32_e32 v2, 0, v2
	v_max_f32_e32 v3, 0, v3
	v_max_f32_e32 v4, 0, v4
	v_cvt_pk_bf16_f32 v13, v16, v13
	global_store_dwordx4 v[14:15], v[10:13], off
	v_max_f32_e32 v5, v5, v5
	s_mov_b64 s[14:15], 0x160000
	v_mul_f32_e32 v10, v2, v2
	v_max_f32_e32 v2, v7, v7
	v_mul_f32_e32 v7, v3, v3
	v_max_f32_e32 v3, v8, v8
	v_mul_f32_e32 v8, v4, v4
	v_max_f32_e32 v4, v9, v9
	v_max_f32_e32 v6, v6, v6
	v_max_f32_e32 v2, 0, v2
	v_max_f32_e32 v3, 0, v3
	v_max_f32_e32 v4, 0, v4
	v_max_f32_e32 v5, 0, v5
	v_lshl_add_u64 v[18:19], v[140:141], 0, s[14:15]
	v_max_f32_e32 v6, 0, v6
	v_mul_f32_e32 v2, v2, v2
	v_mul_f32_e32 v3, v3, v3
	v_mul_f32_e32 v4, v4, v4
	v_mul_f32_e32 v5, v5, v5
	s_and_b64 vcc, exec, s[2:3]
	s_mov_b32 s65, s4
	s_mov_b32 s68, s6
	s_mov_b64 s[18:19], s[10:11]
	s_mov_b64 s[14:15], s[8:9]
	v_mul_f32_e32 v6, v6, v6
	v_cvt_pk_bf16_f32 v2, v6, v2
	v_cvt_pk_bf16_f32 v3, v3, v4
	v_cvt_pk_bf16_f32 v4, v10, v7
	v_cvt_pk_bf16_f32 v5, v8, v5
	global_store_dwordx4 v[18:19], v[2:5], off offset:256
	s_cbranch_vccz .LBB0_192
	s_waitcnt vmcnt(0)
	s_cmpk_gt_u32 s0, 0xff
	s_cbranch_scc1 .LBB0_203
	s_barrier

; template <class Epi, class Sched>
; __device__ __forceinline__ void gemm_phase(PG8_LAS unsigned char* lds, const Gemm g, const Sched& S, const Epi& E, const int tid) {
;     ...
;         const bool has_next = S.next(ui + 1, nxt);
;         const char* nA = has_next ? (const char*)g.A + a_tile_row(g, nxt.pm) * (size_t)K * 2 : cA; const char* nB = has_next ? (const char*)g.Bt + (size_t)nxt.pn * tstep : cB;
;         for (int t = 0; t < nt; t += 2) {
;             const bool last = (t == nt - 2);
;             const char* a1 = cA + (size_t)(t + 1) * kstep;
;             const char* a2 = last ? nA : cA + (size_t)(t + 2) * kstep; const char* b2 = last ? nB : cB + (size_t)(t + 2) * kstep;
;     ...
; #pragma unroll
;         for (int a = 0; a < 2; ++a)
; #pragma unroll
;             for (int b = 0; b < 2; ++b)
; #pragma unroll
;                 for (int m = 0; m < 4; ++m)
; #pragma unroll
;                     for (int n = 0; n < 2; ++n) acc[a][b][m][n] = (f32x4){0.f, 0.f, 0.f, 0.f};
.LBB0_474:
	s_add_u32 s68, s68, 0x80
	s_addc_u32 s69, s69, 0
	s_add_u32 s90, s72, 0x100
	v_mov_b32_e32 v2, 0
	s_addc_u32 s91, s73, 0
	s_mov_b32 s56, 0
	v_mov_b32_e32 v3, v2
	v_mov_b32_e32 v4, v2
	v_mov_b32_e32 v5, v2
	v_mov_b32_e32 v6, v2
	v_mov_b32_e32 v7, v2
	v_mov_b32_e32 v8, v2
	v_mov_b32_e32 v9, v2
	v_mov_b32_e32 v14, v2
	v_mov_b32_e32 v15, v2
	v_mov_b32_e32 v16, v2
	v_mov_b32_e32 v17, v2
	v_mov_b32_e32 v18, v2
	v_mov_b32_e32 v19, v2
	v_mov_b32_e32 v20, v2
	v_mov_b32_e32 v21, v2
	v_mov_b32_e32 v30, v2
	v_mov_b32_e32 v31, v2
	v_mov_b32_e32 v32, v2
	v_mov_b32_e32 v33, v2
	v_mov_b32_e32 v34, v2
	v_mov_b32_e32 v35, v2
	v_mov_b32_e32 v36, v2
	v_mov_b32_e32 v37, v2
	v_mov_b32_e32 v46, v2
	v_mov_b32_e32 v47, v2
	v_mov_b32_e32 v48, v2
	v_mov_b32_e32 v49, v2
	v_mov_b32_e32 v50, v2
	v_mov_b32_e32 v51, v2
	v_mov_b32_e32 v52, v2
	v_mov_b32_e32 v53, v2
	v_mov_b32_e32 v10, v2
	v_mov_b32_e32 v11, v2
	v_mov_b32_e32 v12, v2
	v_mov_b32_e32 v13, v2
	v_mov_b32_e32 v22, v2
	v_mov_b32_e32 v23, v2
	v_mov_b32_e32 v24, v2
	v_mov_b32_e32 v25, v2
	v_mov_b32_e32 v26, v2
	v_mov_b32_e32 v27, v2
	v_mov_b32_e32 v28, v2
	v_mov_b32_e32 v29, v2
	v_mov_b32_e32 v38, v2
	v_mov_b32_e32 v39, v2
	v_mov_b32_e32 v40, v2
	v_mov_b32_e32 v41, v2
	v_mov_b32_e32 v42, v2
	v_mov_b32_e32 v43, v2
	v_mov_b32_e32 v44, v2
	v_mov_b32_e32 v45, v2
	v_mov_b32_e32 v54, v2
	v_mov_b32_e32 v55, v2
	v_mov_b32_e32 v56, v2
	v_mov_b32_e32 v57, v2
	v_mov_b32_e32 v58, v2
	v_mov_b32_e32 v59, v2
	v_mov_b32_e32 v60, v2
	v_mov_b32_e32 v61, v2
	v_mov_b32_e32 v62, v2
	v_mov_b32_e32 v63, v2
	v_mov_b32_e32 v64, v2
	v_mov_b32_e32 v65, v2
	v_mov_b32_e32 v66, v2
	v_mov_b32_e32 v67, v2
	v_mov_b32_e32 v68, v2
	v_mov_b32_e32 v69, v2
	v_mov_b32_e32 v70, v2
	v_mov_b32_e32 v71, v2
	v_mov_b32_e32 v72, v2
	v_mov_b32_e32 v73, v2
	v_mov_b32_e32 v78, v2
	v_mov_b32_e32 v79, v2
	v_mov_b32_e32 v80, v2
	v_mov_b32_e32 v81, v2
	v_mov_b32_e32 v82, v2
	v_mov_b32_e32 v83, v2
	v_mov_b32_e32 v84, v2
	v_mov_b32_e32 v85, v2
	v_mov_b32_e32 v94, v2
	v_mov_b32_e32 v95, v2
	v_mov_b32_e32 v96, v2
	v_mov_b32_e32 v97, v2
	v_mov_b32_e32 v98, v2
	v_mov_b32_e32 v99, v2
	v_mov_b32_e32 v100, v2
	v_mov_b32_e32 v101, v2
	v_mov_b32_e32 v110, v2
	v_mov_b32_e32 v111, v2
	v_mov_b32_e32 v112, v2
	v_mov_b32_e32 v113, v2
	v_mov_b32_e32 v114, v2
	v_mov_b32_e32 v115, v2
	v_mov_b32_e32 v116, v2
	v_mov_b32_e32 v117, v2
	v_mov_b32_e32 v74, v2
	v_mov_b32_e32 v75, v2
	v_mov_b32_e32 v76, v2
	v_mov_b32_e32 v77, v2
	v_mov_b32_e32 v86, v2
	v_mov_b32_e32 v87, v2
	v_mov_b32_e32 v88, v2
	v_mov_b32_e32 v89, v2
	v_mov_b32_e32 v90, v2
	v_mov_b32_e32 v91, v2
	v_mov_b32_e32 v92, v2
	v_mov_b32_e32 v93, v2
	v_mov_b32_e32 v102, v2
	v_mov_b32_e32 v103, v2
	v_mov_b32_e32 v104, v2
	v_mov_b32_e32 v105, v2
	v_mov_b32_e32 v106, v2
	v_mov_b32_e32 v107, v2
	v_mov_b32_e32 v108, v2
	v_mov_b32_e32 v109, v2
	v_mov_b32_e32 v118, v2
	v_mov_b32_e32 v119, v2
	v_mov_b32_e32 v120, v2
	v_mov_b32_e32 v121, v2
	v_mov_b32_e32 v122, v2
	v_mov_b32_e32 v123, v2
	v_mov_b32_e32 v124, v2
	v_mov_b32_e32 v125, v2
	v_mov_b32_e32 v126, v2
	v_mov_b32_e32 v127, v2
	v_mov_b32_e32 v128, v2
	v_mov_b32_e32 v129, v2
	v_readlane_b32 s101, v254, 14
	s_bitcmp1_b32 s101, 0
	s_cbranch_scc0 .Lprio_skip2
	s_setprio 1

; #define PG8_STAGE(bufoff, gbase, voff) do { _Pragma("unroll") for (int _i = 0; _i < 2; ++_i) \
;         __builtin_amdgcn_global_load_lds((const unsigned*)((const char*)(gbase) + (voff)[_i]), (PG8_LAS unsigned*)(lds + (bufoff) + ldsw + _i * 8192), 16, 0, 0); } while (0)
; #define PG8_LDA(dst, b, h) do { _Pragma("unroll") for (int m = 0; m < 4; ++m) _Pragma("unroll") for (int k = 0; k < 2; ++k) dst[m][k] = *(const PG8_LAS bf16x8*)(lds + PG8_SA(b, h) + aoff + m * 2048 + k * 1024); } while (0)
; #define PG8_LDB(dst, b, h) do { _Pragma("unroll") for (int n = 0; n < 2; ++n) _Pragma("unroll") for (int k = 0; k < 2; ++k) dst[n][k] = *(const PG8_LAS bf16x8*)(lds + PG8_SB(b, h) + boff + n * 2048 + k * 1024); } while (0)
; #define PG8_MMA(ai, bj, At, Bt) do { __builtin_amdgcn_s_setprio(1); _Pragma("unroll") for (int m = 0; m < 4; ++m) _Pragma("unroll") for (int n = 0; n < 2; ++n) _Pragma("unroll") for (int k = 0; k < 2; ++k) \
;         acc[ai][bj][m][n] = __builtin_amdgcn_mfma_f32_16x16x32_bf16(Bt[n][k], At[m][k], acc[ai][bj][m][n], 0, 0, 0); __builtin_amdgcn_s_setprio(0); } while (0)
; #define PG8_WAIT_V(n) asm volatile("s_waitcnt vmcnt(" #n ")" ::: "memory")
; #define PG8_WAIT_L(n) asm volatile("s_waitcnt lgkmcnt(" #n ")" ::: "memory")
; #define PG8_BAR __builtin_amdgcn_s_barrier()
; #define PG8_SCHED __builtin_amdgcn_sched_barrier(0)
; template <class Epi, class Sched>
; __device__ __forceinline__ void gemm_phase(PG8_LAS unsigned char* lds, const Gemm g, const Sched& S, const Epi& E, const int tid) {
;     ...
;             PG8_LDB(B0, 0, 0); PG8_SCHED; PG8_LDA(At, 0, 0); PG8_STAGE(PG8_SA(1, 1), a1 + hstep, voffA);
;             PG8_WAIT_L(8); PG8_BAR; PG8_WAIT_L(0); PG8_MMA(0, 0, At, B0); PG8_BAR; PG8_SCHED;
;             PG8_LDB(B1, 0, 1); PG8_STAGE(PG8_SB(0, 0), b2, voffB);
;             PG8_BAR; PG8_WAIT_L(0); PG8_MMA(0, 1, At, B1); PG8_BAR;
;             PG8_LDA(At, 0, 1); PG8_STAGE(PG8_SA(0, 0), a2, voffA);
;             PG8_BAR; PG8_WAIT_L(0); PG8_MMA(1, 0, At, B0); PG8_BAR; PG8_SCHED;
;             PG8_STAGE(PG8_SB(0, 1), b2 + hstep, voffB);
;             PG8_WAIT_V(6); PG8_BAR; PG8_MMA(1, 1, At, B1); PG8_BAR;
.LBB0_475:
	s_add_i32 s94, s56, 2
	s_add_u32 s72, s68, 0x80
	s_addc_u32 s57, s69, 0
	s_add_i32 s95, 0, 0x10000
	v_add_u32_e32 v148, s95, v157
	ds_read_b128 v[130:133], v148
	ds_read_b128 v[134:137], v148 offset:1024
	ds_read_b128 v[138:141], v148 offset:2048
	ds_read_b128 v[148:151], v148 offset:3072
	s_cmp_eq_u32 s63, s56
	s_cselect_b32 s56, s4, s72
	s_cselect_b32 s57, s5, s57
	s_cselect_b32 s73, s7, s91
	s_cselect_b32 s72, s6, s90
	v_lshl_add_u64 v[188:189], s[68:69], 0, v[144:145]
	s_add_i32 m0, s0, 0xc000
	ds_read_b128 v[152:155], v159
	ds_read_b128 v[160:163], v159 offset:1024
	ds_read_b128 v[164:167], v159 offset:2048
	ds_read_b128 v[168:171], v159 offset:3072
	ds_read_b128 v[172:175], v159 offset:4096
	ds_read_b128 v[176:179], v159 offset:5120
	ds_read_b128 v[180:183], v159 offset:6144
	ds_read_b128 v[184:187], v159 offset:7168
	global_load_lds_dwordx4 v[188:189], off
	v_lshl_add_u64 v[188:189], s[68:69], 0, v[146:147]
	s_add_i32 m0, s0, 0xe000
	s_nop 0
	global_load_lds_dwordx4 v[188:189], off
	s_waitcnt lgkmcnt(8)
	s_barrier
	s_waitcnt lgkmcnt(0)
	s_waitcnt lgkmcnt(0)
	v_mfma_f32_16x16x32_bf16 v[126:129], v[130:133], v[152:155], v[126:129]
	v_mfma_f32_16x16x32_bf16 v[122:125], v[138:141], v[152:155], v[122:125]
	v_mfma_f32_16x16x32_bf16 v[118:121], v[130:133], v[164:167], v[118:121]
	v_mfma_f32_16x16x32_bf16 v[106:109], v[138:141], v[164:167], v[106:109]
	v_mfma_f32_16x16x32_bf16 v[102:105], v[130:133], v[172:175], v[102:105]
	v_mfma_f32_16x16x32_bf16 v[90:93], v[138:141], v[172:175], v[90:93]
	v_mfma_f32_16x16x32_bf16 v[86:89], v[130:133], v[180:183], v[86:89]
	v_mfma_f32_16x16x32_bf16 v[74:77], v[138:141], v[180:183], v[74:77]
	v_mfma_f32_16x16x32_bf16 v[126:129], v[134:137], v[160:163], v[126:129]
	v_mfma_f32_16x16x32_bf16 v[122:125], v[148:151], v[160:163], v[122:125]
	v_mfma_f32_16x16x32_bf16 v[118:121], v[134:137], v[168:171], v[118:121]
	v_mfma_f32_16x16x32_bf16 v[106:109], v[148:151], v[168:171], v[106:109]
	v_mfma_f32_16x16x32_bf16 v[102:105], v[134:137], v[176:179], v[102:105]
	v_mfma_f32_16x16x32_bf16 v[90:93], v[148:151], v[176:179], v[90:93]
	v_mfma_f32_16x16x32_bf16 v[86:89], v[134:137], v[184:187], v[86:89]
	v_mfma_f32_16x16x32_bf16 v[74:77], v[148:151], v[184:187], v[74:77]
	s_barrier
	s_add_i32 s96, 0, 0x14000
	v_add_u32_e32 v196, s96, v157
	s_add_i32 s95, s95, s45
	ds_read_b128 v[188:191], v196
	ds_read_b128 v[192:195], v196 offset:1024
	ds_read_b128 v[200:203], v196 offset:2048
	ds_read_b128 v[216:219], v196 offset:3072
	v_lshl_add_u64 v[196:197], s[72:73], 0, v[0:1]
	s_mov_b32 m0, s95
	v_lshl_add_u64 v[198:199], s[72:73], 0, v[142:143]
	global_load_lds_dwordx4 v[196:197], off
	s_add_i32 m0, s95, 0x2000
	s_nop 0
	global_load_lds_dwordx4 v[198:199], off
	s_barrier
	s_waitcnt lgkmcnt(0)
	s_waitcnt lgkmcnt(0)
	v_mfma_f32_16x16x32_bf16 v[114:117], v[188:191], v[152:155], v[114:117]
	v_mfma_f32_16x16x32_bf16 v[110:113], v[200:203], v[152:155], v[110:113]
	v_mfma_f32_16x16x32_bf16 v[98:101], v[188:191], v[164:167], v[98:101]
	v_mfma_f32_16x16x32_bf16 v[94:97], v[200:203], v[164:167], v[94:97]
	v_mfma_f32_16x16x32_bf16 v[82:85], v[188:191], v[172:175], v[82:85]
	v_mfma_f32_16x16x32_bf16 v[78:81], v[200:203], v[172:175], v[78:81]
	v_mfma_f32_16x16x32_bf16 v[70:73], v[188:191], v[180:183], v[70:73]
	v_mfma_f32_16x16x32_bf16 v[66:69], v[200:203], v[180:183], v[66:69]
	v_mfma_f32_16x16x32_bf16 v[114:117], v[192:195], v[160:163], v[114:117]
	v_mfma_f32_16x16x32_bf16 v[110:113], v[216:219], v[160:163], v[110:113]
	v_mfma_f32_16x16x32_bf16 v[98:101], v[192:195], v[168:171], v[98:101]
	v_mfma_f32_16x16x32_bf16 v[94:97], v[216:219], v[168:171], v[94:97]
	v_mfma_f32_16x16x32_bf16 v[82:85], v[192:195], v[176:179], v[82:85]
	v_mfma_f32_16x16x32_bf16 v[78:81], v[216:219], v[176:179], v[78:81]
	v_mfma_f32_16x16x32_bf16 v[70:73], v[192:195], v[184:187], v[70:73]
	v_mfma_f32_16x16x32_bf16 v[66:69], v[216:219], v[184:187], v[66:69]
	s_mov_b32 m0, s0
	v_lshl_add_u64 v[220:221], s[56:57], 0, v[0:1]
	s_barrier
	ds_read_b128 v[152:155], v159 offset:16384
	ds_read_b128 v[160:163], v159 offset:17408
	ds_read_b128 v[164:167], v159 offset:18432
	ds_read_b128 v[168:171], v159 offset:19456
	ds_read_b128 v[172:175], v159 offset:20480
	ds_read_b128 v[176:179], v159 offset:21504
	ds_read_b128 v[180:183], v159 offset:22528
	ds_read_b128 v[184:187], v159 offset:23552
	global_load_lds_dwordx4 v[220:221], off
	v_lshl_add_u64 v[222:223], s[56:57], 0, v[142:143]
	s_mov_b32 m0, s1
	s_nop 0
	global_load_lds_dwordx4 v[222:223], off
	s_barrier
	s_waitcnt lgkmcnt(0)
	s_waitcnt lgkmcnt(0)
	v_mfma_f32_16x16x32_bf16 v[62:65], v[130:133], v[152:155], v[62:65]
	v_mfma_f32_16x16x32_bf16 v[58:61], v[138:141], v[152:155], v[58:61]
	v_mfma_f32_16x16x32_bf16 v[54:57], v[130:133], v[164:167], v[54:57]
	v_mfma_f32_16x16x32_bf16 v[42:45], v[138:141], v[164:167], v[42:45]
	v_mfma_f32_16x16x32_bf16 v[38:41], v[130:133], v[172:175], v[38:41]
	v_mfma_f32_16x16x32_bf16 v[26:29], v[138:141], v[172:175], v[26:29]
	v_mfma_f32_16x16x32_bf16 v[22:25], v[130:133], v[180:183], v[22:25]
	v_mfma_f32_16x16x32_bf16 v[10:13], v[138:141], v[180:183], v[10:13]
	v_mfma_f32_16x16x32_bf16 v[62:65], v[134:137], v[160:163], v[62:65]
	v_mfma_f32_16x16x32_bf16 v[58:61], v[148:151], v[160:163], v[58:61]
	v_mfma_f32_16x16x32_bf16 v[54:57], v[134:137], v[168:171], v[54:57]
	v_mfma_f32_16x16x32_bf16 v[42:45], v[148:151], v[168:171], v[42:45]
	v_mfma_f32_16x16x32_bf16 v[38:41], v[134:137], v[176:179], v[38:41]
	v_mfma_f32_16x16x32_bf16 v[26:29], v[148:151], v[176:179], v[26:29]
	v_mfma_f32_16x16x32_bf16 v[22:25], v[134:137], v[184:187], v[22:25]
	v_mfma_f32_16x16x32_bf16 v[10:13], v[148:151], v[184:187], v[10:13]
	s_barrier
; #define PG8_STAGE(bufoff, gbase, voff) do { _Pragma("unroll") for (int _i = 0; _i < 2; ++_i) \
;         __builtin_amdgcn_global_load_lds((const unsigned*)((const char*)(gbase) + (voff)[_i]), (PG8_LAS unsigned*)(lds + (bufoff) + ldsw + _i * 8192), 16, 0, 0); } while (0)
; #define PG8_LDA(dst, b, h) do { _Pragma("unroll") for (int m = 0; m < 4; ++m) _Pragma("unroll") for (int k = 0; k < 2; ++k) dst[m][k] = *(const PG8_LAS bf16x8*)(lds + PG8_SA(b, h) + aoff + m * 2048 + k * 1024); } while (0)
; #define PG8_LDB(dst, b, h) do { _Pragma("unroll") for (int n = 0; n < 2; ++n) _Pragma("unroll") for (int k = 0; k < 2; ++k) dst[n][k] = *(const PG8_LAS bf16x8*)(lds + PG8_SB(b, h) + boff + n * 2048 + k * 1024); } while (0)
; #define PG8_MMA(ai, bj, At, Bt) do { __builtin_amdgcn_s_setprio(1); _Pragma("unroll") for (int m = 0; m < 4; ++m) _Pragma("unroll") for (int n = 0; n < 2; ++n) _Pragma("unroll") for (int k = 0; k < 2; ++k) \
;         acc[ai][bj][m][n] = __builtin_amdgcn_mfma_f32_16x16x32_bf16(Bt[n][k], At[m][k], acc[ai][bj][m][n], 0, 0, 0); __builtin_amdgcn_s_setprio(0); } while (0)
; #define PG8_WAIT_V(n) asm volatile("s_waitcnt vmcnt(" #n ")" ::: "memory")
; #define PG8_WAIT_L(n) asm volatile("s_waitcnt lgkmcnt(" #n ")" ::: "memory")
; #define PG8_BAR __builtin_amdgcn_s_barrier()
; #define PG8_SCHED __builtin_amdgcn_sched_barrier(0)
; template <class Epi, class Sched>
; __device__ __forceinline__ void gemm_phase(PG8_LAS unsigned char* lds, const Gemm g, const Sched& S, const Epi& E, const int tid) {
;     ...
;             PG8_WAIT_V(6); PG8_BAR; PG8_MMA(1, 1, At, B1); PG8_BAR;
;             PG8_LDB(B0, 1, 0); PG8_SCHED; PG8_LDA(At, 1, 0); PG8_STAGE(PG8_SA(0, 1), a2 + hstep, voffA);
;             PG8_WAIT_L(8); PG8_BAR; PG8_WAIT_L(0); PG8_MMA(0, 0, At, B0); PG8_BAR; PG8_SCHED;
;             PG8_LDB(B1, 1, 1); PG8_STAGE(PG8_SB(1, 0), b3, voffB);
;             PG8_BAR; PG8_WAIT_L(0); PG8_MMA(0, 1, At, B1); PG8_BAR;
;             PG8_LDA(At, 1, 1); PG8_STAGE(PG8_SA(1, 0), a3, voffA);
;             PG8_BAR; PG8_WAIT_L(0); PG8_MMA(1, 0, At, B0); PG8_BAR; PG8_SCHED;
	s_add_u32 s72, s72, s14
	s_addc_u32 s73, s73, s15
	s_add_i32 s95, s96, s45
	v_lshl_add_u64 v[224:225], s[72:73], 0, v[0:1]
	s_mov_b32 m0, s95
	v_lshl_add_u64 v[226:227], s[72:73], 0, v[142:143]
	global_load_lds_dwordx4 v[224:225], off
	s_add_i32 m0, s95, 0x2000
	s_nop 0
	global_load_lds_dwordx4 v[226:227], off
	s_waitcnt vmcnt(6)
	s_barrier
	v_mfma_f32_16x16x32_bf16 v[50:53], v[188:191], v[152:155], v[50:53]
	v_mfma_f32_16x16x32_bf16 v[46:49], v[200:203], v[152:155], v[46:49]
	v_mfma_f32_16x16x32_bf16 v[34:37], v[188:191], v[164:167], v[34:37]
	v_mfma_f32_16x16x32_bf16 v[30:33], v[200:203], v[164:167], v[30:33]
	v_mfma_f32_16x16x32_bf16 v[18:21], v[188:191], v[172:175], v[18:21]
	v_mfma_f32_16x16x32_bf16 v[14:17], v[200:203], v[172:175], v[14:17]
	v_mfma_f32_16x16x32_bf16 v[6:9], v[188:191], v[180:183], v[6:9]
	v_mfma_f32_16x16x32_bf16 v[2:5], v[200:203], v[180:183], v[2:5]
	v_mfma_f32_16x16x32_bf16 v[50:53], v[192:195], v[160:163], v[50:53]
	v_mfma_f32_16x16x32_bf16 v[46:49], v[216:219], v[160:163], v[46:49]
	v_mfma_f32_16x16x32_bf16 v[34:37], v[192:195], v[168:171], v[34:37]
	v_mfma_f32_16x16x32_bf16 v[30:33], v[216:219], v[168:171], v[30:33]
	v_mfma_f32_16x16x32_bf16 v[18:21], v[192:195], v[176:179], v[18:21]
	v_mfma_f32_16x16x32_bf16 v[14:17], v[216:219], v[176:179], v[14:17]
	v_mfma_f32_16x16x32_bf16 v[6:9], v[192:195], v[184:187], v[6:9]
	v_mfma_f32_16x16x32_bf16 v[2:5], v[216:219], v[184:187], v[2:5]
	s_add_i32 s72, 0, 0x18000
	v_add_u32_e32 v148, s72, v157
	s_barrier
	ds_read_b128 v[130:133], v148
	ds_read_b128 v[134:137], v148 offset:1024
	ds_read_b128 v[138:141], v148 offset:2048
	ds_read_b128 v[148:151], v148 offset:3072
	s_add_u32 s56, s56, s14
	s_addc_u32 s57, s57, s15
	s_mov_b32 m0, s12
	v_lshl_add_u64 v[188:189], s[56:57], 0, v[0:1]
	ds_read_b128 v[152:155], v159 offset:32768
	ds_read_b128 v[160:163], v159 offset:33792
	ds_read_b128 v[164:167], v159 offset:34816
	ds_read_b128 v[168:171], v159 offset:35840
	ds_read_b128 v[172:175], v159 offset:36864
	ds_read_b128 v[176:179], v159 offset:37888
	ds_read_b128 v[180:183], v159 offset:38912
	ds_read_b128 v[184:187], v159 offset:39936
	global_load_lds_dwordx4 v[188:189], off
	v_lshl_add_u64 v[188:189], s[56:57], 0, v[142:143]
	s_mov_b32 m0, s13
	s_nop 0
	global_load_lds_dwordx4 v[188:189], off
	s_waitcnt lgkmcnt(8)
	s_barrier
	s_waitcnt lgkmcnt(0)
	s_waitcnt lgkmcnt(0)
	v_mfma_f32_16x16x32_bf16 v[126:129], v[130:133], v[152:155], v[126:129]
	v_mfma_f32_16x16x32_bf16 v[122:125], v[138:141], v[152:155], v[122:125]
	v_mfma_f32_16x16x32_bf16 v[118:121], v[130:133], v[164:167], v[118:121]
	v_mfma_f32_16x16x32_bf16 v[106:109], v[138:141], v[164:167], v[106:109]
	v_mfma_f32_16x16x32_bf16 v[102:105], v[130:133], v[172:175], v[102:105]
	v_mfma_f32_16x16x32_bf16 v[90:93], v[138:141], v[172:175], v[90:93]
	v_mfma_f32_16x16x32_bf16 v[86:89], v[130:133], v[180:183], v[86:89]
	v_mfma_f32_16x16x32_bf16 v[74:77], v[138:141], v[180:183], v[74:77]
	v_mfma_f32_16x16x32_bf16 v[126:129], v[134:137], v[160:163], v[126:129]
	v_mfma_f32_16x16x32_bf16 v[122:125], v[148:151], v[160:163], v[122:125]
	v_mfma_f32_16x16x32_bf16 v[118:121], v[134:137], v[168:171], v[118:121]
	v_mfma_f32_16x16x32_bf16 v[106:109], v[148:151], v[168:171], v[106:109]
	v_mfma_f32_16x16x32_bf16 v[102:105], v[134:137], v[176:179], v[102:105]
	v_mfma_f32_16x16x32_bf16 v[90:93], v[148:151], v[176:179], v[90:93]
	v_mfma_f32_16x16x32_bf16 v[86:89], v[134:137], v[184:187], v[86:89]
	v_mfma_f32_16x16x32_bf16 v[74:77], v[148:151], v[184:187], v[74:77]
	s_barrier
	s_add_i32 s56, 0, 0x1c000
	s_add_i32 s57, s72, s45
	v_add_u32_e32 v216, s56, v157
	v_lshl_add_u64 v[196:197], v[196:197], 0, s[92:93]
	s_mov_b32 m0, s57
	ds_read_b128 v[188:191], v216
	ds_read_b128 v[192:195], v216 offset:1024
	ds_read_b128 v[200:203], v216 offset:2048
	ds_read_b128 v[216:219], v216 offset:3072
	global_load_lds_dwordx4 v[196:197], off
	v_lshl_add_u64 v[196:197], v[198:199], 0, s[92:93]
	s_add_i32 m0, s57, 0x2000
	s_nop 0
	global_load_lds_dwordx4 v[196:197], off
	s_barrier
	s_waitcnt lgkmcnt(0)
	s_waitcnt lgkmcnt(0)
	v_mfma_f32_16x16x32_bf16 v[114:117], v[188:191], v[152:155], v[114:117]
	v_mfma_f32_16x16x32_bf16 v[110:113], v[200:203], v[152:155], v[110:113]
	v_mfma_f32_16x16x32_bf16 v[98:101], v[188:191], v[164:167], v[98:101]
	v_mfma_f32_16x16x32_bf16 v[94:97], v[200:203], v[164:167], v[94:97]
	v_mfma_f32_16x16x32_bf16 v[82:85], v[188:191], v[172:175], v[82:85]
	v_mfma_f32_16x16x32_bf16 v[78:81], v[200:203], v[172:175], v[78:81]
	v_mfma_f32_16x16x32_bf16 v[70:73], v[188:191], v[180:183], v[70:73]
	v_mfma_f32_16x16x32_bf16 v[66:69], v[200:203], v[180:183], v[66:69]
	v_mfma_f32_16x16x32_bf16 v[114:117], v[192:195], v[160:163], v[114:117]
	v_mfma_f32_16x16x32_bf16 v[110:113], v[216:219], v[160:163], v[110:113]
	v_mfma_f32_16x16x32_bf16 v[98:101], v[192:195], v[168:171], v[98:101]
	v_mfma_f32_16x16x32_bf16 v[94:97], v[216:219], v[168:171], v[94:97]
	v_mfma_f32_16x16x32_bf16 v[82:85], v[192:195], v[176:179], v[82:85]
	v_mfma_f32_16x16x32_bf16 v[78:81], v[216:219], v[176:179], v[78:81]
	v_mfma_f32_16x16x32_bf16 v[70:73], v[192:195], v[184:187], v[70:73]
	v_mfma_f32_16x16x32_bf16 v[66:69], v[216:219], v[184:187], v[66:69]
	s_mov_b32 m0, s64
	v_lshl_add_u64 v[196:197], v[220:221], 0, s[92:93]
	s_barrier
	ds_read_b128 v[152:155], v159 offset:49152
	ds_read_b128 v[160:163], v159 offset:50176
	ds_read_b128 v[164:167], v159 offset:51200
	ds_read_b128 v[168:171], v159 offset:52224
	ds_read_b128 v[172:175], v159 offset:53248
	ds_read_b128 v[176:179], v159 offset:54272
	ds_read_b128 v[180:183], v159 offset:55296
	ds_read_b128 v[184:187], v159 offset:56320
	global_load_lds_dwordx4 v[196:197], off
	v_lshl_add_u64 v[196:197], v[222:223], 0, s[92:93]
	s_mov_b32 m0, s65
	s_nop 0
	global_load_lds_dwordx4 v[196:197], off
	s_barrier
; #define PG8_STAGE(bufoff, gbase, voff) do { _Pragma("unroll") for (int _i = 0; _i < 2; ++_i) \
;         __builtin_amdgcn_global_load_lds((const unsigned*)((const char*)(gbase) + (voff)[_i]), (PG8_LAS unsigned*)(lds + (bufoff) + ldsw + _i * 8192), 16, 0, 0); } while (0)
; #define PG8_MMA(ai, bj, At, Bt) do { __builtin_amdgcn_s_setprio(1); _Pragma("unroll") for (int m = 0; m < 4; ++m) _Pragma("unroll") for (int n = 0; n < 2; ++n) _Pragma("unroll") for (int k = 0; k < 2; ++k) \
;         acc[ai][bj][m][n] = __builtin_amdgcn_mfma_f32_16x16x32_bf16(Bt[n][k], At[m][k], acc[ai][bj][m][n], 0, 0, 0); __builtin_amdgcn_s_setprio(0); } while (0)
; #define PG8_WAIT_V(n) asm volatile("s_waitcnt vmcnt(" #n ")" ::: "memory")
; #define PG8_WAIT_L(n) asm volatile("s_waitcnt lgkmcnt(" #n ")" ::: "memory")
; #define PG8_BAR __builtin_amdgcn_s_barrier()
; #define PG8_SCHED __builtin_amdgcn_sched_barrier(0)
; template <class Epi, class Sched>
; __device__ __forceinline__ void gemm_phase(PG8_LAS unsigned char* lds, const Gemm g, const Sched& S, const Epi& E, const int tid) {
;     ...
;             PG8_BAR; PG8_WAIT_L(0); PG8_MMA(1, 0, At, B0); PG8_BAR; PG8_SCHED;
;             PG8_STAGE(PG8_SB(1, 1), b3 + hstep, voffB);
;             PG8_WAIT_V(6); PG8_BAR; PG8_MMA(1, 1, At, B1); PG8_BAR;
;     __device__ __forceinline__ void operator()(const f32x4 (&acc)[2][2][4][2], const Unit& u, int wr, int wc, int fr, int fq) const {
;         const int row0 = u.pm * BM + wr * 64 + fr, col0 = u.pn * BM + wc * 32 + 4 * fq;
; #pragma unroll
;         for (int ai = 0; ai < 2; ++ai) {
;             f32x4 xv[4][2][2];
; #pragma unroll
;             for (int m = 0; m < 4; ++m)
; #pragma unroll
;                 for (int bj = 0; bj < 2; ++bj)
; #pragma unroll
;                     for (int n = 0; n < 2; ++n) xv[m][bj][n] = *(const f32x4*)(X + (size_t)(row0 + ai * HALF + m * 16) * 1024 + col0 + bj * HALF + n * 16);
	s_waitcnt lgkmcnt(0)
	s_waitcnt lgkmcnt(0)
	v_mfma_f32_16x16x32_bf16 v[62:65], v[130:133], v[152:155], v[62:65]
	v_mfma_f32_16x16x32_bf16 v[58:61], v[138:141], v[152:155], v[58:61]
	v_mfma_f32_16x16x32_bf16 v[54:57], v[130:133], v[164:167], v[54:57]
	v_mfma_f32_16x16x32_bf16 v[42:45], v[138:141], v[164:167], v[42:45]
	v_mfma_f32_16x16x32_bf16 v[38:41], v[130:133], v[172:175], v[38:41]
	v_mfma_f32_16x16x32_bf16 v[26:29], v[138:141], v[172:175], v[26:29]
	v_mfma_f32_16x16x32_bf16 v[22:25], v[130:133], v[180:183], v[22:25]
	v_mfma_f32_16x16x32_bf16 v[10:13], v[138:141], v[180:183], v[10:13]
	v_mfma_f32_16x16x32_bf16 v[62:65], v[134:137], v[160:163], v[62:65]
	v_mfma_f32_16x16x32_bf16 v[58:61], v[148:151], v[160:163], v[58:61]
	v_mfma_f32_16x16x32_bf16 v[54:57], v[134:137], v[168:171], v[54:57]
	v_mfma_f32_16x16x32_bf16 v[42:45], v[148:151], v[168:171], v[42:45]
	v_mfma_f32_16x16x32_bf16 v[38:41], v[134:137], v[176:179], v[38:41]
	v_mfma_f32_16x16x32_bf16 v[26:29], v[148:151], v[176:179], v[26:29]
	v_mfma_f32_16x16x32_bf16 v[22:25], v[134:137], v[184:187], v[22:25]
	v_mfma_f32_16x16x32_bf16 v[10:13], v[148:151], v[184:187], v[10:13]
	s_barrier
	s_add_i32 s56, s56, s45
	v_lshl_add_u64 v[130:131], v[224:225], 0, s[92:93]
	s_mov_b32 m0, s56
	s_nop 0
	global_load_lds_dwordx4 v[130:131], off
	v_lshl_add_u64 v[130:131], v[226:227], 0, s[92:93]
	s_add_i32 m0, s56, 0x2000
	s_nop 0
	global_load_lds_dwordx4 v[130:131], off
	s_waitcnt vmcnt(6)
	s_barrier
	v_mfma_f32_16x16x32_bf16 v[50:53], v[188:191], v[152:155], v[50:53]
	v_mfma_f32_16x16x32_bf16 v[46:49], v[200:203], v[152:155], v[46:49]
	v_mfma_f32_16x16x32_bf16 v[34:37], v[188:191], v[164:167], v[34:37]
	v_mfma_f32_16x16x32_bf16 v[30:33], v[200:203], v[164:167], v[30:33]
	v_mfma_f32_16x16x32_bf16 v[18:21], v[188:191], v[172:175], v[18:21]
	v_mfma_f32_16x16x32_bf16 v[14:17], v[200:203], v[172:175], v[14:17]
	v_mfma_f32_16x16x32_bf16 v[6:9], v[188:191], v[180:183], v[6:9]
	v_mfma_f32_16x16x32_bf16 v[2:5], v[200:203], v[180:183], v[2:5]
	v_mfma_f32_16x16x32_bf16 v[50:53], v[192:195], v[160:163], v[50:53]
	v_mfma_f32_16x16x32_bf16 v[46:49], v[216:219], v[160:163], v[46:49]
	v_mfma_f32_16x16x32_bf16 v[34:37], v[192:195], v[168:171], v[34:37]
	v_mfma_f32_16x16x32_bf16 v[30:33], v[216:219], v[168:171], v[30:33]
	v_mfma_f32_16x16x32_bf16 v[18:21], v[192:195], v[176:179], v[18:21]
	v_mfma_f32_16x16x32_bf16 v[14:17], v[216:219], v[176:179], v[14:17]
	v_mfma_f32_16x16x32_bf16 v[6:9], v[192:195], v[184:187], v[6:9]
	v_mfma_f32_16x16x32_bf16 v[2:5], v[216:219], v[184:187], v[2:5]
	s_add_u32 s68, s68, 0x100
	s_addc_u32 s69, s69, 0
	s_add_u32 s90, s90, 0x100
	s_addc_u32 s91, s91, 0
	s_cmp_ge_u32 s94, s62
	s_mov_b32 s56, s94
	s_barrier
	s_cbranch_scc0 .LBB0_475
	v_and_b32_e32 v130, 8, v156
	v_sub_u32_e32 v131, v156, v130
	v_lshl_add_u32 v131, s89, 8, v131
	v_lshl_add_u32 v130, v130, 1, v158
	v_lshl_add_u32 v130, s88, 8, v130
	v_lshlrev_b32_e32 v130, 2, v130
	v_lshl_add_u32 v130, v131, 12, v130
	v_mov_b32_e32 v131, 0
	s_mov_b64 s[56:57], 0x8000
	s_mov_b64 s[98:99], 0x80000
	s_sub_u32 s100, s24, s54
	s_subb_u32 s101, s25, s55
	v_lshl_add_u64 v[132:133], v[130:131], 0, s[54:55]
	v_lshl_add_u64 v[134:135], v[132:133], 0, s[56:57]
	global_load_dwordx4 v[160:163], v[132:133], off
	global_load_dwordx4 v[164:167], v[134:135], off
	global_load_dwordx4 v[168:171], v[132:133], off offset:512
	global_load_dwordx4 v[172:175], v[134:135], off offset:512
	v_lshl_add_u64 v[136:137], v[134:135], 0, s[56:57]
	v_lshl_add_u64 v[138:139], v[136:137], 0, s[56:57]
	global_load_dwordx4 v[176:179], v[136:137], off
	global_load_dwordx4 v[180:183], v[138:139], off
	global_load_dwordx4 v[184:187], v[136:137], off offset:512
	global_load_dwordx4 v[188:191], v[138:139], off offset:512
	v_lshl_add_u64 v[140:141], v[138:139], 0, s[56:57]
	v_lshl_add_u64 v[148:149], v[140:141], 0, s[56:57]
	global_load_dwordx4 v[192:195], v[140:141], off
	global_load_dwordx4 v[196:199], v[148:149], off
	global_load_dwordx4 v[200:203], v[140:141], off offset:512
	global_load_dwordx4 v[216:219], v[148:149], off offset:512
	v_lshl_add_u64 v[150:151], v[148:149], 0, s[56:57]
	v_lshl_add_u64 v[152:153], v[150:151], 0, s[56:57]
	global_load_dwordx4 v[220:223], v[150:151], off
	global_load_dwordx4 v[224:227], v[152:153], off
	global_load_dwordx4 v[228:231], v[150:151], off offset:512
	global_load_dwordx4 v[232:235], v[152:153], off offset:512
	s_and_b64 vcc, exec, s[2:3]
	s_mov_b32 s88, s77
	s_mov_b32 s89, s84
	s_mov_b64 s[72:73], s[6:7]
	s_mov_b64 s[68:69], s[4:5]
	v_mov_b32_dpp v236, v122 row_ror:8 row_mask:0xf bank_mask:0xf
	v_mov_b32_dpp v237, v123 row_ror:8 row_mask:0xf bank_mask:0xf
	v_mov_b32_dpp v238, v124 row_ror:8 row_mask:0xf bank_mask:0xf
	v_mov_b32_dpp v239, v125 row_ror:8 row_mask:0xf bank_mask:0xf
	v_mov_b32_dpp v122, v126 row_ror:8 row_mask:0xf bank_mask:0x3
	v_mov_b32_dpp v123, v127 row_ror:8 row_mask:0xf bank_mask:0x3
	v_mov_b32_dpp v124, v128 row_ror:8 row_mask:0xf bank_mask:0x3
	v_mov_b32_dpp v125, v129 row_ror:8 row_mask:0xf bank_mask:0x3
	v_mov_b32_dpp v126, v236 quad_perm:[0,1,2,3] row_mask:0xf bank_mask:0xc
	v_mov_b32_dpp v127, v237 quad_perm:[0,1,2,3] row_mask:0xf bank_mask:0xc
	v_mov_b32_dpp v128, v238 quad_perm:[0,1,2,3] row_mask:0xf bank_mask:0xc
	v_mov_b32_dpp v129, v239 quad_perm:[0,1,2,3] row_mask:0xf bank_mask:0xc
	v_mov_b32_dpp v236, v110 row_ror:8 row_mask:0xf bank_mask:0xf
	v_mov_b32_dpp v237, v111 row_ror:8 row_mask:0xf bank_mask:0xf
	v_mov_b32_dpp v238, v112 row_ror:8 row_mask:0xf bank_mask:0xf
	v_mov_b32_dpp v239, v113 row_ror:8 row_mask:0xf bank_mask:0xf
	v_mov_b32_dpp v110, v114 row_ror:8 row_mask:0xf bank_mask:0x3
;     __device__ __forceinline__ void operator()(const f32x4 (&acc)[2][2][4][2], const Unit& u, int wr, int wc, int fr, int fq) const {
;     ...
;                     for (int n = 0; n < 2; ++n) xv[m][bj][n] = *(const f32x4*)(X + (size_t)(row0 + ai * HALF + m * 16) * 1024 + col0 + bj * HALF + n * 16);
; #pragma unroll
;             for (int m = 0; m < 4; ++m)
; #pragma unroll
;                 for (int bj = 0; bj < 2; ++bj)
; #pragma unroll
;                     for (int n = 0; n < 2; ++n) *(f32x4*)(C + (size_t)(row0 + ai * HALF + m * 16) * 1024 + col0 + bj * HALF + n * 16) = xv[m][bj][n] + acc[ai][bj][m][n];
	v_mov_b32_dpp v111, v115 row_ror:8 row_mask:0xf bank_mask:0x3
	v_mov_b32_dpp v112, v116 row_ror:8 row_mask:0xf bank_mask:0x3
	v_mov_b32_dpp v113, v117 row_ror:8 row_mask:0xf bank_mask:0x3
	v_mov_b32_dpp v114, v236 quad_perm:[0,1,2,3] row_mask:0xf bank_mask:0xc
	v_mov_b32_dpp v115, v237 quad_perm:[0,1,2,3] row_mask:0xf bank_mask:0xc
	v_mov_b32_dpp v116, v238 quad_perm:[0,1,2,3] row_mask:0xf bank_mask:0xc
	v_mov_b32_dpp v117, v239 quad_perm:[0,1,2,3] row_mask:0xf bank_mask:0xc
	v_mov_b32_dpp v236, v106 row_ror:8 row_mask:0xf bank_mask:0xf
	v_mov_b32_dpp v237, v107 row_ror:8 row_mask:0xf bank_mask:0xf
	v_mov_b32_dpp v238, v108 row_ror:8 row_mask:0xf bank_mask:0xf
	v_mov_b32_dpp v239, v109 row_ror:8 row_mask:0xf bank_mask:0xf
	v_mov_b32_dpp v106, v118 row_ror:8 row_mask:0xf bank_mask:0x3
	v_mov_b32_dpp v107, v119 row_ror:8 row_mask:0xf bank_mask:0x3
	v_mov_b32_dpp v108, v120 row_ror:8 row_mask:0xf bank_mask:0x3
	v_mov_b32_dpp v109, v121 row_ror:8 row_mask:0xf bank_mask:0x3
	v_mov_b32_dpp v118, v236 quad_perm:[0,1,2,3] row_mask:0xf bank_mask:0xc
	v_mov_b32_dpp v119, v237 quad_perm:[0,1,2,3] row_mask:0xf bank_mask:0xc
	v_mov_b32_dpp v120, v238 quad_perm:[0,1,2,3] row_mask:0xf bank_mask:0xc
	v_mov_b32_dpp v121, v239 quad_perm:[0,1,2,3] row_mask:0xf bank_mask:0xc
	v_mov_b32_dpp v236, v94 row_ror:8 row_mask:0xf bank_mask:0xf
	v_mov_b32_dpp v237, v95 row_ror:8 row_mask:0xf bank_mask:0xf
	v_mov_b32_dpp v238, v96 row_ror:8 row_mask:0xf bank_mask:0xf
	v_mov_b32_dpp v239, v97 row_ror:8 row_mask:0xf bank_mask:0xf
	v_mov_b32_dpp v94, v98 row_ror:8 row_mask:0xf bank_mask:0x3
	v_mov_b32_dpp v95, v99 row_ror:8 row_mask:0xf bank_mask:0x3
	v_mov_b32_dpp v96, v100 row_ror:8 row_mask:0xf bank_mask:0x3
	v_mov_b32_dpp v97, v101 row_ror:8 row_mask:0xf bank_mask:0x3
	v_mov_b32_dpp v98, v236 quad_perm:[0,1,2,3] row_mask:0xf bank_mask:0xc
	v_mov_b32_dpp v99, v237 quad_perm:[0,1,2,3] row_mask:0xf bank_mask:0xc
	v_mov_b32_dpp v100, v238 quad_perm:[0,1,2,3] row_mask:0xf bank_mask:0xc
	v_mov_b32_dpp v101, v239 quad_perm:[0,1,2,3] row_mask:0xf bank_mask:0xc
	v_mov_b32_dpp v236, v90 row_ror:8 row_mask:0xf bank_mask:0xf
	v_mov_b32_dpp v237, v91 row_ror:8 row_mask:0xf bank_mask:0xf
	v_mov_b32_dpp v238, v92 row_ror:8 row_mask:0xf bank_mask:0xf
	v_mov_b32_dpp v239, v93 row_ror:8 row_mask:0xf bank_mask:0xf
	v_mov_b32_dpp v90, v102 row_ror:8 row_mask:0xf bank_mask:0x3
	v_mov_b32_dpp v91, v103 row_ror:8 row_mask:0xf bank_mask:0x3
	v_mov_b32_dpp v92, v104 row_ror:8 row_mask:0xf bank_mask:0x3
	v_mov_b32_dpp v93, v105 row_ror:8 row_mask:0xf bank_mask:0x3
	v_mov_b32_dpp v102, v236 quad_perm:[0,1,2,3] row_mask:0xf bank_mask:0xc
	v_mov_b32_dpp v103, v237 quad_perm:[0,1,2,3] row_mask:0xf bank_mask:0xc
	v_mov_b32_dpp v104, v238 quad_perm:[0,1,2,3] row_mask:0xf bank_mask:0xc
	v_mov_b32_dpp v105, v239 quad_perm:[0,1,2,3] row_mask:0xf bank_mask:0xc
	v_mov_b32_dpp v236, v78 row_ror:8 row_mask:0xf bank_mask:0xf
	v_mov_b32_dpp v237, v79 row_ror:8 row_mask:0xf bank_mask:0xf
	v_mov_b32_dpp v238, v80 row_ror:8 row_mask:0xf bank_mask:0xf
	v_mov_b32_dpp v239, v81 row_ror:8 row_mask:0xf bank_mask:0xf
	v_mov_b32_dpp v78, v82 row_ror:8 row_mask:0xf bank_mask:0x3
	v_mov_b32_dpp v79, v83 row_ror:8 row_mask:0xf bank_mask:0x3
	v_mov_b32_dpp v80, v84 row_ror:8 row_mask:0xf bank_mask:0x3
	v_mov_b32_dpp v81, v85 row_ror:8 row_mask:0xf bank_mask:0x3
	v_mov_b32_dpp v82, v236 quad_perm:[0,1,2,3] row_mask:0xf bank_mask:0xc
	v_mov_b32_dpp v83, v237 quad_perm:[0,1,2,3] row_mask:0xf bank_mask:0xc
	v_mov_b32_dpp v84, v238 quad_perm:[0,1,2,3] row_mask:0xf bank_mask:0xc
	v_mov_b32_dpp v85, v239 quad_perm:[0,1,2,3] row_mask:0xf bank_mask:0xc
	v_mov_b32_dpp v236, v74 row_ror:8 row_mask:0xf bank_mask:0xf
	v_mov_b32_dpp v237, v75 row_ror:8 row_mask:0xf bank_mask:0xf
	v_mov_b32_dpp v238, v76 row_ror:8 row_mask:0xf bank_mask:0xf
	v_mov_b32_dpp v239, v77 row_ror:8 row_mask:0xf bank_mask:0xf
	v_mov_b32_dpp v74, v86 row_ror:8 row_mask:0xf bank_mask:0x3
	v_mov_b32_dpp v75, v87 row_ror:8 row_mask:0xf bank_mask:0x3
	v_mov_b32_dpp v76, v88 row_ror:8 row_mask:0xf bank_mask:0x3
	v_mov_b32_dpp v77, v89 row_ror:8 row_mask:0xf bank_mask:0x3
	v_mov_b32_dpp v86, v236 quad_perm:[0,1,2,3] row_mask:0xf bank_mask:0xc
	v_mov_b32_dpp v87, v237 quad_perm:[0,1,2,3] row_mask:0xf bank_mask:0xc
	v_mov_b32_dpp v88, v238 quad_perm:[0,1,2,3] row_mask:0xf bank_mask:0xc
	v_mov_b32_dpp v89, v239 quad_perm:[0,1,2,3] row_mask:0xf bank_mask:0xc
	v_mov_b32_dpp v236, v66 row_ror:8 row_mask:0xf bank_mask:0xf
	v_mov_b32_dpp v237, v67 row_ror:8 row_mask:0xf bank_mask:0xf
	v_mov_b32_dpp v238, v68 row_ror:8 row_mask:0xf bank_mask:0xf
	v_mov_b32_dpp v239, v69 row_ror:8 row_mask:0xf bank_mask:0xf
	v_mov_b32_dpp v66, v70 row_ror:8 row_mask:0xf bank_mask:0x3
	v_mov_b32_dpp v67, v71 row_ror:8 row_mask:0xf bank_mask:0x3
	v_mov_b32_dpp v68, v72 row_ror:8 row_mask:0xf bank_mask:0x3
	v_mov_b32_dpp v69, v73 row_ror:8 row_mask:0xf bank_mask:0x3
	v_mov_b32_dpp v70, v236 quad_perm:[0,1,2,3] row_mask:0xf bank_mask:0xc
	v_mov_b32_dpp v71, v237 quad_perm:[0,1,2,3] row_mask:0xf bank_mask:0xc
	v_mov_b32_dpp v72, v238 quad_perm:[0,1,2,3] row_mask:0xf bank_mask:0xc
	v_mov_b32_dpp v73, v239 quad_perm:[0,1,2,3] row_mask:0xf bank_mask:0xc
	v_mov_b32_dpp v236, v58 row_ror:8 row_mask:0xf bank_mask:0xf
	v_mov_b32_dpp v237, v59 row_ror:8 row_mask:0xf bank_mask:0xf
	v_mov_b32_dpp v238, v60 row_ror:8 row_mask:0xf bank_mask:0xf
	v_mov_b32_dpp v239, v61 row_ror:8 row_mask:0xf bank_mask:0xf
	v_mov_b32_dpp v58, v62 row_ror:8 row_mask:0xf bank_mask:0x3
	v_mov_b32_dpp v59, v63 row_ror:8 row_mask:0xf bank_mask:0x3
	v_mov_b32_dpp v60, v64 row_ror:8 row_mask:0xf bank_mask:0x3
;     __device__ __forceinline__ void operator()(const f32x4 (&acc)[2][2][4][2], const Unit& u, int wr, int wc, int fr, int fq) const {
;     ...
;                     for (int n = 0; n < 2; ++n) xv[m][bj][n] = *(const f32x4*)(X + (size_t)(row0 + ai * HALF + m * 16) * 1024 + col0 + bj * HALF + n * 16);
; #pragma unroll
;             for (int m = 0; m < 4; ++m)
; #pragma unroll
;                 for (int bj = 0; bj < 2; ++bj)
; #pragma unroll
;                     for (int n = 0; n < 2; ++n) *(f32x4*)(C + (size_t)(row0 + ai * HALF + m * 16) * 1024 + col0 + bj * HALF + n * 16) = xv[m][bj][n] + acc[ai][bj][m][n];
	v_mov_b32_dpp v61, v65 row_ror:8 row_mask:0xf bank_mask:0x3
	v_mov_b32_dpp v62, v236 quad_perm:[0,1,2,3] row_mask:0xf bank_mask:0xc
	v_mov_b32_dpp v63, v237 quad_perm:[0,1,2,3] row_mask:0xf bank_mask:0xc
	v_mov_b32_dpp v64, v238 quad_perm:[0,1,2,3] row_mask:0xf bank_mask:0xc
	v_mov_b32_dpp v65, v239 quad_perm:[0,1,2,3] row_mask:0xf bank_mask:0xc
	v_mov_b32_dpp v236, v46 row_ror:8 row_mask:0xf bank_mask:0xf
	v_mov_b32_dpp v237, v47 row_ror:8 row_mask:0xf bank_mask:0xf
	v_mov_b32_dpp v238, v48 row_ror:8 row_mask:0xf bank_mask:0xf
	v_mov_b32_dpp v239, v49 row_ror:8 row_mask:0xf bank_mask:0xf
	v_mov_b32_dpp v46, v50 row_ror:8 row_mask:0xf bank_mask:0x3
	v_mov_b32_dpp v47, v51 row_ror:8 row_mask:0xf bank_mask:0x3
	v_mov_b32_dpp v48, v52 row_ror:8 row_mask:0xf bank_mask:0x3
	v_mov_b32_dpp v49, v53 row_ror:8 row_mask:0xf bank_mask:0x3
	v_mov_b32_dpp v50, v236 quad_perm:[0,1,2,3] row_mask:0xf bank_mask:0xc
	v_mov_b32_dpp v51, v237 quad_perm:[0,1,2,3] row_mask:0xf bank_mask:0xc
	v_mov_b32_dpp v52, v238 quad_perm:[0,1,2,3] row_mask:0xf bank_mask:0xc
	v_mov_b32_dpp v53, v239 quad_perm:[0,1,2,3] row_mask:0xf bank_mask:0xc
	v_mov_b32_dpp v236, v42 row_ror:8 row_mask:0xf bank_mask:0xf
	v_mov_b32_dpp v237, v43 row_ror:8 row_mask:0xf bank_mask:0xf
	v_mov_b32_dpp v238, v44 row_ror:8 row_mask:0xf bank_mask:0xf
	v_mov_b32_dpp v239, v45 row_ror:8 row_mask:0xf bank_mask:0xf
	v_mov_b32_dpp v42, v54 row_ror:8 row_mask:0xf bank_mask:0x3
	v_mov_b32_dpp v43, v55 row_ror:8 row_mask:0xf bank_mask:0x3
	v_mov_b32_dpp v44, v56 row_ror:8 row_mask:0xf bank_mask:0x3
	v_mov_b32_dpp v45, v57 row_ror:8 row_mask:0xf bank_mask:0x3
	v_mov_b32_dpp v54, v236 quad_perm:[0,1,2,3] row_mask:0xf bank_mask:0xc
	v_mov_b32_dpp v55, v237 quad_perm:[0,1,2,3] row_mask:0xf bank_mask:0xc
	v_mov_b32_dpp v56, v238 quad_perm:[0,1,2,3] row_mask:0xf bank_mask:0xc
	v_mov_b32_dpp v57, v239 quad_perm:[0,1,2,3] row_mask:0xf bank_mask:0xc
	v_mov_b32_dpp v236, v30 row_ror:8 row_mask:0xf bank_mask:0xf
	v_mov_b32_dpp v237, v31 row_ror:8 row_mask:0xf bank_mask:0xf
	v_mov_b32_dpp v238, v32 row_ror:8 row_mask:0xf bank_mask:0xf
	v_mov_b32_dpp v239, v33 row_ror:8 row_mask:0xf bank_mask:0xf
	v_mov_b32_dpp v30, v34 row_ror:8 row_mask:0xf bank_mask:0x3
	v_mov_b32_dpp v31, v35 row_ror:8 row_mask:0xf bank_mask:0x3
	v_mov_b32_dpp v32, v36 row_ror:8 row_mask:0xf bank_mask:0x3
	v_mov_b32_dpp v33, v37 row_ror:8 row_mask:0xf bank_mask:0x3
	v_mov_b32_dpp v34, v236 quad_perm:[0,1,2,3] row_mask:0xf bank_mask:0xc
	v_mov_b32_dpp v35, v237 quad_perm:[0,1,2,3] row_mask:0xf bank_mask:0xc
	v_mov_b32_dpp v36, v238 quad_perm:[0,1,2,3] row_mask:0xf bank_mask:0xc
	v_mov_b32_dpp v37, v239 quad_perm:[0,1,2,3] row_mask:0xf bank_mask:0xc
	v_mov_b32_dpp v236, v26 row_ror:8 row_mask:0xf bank_mask:0xf
	v_mov_b32_dpp v237, v27 row_ror:8 row_mask:0xf bank_mask:0xf
	v_mov_b32_dpp v238, v28 row_ror:8 row_mask:0xf bank_mask:0xf
	v_mov_b32_dpp v239, v29 row_ror:8 row_mask:0xf bank_mask:0xf
	v_mov_b32_dpp v26, v38 row_ror:8 row_mask:0xf bank_mask:0x3
	v_mov_b32_dpp v27, v39 row_ror:8 row_mask:0xf bank_mask:0x3
	v_mov_b32_dpp v28, v40 row_ror:8 row_mask:0xf bank_mask:0x3
	v_mov_b32_dpp v29, v41 row_ror:8 row_mask:0xf bank_mask:0x3
	v_mov_b32_dpp v38, v236 quad_perm:[0,1,2,3] row_mask:0xf bank_mask:0xc
	v_mov_b32_dpp v39, v237 quad_perm:[0,1,2,3] row_mask:0xf bank_mask:0xc
	v_mov_b32_dpp v40, v238 quad_perm:[0,1,2,3] row_mask:0xf bank_mask:0xc
	v_mov_b32_dpp v41, v239 quad_perm:[0,1,2,3] row_mask:0xf bank_mask:0xc
	v_mov_b32_dpp v236, v14 row_ror:8 row_mask:0xf bank_mask:0xf
	v_mov_b32_dpp v237, v15 row_ror:8 row_mask:0xf bank_mask:0xf
	v_mov_b32_dpp v238, v16 row_ror:8 row_mask:0xf bank_mask:0xf
	v_mov_b32_dpp v239, v17 row_ror:8 row_mask:0xf bank_mask:0xf
	v_mov_b32_dpp v14, v18 row_ror:8 row_mask:0xf bank_mask:0x3
	v_mov_b32_dpp v15, v19 row_ror:8 row_mask:0xf bank_mask:0x3
	v_mov_b32_dpp v16, v20 row_ror:8 row_mask:0xf bank_mask:0x3
	v_mov_b32_dpp v17, v21 row_ror:8 row_mask:0xf bank_mask:0x3
	v_mov_b32_dpp v18, v236 quad_perm:[0,1,2,3] row_mask:0xf bank_mask:0xc
	v_mov_b32_dpp v19, v237 quad_perm:[0,1,2,3] row_mask:0xf bank_mask:0xc
	v_mov_b32_dpp v20, v238 quad_perm:[0,1,2,3] row_mask:0xf bank_mask:0xc
	v_mov_b32_dpp v21, v239 quad_perm:[0,1,2,3] row_mask:0xf bank_mask:0xc
	v_mov_b32_dpp v236, v10 row_ror:8 row_mask:0xf bank_mask:0xf
	v_mov_b32_dpp v237, v11 row_ror:8 row_mask:0xf bank_mask:0xf
	v_mov_b32_dpp v238, v12 row_ror:8 row_mask:0xf bank_mask:0xf
	v_mov_b32_dpp v239, v13 row_ror:8 row_mask:0xf bank_mask:0xf
	v_mov_b32_dpp v10, v22 row_ror:8 row_mask:0xf bank_mask:0x3
	v_mov_b32_dpp v11, v23 row_ror:8 row_mask:0xf bank_mask:0x3
	v_mov_b32_dpp v12, v24 row_ror:8 row_mask:0xf bank_mask:0x3
	v_mov_b32_dpp v13, v25 row_ror:8 row_mask:0xf bank_mask:0x3
	v_mov_b32_dpp v22, v236 quad_perm:[0,1,2,3] row_mask:0xf bank_mask:0xc
	v_mov_b32_dpp v23, v237 quad_perm:[0,1,2,3] row_mask:0xf bank_mask:0xc
	v_mov_b32_dpp v24, v238 quad_perm:[0,1,2,3] row_mask:0xf bank_mask:0xc
	v_mov_b32_dpp v25, v239 quad_perm:[0,1,2,3] row_mask:0xf bank_mask:0xc
	v_mov_b32_dpp v236, v2 row_ror:8 row_mask:0xf bank_mask:0xf
	v_mov_b32_dpp v237, v3 row_ror:8 row_mask:0xf bank_mask:0xf
	v_mov_b32_dpp v238, v4 row_ror:8 row_mask:0xf bank_mask:0xf
	v_mov_b32_dpp v239, v5 row_ror:8 row_mask:0xf bank_mask:0xf
	v_mov_b32_dpp v2, v6 row_ror:8 row_mask:0xf bank_mask:0x3
	v_mov_b32_dpp v3, v7 row_ror:8 row_mask:0xf bank_mask:0x3
	v_mov_b32_dpp v4, v8 row_ror:8 row_mask:0xf bank_mask:0x3
	v_mov_b32_dpp v5, v9 row_ror:8 row_mask:0xf bank_mask:0x3
	v_mov_b32_dpp v6, v236 quad_perm:[0,1,2,3] row_mask:0xf bank_mask:0xc
	v_mov_b32_dpp v7, v237 quad_perm:[0,1,2,3] row_mask:0xf bank_mask:0xc
	v_mov_b32_dpp v8, v238 quad_perm:[0,1,2,3] row_mask:0xf bank_mask:0xc
	v_mov_b32_dpp v9, v239 quad_perm:[0,1,2,3] row_mask:0xf bank_mask:0xc
	s_waitcnt vmcnt(12)
;     __device__ __forceinline__ void operator()(const f32x4 (&acc)[2][2][4][2], const Unit& u, int wr, int wc, int fr, int fq) const {
;     ...
;                     for (int n = 0; n < 2; ++n) xv[m][bj][n] = *(const f32x4*)(X + (size_t)(row0 + ai * HALF + m * 16) * 1024 + col0 + bj * HALF + n * 16);
; #pragma unroll
;             for (int m = 0; m < 4; ++m)
; #pragma unroll
;                 for (int bj = 0; bj < 2; ++bj)
; #pragma unroll
;                     for (int n = 0; n < 2; ++n) *(f32x4*)(C + (size_t)(row0 + ai * HALF + m * 16) * 1024 + col0 + bj * HALF + n * 16) = xv[m][bj][n] + acc[ai][bj][m][n];
	v_pk_add_f32 v[126:127], v[126:127], v[160:161]
	v_pk_add_f32 v[128:129], v[128:129], v[162:163]
	v_pk_add_f32 v[122:123], v[122:123], v[164:165]
	v_pk_add_f32 v[124:125], v[124:125], v[166:167]
	v_pk_add_f32 v[114:115], v[114:115], v[168:169]
	v_pk_add_f32 v[116:117], v[116:117], v[170:171]
	v_pk_add_f32 v[110:111], v[110:111], v[172:173]
	v_pk_add_f32 v[112:113], v[112:113], v[174:175]
	v_lshl_add_u64 v[240:241], v[132:133], 0, s[100:101]
	v_lshl_add_u64 v[246:247], v[134:135], 0, s[100:101]
	global_store_dwordx4 v[240:241], v[126:129], off
	global_store_dwordx4 v[246:247], v[122:125], off
	global_store_dwordx4 v[240:241], v[114:117], off offset:512
	global_store_dwordx4 v[246:247], v[110:113], off offset:512
	v_lshl_add_u64 v[132:133], v[132:133], 0, s[98:99]
	v_lshl_add_u64 v[134:135], v[134:135], 0, s[98:99]
	global_load_dwordx4 v[160:163], v[132:133], off
	global_load_dwordx4 v[164:167], v[134:135], off
	global_load_dwordx4 v[168:171], v[132:133], off offset:512
	global_load_dwordx4 v[172:175], v[134:135], off offset:512
	s_waitcnt vmcnt(16)
	v_pk_add_f32 v[118:119], v[118:119], v[176:177]
	v_pk_add_f32 v[120:121], v[120:121], v[178:179]
	v_pk_add_f32 v[106:107], v[106:107], v[180:181]
	v_pk_add_f32 v[108:109], v[108:109], v[182:183]
	v_pk_add_f32 v[98:99], v[98:99], v[184:185]
	v_pk_add_f32 v[100:101], v[100:101], v[186:187]
	v_pk_add_f32 v[94:95], v[94:95], v[188:189]
	v_pk_add_f32 v[96:97], v[96:97], v[190:191]
	v_lshl_add_u64 v[240:241], v[136:137], 0, s[100:101]
	v_lshl_add_u64 v[246:247], v[138:139], 0, s[100:101]
	global_store_dwordx4 v[240:241], v[118:121], off
	global_store_dwordx4 v[246:247], v[106:109], off
	global_store_dwordx4 v[240:241], v[98:101], off offset:512
	global_store_dwordx4 v[246:247], v[94:97], off offset:512
	v_lshl_add_u64 v[136:137], v[136:137], 0, s[98:99]
	v_lshl_add_u64 v[138:139], v[138:139], 0, s[98:99]
	global_load_dwordx4 v[176:179], v[136:137], off
	global_load_dwordx4 v[180:183], v[138:139], off
	global_load_dwordx4 v[184:187], v[136:137], off offset:512
	global_load_dwordx4 v[188:191], v[138:139], off offset:512
	s_waitcnt vmcnt(20)
	v_pk_add_f32 v[102:103], v[102:103], v[192:193]
	v_pk_add_f32 v[104:105], v[104:105], v[194:195]
	v_pk_add_f32 v[90:91], v[90:91], v[196:197]
	v_pk_add_f32 v[92:93], v[92:93], v[198:199]
	v_pk_add_f32 v[82:83], v[82:83], v[200:201]
	v_pk_add_f32 v[84:85], v[84:85], v[202:203]
	v_pk_add_f32 v[78:79], v[78:79], v[216:217]
	v_pk_add_f32 v[80:81], v[80:81], v[218:219]
	v_lshl_add_u64 v[240:241], v[140:141], 0, s[100:101]
	v_lshl_add_u64 v[246:247], v[148:149], 0, s[100:101]
	global_store_dwordx4 v[240:241], v[102:105], off
	global_store_dwordx4 v[246:247], v[90:93], off
	global_store_dwordx4 v[240:241], v[82:85], off offset:512
	global_store_dwordx4 v[246:247], v[78:81], off offset:512
	v_lshl_add_u64 v[140:141], v[140:141], 0, s[98:99]
	v_lshl_add_u64 v[148:149], v[148:149], 0, s[98:99]
	global_load_dwordx4 v[192:195], v[140:141], off
	global_load_dwordx4 v[196:199], v[148:149], off
	global_load_dwordx4 v[200:203], v[140:141], off offset:512
	global_load_dwordx4 v[216:219], v[148:149], off offset:512
	s_waitcnt vmcnt(24)
	v_pk_add_f32 v[86:87], v[86:87], v[220:221]
	v_pk_add_f32 v[88:89], v[88:89], v[222:223]
	v_pk_add_f32 v[74:75], v[74:75], v[224:225]
	v_pk_add_f32 v[76:77], v[76:77], v[226:227]
	v_pk_add_f32 v[70:71], v[70:71], v[228:229]
	v_pk_add_f32 v[72:73], v[72:73], v[230:231]
	v_pk_add_f32 v[66:67], v[66:67], v[232:233]
	v_pk_add_f32 v[68:69], v[68:69], v[234:235]
	v_lshl_add_u64 v[240:241], v[150:151], 0, s[100:101]
	v_lshl_add_u64 v[246:247], v[152:153], 0, s[100:101]
	global_store_dwordx4 v[240:241], v[86:89], off
	global_store_dwordx4 v[246:247], v[74:77], off
	global_store_dwordx4 v[240:241], v[70:73], off offset:512
	global_store_dwordx4 v[246:247], v[66:69], off offset:512
	v_lshl_add_u64 v[150:151], v[150:151], 0, s[98:99]
	v_lshl_add_u64 v[152:153], v[152:153], 0, s[98:99]
	global_load_dwordx4 v[220:223], v[150:151], off
	global_load_dwordx4 v[224:227], v[152:153], off
	global_load_dwordx4 v[228:231], v[150:151], off offset:512
	global_load_dwordx4 v[232:235], v[152:153], off offset:512
	s_waitcnt vmcnt(24)
	v_pk_add_f32 v[62:63], v[62:63], v[160:161]
	v_pk_add_f32 v[64:65], v[64:65], v[162:163]
	v_pk_add_f32 v[58:59], v[58:59], v[164:165]
	v_pk_add_f32 v[60:61], v[60:61], v[166:167]
	v_pk_add_f32 v[50:51], v[50:51], v[168:169]
	v_pk_add_f32 v[52:53], v[52:53], v[170:171]
	v_pk_add_f32 v[46:47], v[46:47], v[172:173]
	v_pk_add_f32 v[48:49], v[48:49], v[174:175]
	v_lshl_add_u64 v[240:241], v[132:133], 0, s[100:101]
	v_lshl_add_u64 v[246:247], v[134:135], 0, s[100:101]
	global_store_dwordx4 v[240:241], v[62:65], off
	global_store_dwordx4 v[246:247], v[58:61], off
	global_store_dwordx4 v[240:241], v[50:53], off offset:512
	global_store_dwordx4 v[246:247], v[46:49], off offset:512
	s_waitcnt vmcnt(20)
	v_pk_add_f32 v[54:55], v[54:55], v[176:177]
	v_pk_add_f32 v[56:57], v[56:57], v[178:179]
	v_pk_add_f32 v[42:43], v[42:43], v[180:181]
	v_pk_add_f32 v[44:45], v[44:45], v[182:183]
	v_pk_add_f32 v[34:35], v[34:35], v[184:185]
	v_pk_add_f32 v[36:37], v[36:37], v[186:187]
	v_pk_add_f32 v[30:31], v[30:31], v[188:189]
	v_pk_add_f32 v[32:33], v[32:33], v[190:191]
	v_lshl_add_u64 v[240:241], v[136:137], 0, s[100:101]
	v_lshl_add_u64 v[246:247], v[138:139], 0, s[100:101]
	global_store_dwordx4 v[240:241], v[54:57], off
	global_store_dwordx4 v[246:247], v[42:45], off
	global_store_dwordx4 v[240:241], v[34:37], off offset:512
	global_store_dwordx4 v[246:247], v[30:33], off offset:512
	s_waitcnt vmcnt(16)
	v_pk_add_f32 v[38:39], v[38:39], v[192:193]
	v_pk_add_f32 v[40:41], v[40:41], v[194:195]
	v_pk_add_f32 v[26:27], v[26:27], v[196:197]
	v_pk_add_f32 v[28:29], v[28:29], v[198:199]
	v_pk_add_f32 v[18:19], v[18:19], v[200:201]
	v_pk_add_f32 v[20:21], v[20:21], v[202:203]
	v_pk_add_f32 v[14:15], v[14:15], v[216:217]
	v_pk_add_f32 v[16:17], v[16:17], v[218:219]
	v_lshl_add_u64 v[240:241], v[140:141], 0, s[100:101]
	v_lshl_add_u64 v[246:247], v[148:149], 0, s[100:101]
	global_store_dwordx4 v[240:241], v[38:41], off
	global_store_dwordx4 v[246:247], v[26:29], off
	global_store_dwordx4 v[240:241], v[18:21], off offset:512
	global_store_dwordx4 v[246:247], v[14:17], off offset:512
	s_waitcnt vmcnt(12)
	v_pk_add_f32 v[22:23], v[22:23], v[220:221]
	v_pk_add_f32 v[24:25], v[24:25], v[222:223]
	v_pk_add_f32 v[10:11], v[10:11], v[224:225]
	v_pk_add_f32 v[12:13], v[12:13], v[226:227]
	v_pk_add_f32 v[6:7], v[6:7], v[228:229]
	v_pk_add_f32 v[8:9], v[8:9], v[230:231]
	v_pk_add_f32 v[2:3], v[2:3], v[232:233]
	v_pk_add_f32 v[4:5], v[4:5], v[234:235]
	v_lshl_add_u64 v[240:241], v[150:151], 0, s[100:101]
	v_lshl_add_u64 v[246:247], v[152:153], 0, s[100:101]
	global_store_dwordx4 v[240:241], v[22:25], off
	global_store_dwordx4 v[246:247], v[10:13], off
	global_store_dwordx4 v[240:241], v[6:9], off offset:512
	global_store_dwordx4 v[246:247], v[2:5], off offset:512
	s_cbranch_vccz .LBB0_464
; #define PG8_WAIT_V(n) asm volatile("s_waitcnt vmcnt(" #n ")" ::: "memory")
; #define PG8_BAR __builtin_amdgcn_s_barrier()
; template <class Epi, class Sched>
; __device__ __forceinline__ void gemm_phase(PG8_LAS unsigned char* lds, const Gemm g, const Sched& S, const Epi& E, const int tid) {
;     ...
;     PG8_WAIT_V(0);
;     if (wr == 0) PG8_BAR;
;     PG8_BAR;
	s_waitcnt vmcnt(0)
	s_cmpk_gt_u32 s34, 0xff
	s_cbranch_scc1 .LBB0_479
	s_barrier

; template <class Epi, class Sched>
; __device__ __forceinline__ void gemm_phase(PG8_LAS unsigned char* lds, const Gemm g, const Sched& S, const Epi& E, const int tid) {
;     ...
;         const bool has_next = S.next(ui + 1, nxt);
;         const char* nA = has_next ? (const char*)g.A + a_tile_row(g, nxt.pm) * (size_t)K * 2 : cA; const char* nB = has_next ? (const char*)g.Bt + (size_t)nxt.pn * tstep : cB;
;         for (int t = 0; t < nt; t += 2) {
;             const bool last = (t == nt - 2);
;             const char* a1 = cA + (size_t)(t + 1) * kstep;
;             const char* a2 = last ? nA : cA + (size_t)(t + 2) * kstep; const char* b2 = last ? nB : cB + (size_t)(t + 2) * kstep;
;     ...
; #pragma unroll
;         for (int a = 0; a < 2; ++a)
; #pragma unroll
;             for (int b = 0; b < 2; ++b)
; #pragma unroll
;                 for (int m = 0; m < 4; ++m)
; #pragma unroll
;                     for (int n = 0; n < 2; ++n) acc[a][b][m][n] = (f32x4){0.f, 0.f, 0.f, 0.f};
.LBB0_565:
	s_ashr_i32 s19, s18, 31
	s_lshl_b64 s[34:35], s[18:19], 19
	s_add_u32 s72, s45, s34
	s_addc_u32 s73, s64, s35
	s_and_b64 s[6:7], s[6:7], exec
	s_cselect_b32 s9, s73, s11
	s_cselect_b32 s19, s72, s10
	s_add_u32 s6, s76, 0x40080
	s_addc_u32 s7, s77, 0
	s_add_u32 s34, s10, 0x100
	v_mov_b32_e32 v2, 0
	s_addc_u32 s35, s11, 0
	s_mov_b32 s76, -2
	v_mov_b32_e32 v3, v2
	v_mov_b32_e32 v4, v2
	v_mov_b32_e32 v5, v2
	v_mov_b32_e32 v6, v2
	v_mov_b32_e32 v7, v2
	v_mov_b32_e32 v8, v2
	v_mov_b32_e32 v9, v2
	v_mov_b32_e32 v18, v2
	v_mov_b32_e32 v19, v2
	v_mov_b32_e32 v20, v2
	v_mov_b32_e32 v21, v2
	v_mov_b32_e32 v22, v2
	v_mov_b32_e32 v23, v2
	v_mov_b32_e32 v24, v2
	v_mov_b32_e32 v25, v2
	v_mov_b32_e32 v34, v2
	v_mov_b32_e32 v35, v2
	v_mov_b32_e32 v36, v2
	v_mov_b32_e32 v37, v2
	v_mov_b32_e32 v38, v2
	v_mov_b32_e32 v39, v2
	v_mov_b32_e32 v40, v2
	v_mov_b32_e32 v41, v2
	v_mov_b32_e32 v50, v2
	v_mov_b32_e32 v51, v2
	v_mov_b32_e32 v52, v2
	v_mov_b32_e32 v53, v2
	v_mov_b32_e32 v54, v2
	v_mov_b32_e32 v55, v2
	v_mov_b32_e32 v56, v2
	v_mov_b32_e32 v57, v2
	v_mov_b32_e32 v10, v2
	v_mov_b32_e32 v11, v2
	v_mov_b32_e32 v12, v2
	v_mov_b32_e32 v13, v2
	v_mov_b32_e32 v14, v2
	v_mov_b32_e32 v15, v2
	s_waitcnt lgkmcnt(0)
	v_mov_b32_e32 v16, v2
	v_mov_b32_e32 v17, v2
	v_mov_b32_e32 v26, v2
	v_mov_b32_e32 v27, v2
	v_mov_b32_e32 v28, v2
	v_mov_b32_e32 v29, v2
	v_mov_b32_e32 v30, v2
	v_mov_b32_e32 v31, v2
	v_mov_b32_e32 v32, v2
	v_mov_b32_e32 v33, v2
	v_mov_b32_e32 v42, v2
	v_mov_b32_e32 v43, v2
	v_mov_b32_e32 v44, v2
	v_mov_b32_e32 v45, v2
	v_mov_b32_e32 v46, v2
	v_mov_b32_e32 v47, v2
	v_mov_b32_e32 v48, v2
	v_mov_b32_e32 v49, v2
	v_mov_b32_e32 v58, v2
	v_mov_b32_e32 v59, v2
	v_mov_b32_e32 v60, v2
	v_mov_b32_e32 v61, v2
	v_mov_b32_e32 v62, v2
	v_mov_b32_e32 v63, v2
	v_mov_b32_e32 v64, v2
	v_mov_b32_e32 v65, v2
	v_mov_b32_e32 v66, v2
	v_mov_b32_e32 v67, v2
	v_mov_b32_e32 v68, v2
	v_mov_b32_e32 v69, v2
	v_mov_b32_e32 v70, v2
	v_mov_b32_e32 v71, v2
	v_mov_b32_e32 v72, v2
	v_mov_b32_e32 v73, v2
	v_mov_b32_e32 v82, v2
	v_mov_b32_e32 v83, v2
	v_mov_b32_e32 v84, v2
	v_mov_b32_e32 v85, v2
	v_mov_b32_e32 v86, v2
	v_mov_b32_e32 v87, v2
	v_mov_b32_e32 v88, v2
	v_mov_b32_e32 v89, v2
	v_mov_b32_e32 v98, v2
	v_mov_b32_e32 v99, v2
	v_mov_b32_e32 v100, v2
	v_mov_b32_e32 v101, v2
	v_mov_b32_e32 v102, v2
	v_mov_b32_e32 v103, v2
	v_mov_b32_e32 v104, v2
	v_mov_b32_e32 v105, v2
	v_mov_b32_e32 v114, v2
	v_mov_b32_e32 v115, v2
	v_mov_b32_e32 v116, v2
	v_mov_b32_e32 v117, v2
	v_mov_b32_e32 v118, v2
	v_mov_b32_e32 v119, v2
	v_mov_b32_e32 v120, v2
	v_mov_b32_e32 v121, v2
	v_mov_b32_e32 v74, v2
	v_mov_b32_e32 v75, v2
	v_mov_b32_e32 v76, v2
	v_mov_b32_e32 v77, v2
	v_mov_b32_e32 v78, v2
	v_mov_b32_e32 v79, v2
	v_mov_b32_e32 v80, v2
	v_mov_b32_e32 v81, v2
	v_mov_b32_e32 v90, v2
	v_mov_b32_e32 v91, v2
	v_mov_b32_e32 v92, v2
	v_mov_b32_e32 v93, v2
	v_mov_b32_e32 v94, v2
	v_mov_b32_e32 v95, v2
	v_mov_b32_e32 v96, v2
	v_mov_b32_e32 v97, v2
	v_mov_b32_e32 v106, v2
	v_mov_b32_e32 v107, v2
	v_mov_b32_e32 v108, v2
	v_mov_b32_e32 v109, v2
	v_mov_b32_e32 v110, v2
	v_mov_b32_e32 v111, v2
	v_mov_b32_e32 v112, v2
	v_mov_b32_e32 v113, v2
	v_mov_b32_e32 v122, v2
	v_mov_b32_e32 v123, v2
	v_mov_b32_e32 v124, v2
	v_mov_b32_e32 v125, v2
	v_mov_b32_e32 v126, v2
	v_mov_b32_e32 v127, v2
	v_mov_b32_e32 v128, v2
	v_mov_b32_e32 v129, v2
	v_readlane_b32 s101, v254, 14
	s_bitcmp1_b32 s101, 0
	s_cbranch_scc0 .Lprio_skip3
	s_setprio 1

; #define PG8_STAGE(bufoff, gbase, voff) do { _Pragma("unroll") for (int _i = 0; _i < 2; ++_i) \
;         __builtin_amdgcn_global_load_lds((const unsigned*)((const char*)(gbase) + (voff)[_i]), (PG8_LAS unsigned*)(lds + (bufoff) + ldsw + _i * 8192), 16, 0, 0); } while (0)
; #define PG8_LDA(dst, b, h) do { _Pragma("unroll") for (int m = 0; m < 4; ++m) _Pragma("unroll") for (int k = 0; k < 2; ++k) dst[m][k] = *(const PG8_LAS bf16x8*)(lds + PG8_SA(b, h) + aoff + m * 2048 + k * 1024); } while (0)
; #define PG8_LDB(dst, b, h) do { _Pragma("unroll") for (int n = 0; n < 2; ++n) _Pragma("unroll") for (int k = 0; k < 2; ++k) dst[n][k] = *(const PG8_LAS bf16x8*)(lds + PG8_SB(b, h) + boff + n * 2048 + k * 1024); } while (0)
; #define PG8_MMA(ai, bj, At, Bt) do { __builtin_amdgcn_s_setprio(1); _Pragma("unroll") for (int m = 0; m < 4; ++m) _Pragma("unroll") for (int n = 0; n < 2; ++n) _Pragma("unroll") for (int k = 0; k < 2; ++k) \
;         acc[ai][bj][m][n] = __builtin_amdgcn_mfma_f32_16x16x32_bf16(Bt[n][k], At[m][k], acc[ai][bj][m][n], 0, 0, 0); __builtin_amdgcn_s_setprio(0); } while (0)
; #define PG8_WAIT_V(n) asm volatile("s_waitcnt vmcnt(" #n ")" ::: "memory")
; #define PG8_WAIT_L(n) asm volatile("s_waitcnt lgkmcnt(" #n ")" ::: "memory")
; #define PG8_BAR __builtin_amdgcn_s_barrier()
; #define PG8_SCHED __builtin_amdgcn_sched_barrier(0)
; template <class Epi, class Sched>
; __device__ __forceinline__ void gemm_phase(PG8_LAS unsigned char* lds, const Gemm g, const Sched& S, const Epi& E, const int tid) {
;     ...
;             PG8_LDB(B0, 0, 0); PG8_SCHED; PG8_LDA(At, 0, 0); PG8_STAGE(PG8_SA(1, 1), a1 + hstep, voffA);
;             PG8_WAIT_L(8); PG8_BAR; PG8_WAIT_L(0); PG8_MMA(0, 0, At, B0); PG8_BAR; PG8_SCHED;
;             PG8_LDB(B1, 0, 1); PG8_STAGE(PG8_SB(0, 0), b2, voffB);
;             PG8_BAR; PG8_WAIT_L(0); PG8_MMA(0, 1, At, B1); PG8_BAR;
;             PG8_LDA(At, 0, 1); PG8_STAGE(PG8_SA(0, 0), a2, voffA);
;             PG8_BAR; PG8_WAIT_L(0); PG8_MMA(1, 0, At, B0); PG8_BAR; PG8_SCHED;
;             PG8_STAGE(PG8_SB(0, 1), b2 + hstep, voffB);
;             PG8_WAIT_V(6); PG8_BAR; PG8_MMA(1, 1, At, B1); PG8_BAR;
.LBB0_566:
	s_add_u32 s10, s6, 0xfffc0080
	s_addc_u32 s11, s7, -1
	s_add_i32 s77, 0, 0x10000
	v_add_u32_e32 v0, s77, v141
	ds_read_b128 v[162:165], v0
	ds_read_b128 v[168:171], v0 offset:1024
	ds_read_b128 v[172:175], v0 offset:2048
	ds_read_b128 v[176:179], v0 offset:3072
	s_cmp_eq_u32 s76, 12
	s_cselect_b32 s57, s69, s11
	s_cselect_b32 s56, s68, s10
	s_cselect_b32 s11, s9, s35
	s_cselect_b32 s10, s19, s34
	v_lshl_add_u64 v[192:193], s[6:7], 0, v[158:159]
	s_add_i32 m0, s90, 0xc000
	ds_read_b128 v[180:183], v166
	ds_read_b128 v[184:187], v166 offset:1024
	ds_read_b128 v[188:191], v166 offset:2048
	ds_read_b128 v[200:203], v166 offset:3072
	ds_read_b128 v[216:219], v166 offset:4096
	ds_read_b128 v[220:223], v166 offset:5120
	ds_read_b128 v[224:227], v166 offset:6144
	ds_read_b128 v[228:231], v166 offset:7168
	global_load_lds_dwordx4 v[192:193], off
	v_lshl_add_u64 v[192:193], s[6:7], 0, v[160:161]
	s_add_i32 m0, s90, 0xe000
	s_nop 0
	global_load_lds_dwordx4 v[192:193], off
	s_waitcnt lgkmcnt(8)
	s_barrier
	s_waitcnt lgkmcnt(0)
	s_waitcnt lgkmcnt(0)
	v_mfma_f32_16x16x32_bf16 v[126:129], v[162:165], v[180:183], v[126:129]
	v_mfma_f32_16x16x32_bf16 v[122:125], v[172:175], v[180:183], v[122:125]
	v_mfma_f32_16x16x32_bf16 v[110:113], v[162:165], v[188:191], v[110:113]
	v_mfma_f32_16x16x32_bf16 v[106:109], v[172:175], v[188:191], v[106:109]
	v_mfma_f32_16x16x32_bf16 v[94:97], v[162:165], v[216:219], v[94:97]
	v_mfma_f32_16x16x32_bf16 v[90:93], v[172:175], v[216:219], v[90:93]
	v_mfma_f32_16x16x32_bf16 v[78:81], v[162:165], v[224:227], v[78:81]
	v_mfma_f32_16x16x32_bf16 v[74:77], v[172:175], v[224:227], v[74:77]
	v_mfma_f32_16x16x32_bf16 v[126:129], v[168:171], v[184:187], v[126:129]
	v_mfma_f32_16x16x32_bf16 v[122:125], v[176:179], v[184:187], v[122:125]
	v_mfma_f32_16x16x32_bf16 v[110:113], v[168:171], v[200:203], v[110:113]
	v_mfma_f32_16x16x32_bf16 v[106:109], v[176:179], v[200:203], v[106:109]
	v_mfma_f32_16x16x32_bf16 v[94:97], v[168:171], v[220:223], v[94:97]
	v_mfma_f32_16x16x32_bf16 v[90:93], v[176:179], v[220:223], v[90:93]
	v_mfma_f32_16x16x32_bf16 v[78:81], v[168:171], v[228:231], v[78:81]
	v_mfma_f32_16x16x32_bf16 v[74:77], v[176:179], v[228:231], v[74:77]
	s_barrier
	s_add_i32 s84, 0, 0x14000
	s_add_i32 s77, s77, s65
	v_add_u32_e32 v0, s84, v141
	v_lshl_add_u64 v[240:241], s[10:11], 0, v[134:135]
	s_mov_b32 m0, s77
	ds_read_b128 v[232:235], v0
	ds_read_b128 v[236:239], v0 offset:1024
	ds_read_b128 v[246:249], v0 offset:2048
	ds_read_b128 v[192:195], v0 offset:3072
	global_load_lds_dwordx4 v[240:241], off
	v_lshl_add_u64 v[198:199], s[10:11], 0, v[130:131]
	s_add_i32 m0, s77, 0x2000
	s_nop 0
	global_load_lds_dwordx4 v[198:199], off
	s_barrier
	s_waitcnt lgkmcnt(0)
	s_waitcnt lgkmcnt(0)
	v_mfma_f32_16x16x32_bf16 v[118:121], v[232:235], v[180:183], v[118:121]
	v_mfma_f32_16x16x32_bf16 v[114:117], v[246:249], v[180:183], v[114:117]
	v_mfma_f32_16x16x32_bf16 v[102:105], v[232:235], v[188:191], v[102:105]
	v_mfma_f32_16x16x32_bf16 v[98:101], v[246:249], v[188:191], v[98:101]
	v_mfma_f32_16x16x32_bf16 v[86:89], v[232:235], v[216:219], v[86:89]
	v_mfma_f32_16x16x32_bf16 v[82:85], v[246:249], v[216:219], v[82:85]
	v_mfma_f32_16x16x32_bf16 v[70:73], v[232:235], v[224:227], v[70:73]
	v_mfma_f32_16x16x32_bf16 v[66:69], v[246:249], v[224:227], v[66:69]
	v_mfma_f32_16x16x32_bf16 v[118:121], v[236:239], v[184:187], v[118:121]
	v_mfma_f32_16x16x32_bf16 v[114:117], v[192:195], v[184:187], v[114:117]
	v_mfma_f32_16x16x32_bf16 v[102:105], v[236:239], v[200:203], v[102:105]
	v_mfma_f32_16x16x32_bf16 v[98:101], v[192:195], v[200:203], v[98:101]
	v_mfma_f32_16x16x32_bf16 v[86:89], v[236:239], v[220:223], v[86:89]
	v_mfma_f32_16x16x32_bf16 v[82:85], v[192:195], v[220:223], v[82:85]
	v_mfma_f32_16x16x32_bf16 v[70:73], v[236:239], v[228:231], v[70:73]
	v_mfma_f32_16x16x32_bf16 v[66:69], v[192:195], v[228:231], v[66:69]
	s_mov_b32 m0, s90
	v_lshl_add_u64 v[250:251], s[56:57], 0, v[136:137]
	s_barrier
	ds_read_b128 v[180:183], v166 offset:16384
	ds_read_b128 v[184:187], v166 offset:17408
	ds_read_b128 v[188:191], v166 offset:18432
	ds_read_b128 v[200:203], v166 offset:19456
	ds_read_b128 v[216:219], v166 offset:20480
	ds_read_b128 v[220:223], v166 offset:21504
	ds_read_b128 v[224:227], v166 offset:22528
	ds_read_b128 v[228:231], v166 offset:23552
	global_load_lds_dwordx4 v[250:251], off
	v_lshl_add_u64 v[196:197], s[56:57], 0, v[132:133]
	s_mov_b32 m0, s91
	s_nop 0
	global_load_lds_dwordx4 v[196:197], off
	s_barrier
	s_waitcnt lgkmcnt(0)
	s_waitcnt lgkmcnt(0)
	v_mfma_f32_16x16x32_bf16 v[62:65], v[162:165], v[180:183], v[62:65]
	v_mfma_f32_16x16x32_bf16 v[58:61], v[172:175], v[180:183], v[58:61]
	v_mfma_f32_16x16x32_bf16 v[46:49], v[162:165], v[188:191], v[46:49]
	v_mfma_f32_16x16x32_bf16 v[42:45], v[172:175], v[188:191], v[42:45]
	v_mfma_f32_16x16x32_bf16 v[30:33], v[162:165], v[216:219], v[30:33]
	v_mfma_f32_16x16x32_bf16 v[26:29], v[172:175], v[216:219], v[26:29]
	v_mfma_f32_16x16x32_bf16 v[14:17], v[162:165], v[224:227], v[14:17]
	v_mfma_f32_16x16x32_bf16 v[10:13], v[172:175], v[224:227], v[10:13]
	v_mfma_f32_16x16x32_bf16 v[62:65], v[168:171], v[184:187], v[62:65]
	v_mfma_f32_16x16x32_bf16 v[58:61], v[176:179], v[184:187], v[58:61]
	v_mfma_f32_16x16x32_bf16 v[46:49], v[168:171], v[200:203], v[46:49]
	v_mfma_f32_16x16x32_bf16 v[42:45], v[176:179], v[200:203], v[42:45]
	v_mfma_f32_16x16x32_bf16 v[30:33], v[168:171], v[220:223], v[30:33]
	v_mfma_f32_16x16x32_bf16 v[26:29], v[176:179], v[220:223], v[26:29]
	v_mfma_f32_16x16x32_bf16 v[14:17], v[168:171], v[228:231], v[14:17]
	v_mfma_f32_16x16x32_bf16 v[10:13], v[176:179], v[228:231], v[10:13]
	s_barrier
; #define PG8_STAGE(bufoff, gbase, voff) do { _Pragma("unroll") for (int _i = 0; _i < 2; ++_i) \
;         __builtin_amdgcn_global_load_lds((const unsigned*)((const char*)(gbase) + (voff)[_i]), (PG8_LAS unsigned*)(lds + (bufoff) + ldsw + _i * 8192), 16, 0, 0); } while (0)
; #define PG8_LDA(dst, b, h) do { _Pragma("unroll") for (int m = 0; m < 4; ++m) _Pragma("unroll") for (int k = 0; k < 2; ++k) dst[m][k] = *(const PG8_LAS bf16x8*)(lds + PG8_SA(b, h) + aoff + m * 2048 + k * 1024); } while (0)
; #define PG8_LDB(dst, b, h) do { _Pragma("unroll") for (int n = 0; n < 2; ++n) _Pragma("unroll") for (int k = 0; k < 2; ++k) dst[n][k] = *(const PG8_LAS bf16x8*)(lds + PG8_SB(b, h) + boff + n * 2048 + k * 1024); } while (0)
; #define PG8_MMA(ai, bj, At, Bt) do { __builtin_amdgcn_s_setprio(1); _Pragma("unroll") for (int m = 0; m < 4; ++m) _Pragma("unroll") for (int n = 0; n < 2; ++n) _Pragma("unroll") for (int k = 0; k < 2; ++k) \
;         acc[ai][bj][m][n] = __builtin_amdgcn_mfma_f32_16x16x32_bf16(Bt[n][k], At[m][k], acc[ai][bj][m][n], 0, 0, 0); __builtin_amdgcn_s_setprio(0); } while (0)
; #define PG8_WAIT_V(n) asm volatile("s_waitcnt vmcnt(" #n ")" ::: "memory")
; #define PG8_WAIT_L(n) asm volatile("s_waitcnt lgkmcnt(" #n ")" ::: "memory")
; #define PG8_BAR __builtin_amdgcn_s_barrier()
; #define PG8_SCHED __builtin_amdgcn_sched_barrier(0)
; template <class Epi, class Sched>
; __device__ __forceinline__ void gemm_phase(PG8_LAS unsigned char* lds, const Gemm g, const Sched& S, const Epi& E, const int tid) {
;     ...
;             PG8_WAIT_V(6); PG8_BAR; PG8_MMA(1, 1, At, B1); PG8_BAR;
;             PG8_LDB(B0, 1, 0); PG8_SCHED; PG8_LDA(At, 1, 0); PG8_STAGE(PG8_SA(0, 1), a2 + hstep, voffA);
;             PG8_WAIT_L(8); PG8_BAR; PG8_WAIT_L(0); PG8_MMA(0, 0, At, B0); PG8_BAR; PG8_SCHED;
;             PG8_LDB(B1, 1, 1); PG8_STAGE(PG8_SB(1, 0), b3, voffB);
;             PG8_BAR; PG8_WAIT_L(0); PG8_MMA(0, 1, At, B1); PG8_BAR;
;             PG8_LDA(At, 1, 1); PG8_STAGE(PG8_SA(1, 0), a3, voffA);
;             PG8_BAR; PG8_WAIT_L(0); PG8_MMA(1, 0, At, B0); PG8_BAR; PG8_SCHED;
	s_add_u32 s88, s10, 0x40000
	s_addc_u32 s89, s11, 0
	s_add_i32 s77, s84, s65
	v_lshl_add_u64 v[162:163], s[88:89], 0, v[134:135]
	s_mov_b32 m0, s77
	s_nop 0
	global_load_lds_dwordx4 v[162:163], off
	v_lshl_add_u64 v[162:163], s[88:89], 0, v[130:131]
	s_add_i32 m0, s77, 0x2000
	s_nop 0
	global_load_lds_dwordx4 v[162:163], off
	s_waitcnt vmcnt(6)
	s_barrier
	v_mfma_f32_16x16x32_bf16 v[54:57], v[232:235], v[180:183], v[54:57]
	v_mfma_f32_16x16x32_bf16 v[50:53], v[246:249], v[180:183], v[50:53]
	v_mfma_f32_16x16x32_bf16 v[38:41], v[232:235], v[188:191], v[38:41]
	v_mfma_f32_16x16x32_bf16 v[34:37], v[246:249], v[188:191], v[34:37]
	v_mfma_f32_16x16x32_bf16 v[22:25], v[232:235], v[216:219], v[22:25]
	v_mfma_f32_16x16x32_bf16 v[18:21], v[246:249], v[216:219], v[18:21]
	v_mfma_f32_16x16x32_bf16 v[6:9], v[232:235], v[224:227], v[6:9]
	v_mfma_f32_16x16x32_bf16 v[2:5], v[246:249], v[224:227], v[2:5]
	v_mfma_f32_16x16x32_bf16 v[54:57], v[236:239], v[184:187], v[54:57]
	v_mfma_f32_16x16x32_bf16 v[50:53], v[192:195], v[184:187], v[50:53]
	v_mfma_f32_16x16x32_bf16 v[38:41], v[236:239], v[200:203], v[38:41]
	v_mfma_f32_16x16x32_bf16 v[34:37], v[192:195], v[200:203], v[34:37]
	v_mfma_f32_16x16x32_bf16 v[22:25], v[236:239], v[220:223], v[22:25]
	v_mfma_f32_16x16x32_bf16 v[18:21], v[192:195], v[220:223], v[18:21]
	v_mfma_f32_16x16x32_bf16 v[6:9], v[236:239], v[228:231], v[6:9]
	v_mfma_f32_16x16x32_bf16 v[2:5], v[192:195], v[228:231], v[2:5]
	s_add_i32 s77, 0, 0x18000
	v_add_u32_e32 v0, s77, v141
	s_barrier
	ds_read_b128 v[162:165], v0
	ds_read_b128 v[168:171], v0 offset:1024
	ds_read_b128 v[172:175], v0 offset:2048
	ds_read_b128 v[176:179], v0 offset:3072
	s_add_u32 s56, s56, 0x40000
	s_addc_u32 s57, s57, 0
	s_mov_b32 m0, s96
	v_lshl_add_u64 v[228:229], s[56:57], 0, v[136:137]
	ds_read_b128 v[180:183], v166 offset:32768
	ds_read_b128 v[184:187], v166 offset:33792
	ds_read_b128 v[188:191], v166 offset:34816
	ds_read_b128 v[192:195], v166 offset:35840
	ds_read_b128 v[200:203], v166 offset:36864
	ds_read_b128 v[216:219], v166 offset:37888
	ds_read_b128 v[220:223], v166 offset:38912
	ds_read_b128 v[224:227], v166 offset:39936
	global_load_lds_dwordx4 v[228:229], off
	v_lshl_add_u64 v[228:229], s[56:57], 0, v[132:133]
	s_mov_b32 m0, s97
	s_nop 0
	global_load_lds_dwordx4 v[228:229], off
	s_waitcnt lgkmcnt(8)
	s_barrier
	s_waitcnt lgkmcnt(0)
	s_waitcnt lgkmcnt(0)
	v_mfma_f32_16x16x32_bf16 v[126:129], v[162:165], v[180:183], v[126:129]
	v_mfma_f32_16x16x32_bf16 v[122:125], v[172:175], v[180:183], v[122:125]
	v_mfma_f32_16x16x32_bf16 v[110:113], v[162:165], v[188:191], v[110:113]
	v_mfma_f32_16x16x32_bf16 v[106:109], v[172:175], v[188:191], v[106:109]
	v_mfma_f32_16x16x32_bf16 v[94:97], v[162:165], v[200:203], v[94:97]
	v_mfma_f32_16x16x32_bf16 v[90:93], v[172:175], v[200:203], v[90:93]
	v_mfma_f32_16x16x32_bf16 v[78:81], v[162:165], v[220:223], v[78:81]
	v_mfma_f32_16x16x32_bf16 v[74:77], v[172:175], v[220:223], v[74:77]
	v_mfma_f32_16x16x32_bf16 v[126:129], v[168:171], v[184:187], v[126:129]
	v_mfma_f32_16x16x32_bf16 v[122:125], v[176:179], v[184:187], v[122:125]
	v_mfma_f32_16x16x32_bf16 v[110:113], v[168:171], v[192:195], v[110:113]
	v_mfma_f32_16x16x32_bf16 v[106:109], v[176:179], v[192:195], v[106:109]
	v_mfma_f32_16x16x32_bf16 v[94:97], v[168:171], v[216:219], v[94:97]
	v_mfma_f32_16x16x32_bf16 v[90:93], v[176:179], v[216:219], v[90:93]
	v_mfma_f32_16x16x32_bf16 v[78:81], v[168:171], v[224:227], v[78:81]
	v_mfma_f32_16x16x32_bf16 v[74:77], v[176:179], v[224:227], v[74:77]
	s_barrier
	s_add_i32 s56, 0, 0x1c000
	s_add_i32 s57, s77, s65
	v_add_u32_e32 v0, s56, v141
	v_lshl_add_u64 v[240:241], v[240:241], 0, s[92:93]
	s_mov_b32 m0, s57
	ds_read_b128 v[228:231], v0
	ds_read_b128 v[232:235], v0 offset:1024
	ds_read_b128 v[236:239], v0 offset:2048
	ds_read_b128 v[246:249], v0 offset:3072
	global_load_lds_dwordx4 v[240:241], off
	v_lshl_add_u64 v[198:199], v[198:199], 0, s[92:93]
	s_add_i32 m0, s57, 0x2000
	s_nop 0
	global_load_lds_dwordx4 v[198:199], off
	s_barrier
	s_waitcnt lgkmcnt(0)
	s_waitcnt lgkmcnt(0)
	v_mfma_f32_16x16x32_bf16 v[118:121], v[228:231], v[180:183], v[118:121]
	v_mfma_f32_16x16x32_bf16 v[114:117], v[236:239], v[180:183], v[114:117]
	v_mfma_f32_16x16x32_bf16 v[102:105], v[228:231], v[188:191], v[102:105]
	v_mfma_f32_16x16x32_bf16 v[98:101], v[236:239], v[188:191], v[98:101]
	v_mfma_f32_16x16x32_bf16 v[86:89], v[228:231], v[200:203], v[86:89]
	v_mfma_f32_16x16x32_bf16 v[82:85], v[236:239], v[200:203], v[82:85]
	v_mfma_f32_16x16x32_bf16 v[70:73], v[228:231], v[220:223], v[70:73]
	v_mfma_f32_16x16x32_bf16 v[66:69], v[236:239], v[220:223], v[66:69]
	v_mfma_f32_16x16x32_bf16 v[118:121], v[232:235], v[184:187], v[118:121]
	v_mfma_f32_16x16x32_bf16 v[114:117], v[246:249], v[184:187], v[114:117]
	v_mfma_f32_16x16x32_bf16 v[102:105], v[232:235], v[192:195], v[102:105]
	v_mfma_f32_16x16x32_bf16 v[98:101], v[246:249], v[192:195], v[98:101]
	v_mfma_f32_16x16x32_bf16 v[86:89], v[232:235], v[216:219], v[86:89]
	v_mfma_f32_16x16x32_bf16 v[82:85], v[246:249], v[216:219], v[82:85]
	v_mfma_f32_16x16x32_bf16 v[70:73], v[232:235], v[224:227], v[70:73]
	v_mfma_f32_16x16x32_bf16 v[66:69], v[246:249], v[224:227], v[66:69]
	s_mov_b32 m0, s44
	v_lshl_add_u64 v[198:199], v[250:251], 0, s[92:93]
	s_barrier
; __device__ __forceinline__ unsigned cvt_pk_bf16(float lo, float hi) { unsigned r; asm volatile("v_cvt_pk_bf16_f32 %0, %1, %2" : "=v"(r) : "v"(lo), "v"(hi)); return r; }
; #define PG8_STAGE(bufoff, gbase, voff) do { _Pragma("unroll") for (int _i = 0; _i < 2; ++_i) \
;         __builtin_amdgcn_global_load_lds((const unsigned*)((const char*)(gbase) + (voff)[_i]), (PG8_LAS unsigned*)(lds + (bufoff) + ldsw + _i * 8192), 16, 0, 0); } while (0)
; #define PG8_MMA(ai, bj, At, Bt) do { __builtin_amdgcn_s_setprio(1); _Pragma("unroll") for (int m = 0; m < 4; ++m) _Pragma("unroll") for (int n = 0; n < 2; ++n) _Pragma("unroll") for (int k = 0; k < 2; ++k) \
;         acc[ai][bj][m][n] = __builtin_amdgcn_mfma_f32_16x16x32_bf16(Bt[n][k], At[m][k], acc[ai][bj][m][n], 0, 0, 0); __builtin_amdgcn_s_setprio(0); } while (0)
; template <class Epi, class Sched>
; __device__ __forceinline__ void gemm_phase(PG8_LAS unsigned char* lds, const Gemm g, const Sched& S, const Epi& E, const int tid) {
;     ...
;             PG8_BAR; PG8_WAIT_L(0); PG8_MMA(1, 0, At, B0); PG8_BAR; PG8_SCHED;
;             PG8_STAGE(PG8_SB(1, 1), b3 + hstep, voffB);
;             PG8_WAIT_V(6); PG8_BAR; PG8_MMA(1, 1, At, B1); PG8_BAR;
;     __device__ __forceinline__ void operator()(const f32x4 (&acc)[2][2][4][2], const Unit& u, int wr, int wc, int fr, int fq) const {
;         const int rl0 = wr * 64 + fr, cl0 = wc * 32 + 8 * fq;
;         const size_t crow0 = (size_t)u.pm * 256, arow0 = (size_t)(u.pm >> 3) * 4096 + (size_t)half * 2048 + (size_t)(u.pm & 7) * 256;
; #pragma unroll
;         for (int ai = 0; ai < 2; ++ai)
; #pragma unroll
;             for (int m = 0; m < 4; ++m) { const int rl = rl0 + ai * HALF + m * 16;
; #pragma unroll
;                 for (int bj = 0; bj < 2; ++bj) { const f32x4 v0 = acc[ai][bj][m][0], v1 = acc[ai][bj][m][1]; const int cl = cl0 + bj * HALF;
;                     if (u.pn < 16) {
;                         u32x4 w; w.x = cvt_pk_bf16(v0[0], v0[1]); w.y = cvt_pk_bf16(v0[2], v0[3]); w.z = cvt_pk_bf16(v1[0], v1[1]); w.w = cvt_pk_bf16(v1[2], v1[3]);
;                         if (u.pn < 12) *(u32x4*)(Q + (crow0 + rl) * 3072 + u.pn * 256 + cl) = w;
;                         else *(u32x4*)(G + (arow0 + rl) * 1024 + (u.pn - 12) * 256 + cl) = w;
;                     } else if (cl < 16) { float* sp = S + (arow0 + rl) * 16 + cl; *(f32x4*)sp = v0; *(f32x4*)(sp + 4) = v1; } } }
	ds_read_b128 v[180:183], v166 offset:49152
	ds_read_b128 v[184:187], v166 offset:50176
	ds_read_b128 v[188:191], v166 offset:51200
	ds_read_b128 v[192:195], v166 offset:52224
	ds_read_b128 v[200:203], v166 offset:53248
	ds_read_b128 v[216:219], v166 offset:54272
	ds_read_b128 v[220:223], v166 offset:55296
	ds_read_b128 v[224:227], v166 offset:56320
	global_load_lds_dwordx4 v[198:199], off
	v_lshl_add_u64 v[196:197], v[196:197], 0, s[92:93]
	s_mov_b32 m0, s0
	s_nop 0
	global_load_lds_dwordx4 v[196:197], off
	s_barrier
	s_waitcnt lgkmcnt(0)
	s_waitcnt lgkmcnt(0)
	v_mfma_f32_16x16x32_bf16 v[62:65], v[162:165], v[180:183], v[62:65]
	v_mfma_f32_16x16x32_bf16 v[58:61], v[172:175], v[180:183], v[58:61]
	v_mfma_f32_16x16x32_bf16 v[46:49], v[162:165], v[188:191], v[46:49]
	v_mfma_f32_16x16x32_bf16 v[42:45], v[172:175], v[188:191], v[42:45]
	v_mfma_f32_16x16x32_bf16 v[30:33], v[162:165], v[200:203], v[30:33]
	v_mfma_f32_16x16x32_bf16 v[26:29], v[172:175], v[200:203], v[26:29]
	v_mfma_f32_16x16x32_bf16 v[14:17], v[162:165], v[220:223], v[14:17]
	v_mfma_f32_16x16x32_bf16 v[10:13], v[172:175], v[220:223], v[10:13]
	v_mfma_f32_16x16x32_bf16 v[62:65], v[168:171], v[184:187], v[62:65]
	v_mfma_f32_16x16x32_bf16 v[58:61], v[176:179], v[184:187], v[58:61]
	v_mfma_f32_16x16x32_bf16 v[46:49], v[168:171], v[192:195], v[46:49]
	v_mfma_f32_16x16x32_bf16 v[42:45], v[176:179], v[192:195], v[42:45]
	v_mfma_f32_16x16x32_bf16 v[30:33], v[168:171], v[216:219], v[30:33]
	v_mfma_f32_16x16x32_bf16 v[26:29], v[176:179], v[216:219], v[26:29]
	v_mfma_f32_16x16x32_bf16 v[14:17], v[168:171], v[224:227], v[14:17]
	v_mfma_f32_16x16x32_bf16 v[10:13], v[176:179], v[224:227], v[10:13]
	s_barrier
	s_add_u32 s10, s10, 0x40080
	s_addc_u32 s11, s11, 0
	s_add_i32 s56, s56, s65
	v_lshl_add_u64 v[162:163], s[10:11], 0, v[134:135]
	s_mov_b32 m0, s56
	s_nop 0
	global_load_lds_dwordx4 v[162:163], off
	v_lshl_add_u64 v[162:163], s[10:11], 0, v[130:131]
	s_add_i32 m0, s56, 0x2000
	s_nop 0
	global_load_lds_dwordx4 v[162:163], off
	s_waitcnt vmcnt(6)
	s_barrier
	v_mfma_f32_16x16x32_bf16 v[54:57], v[228:231], v[180:183], v[54:57]
	v_mfma_f32_16x16x32_bf16 v[50:53], v[236:239], v[180:183], v[50:53]
	v_mfma_f32_16x16x32_bf16 v[38:41], v[228:231], v[188:191], v[38:41]
	v_mfma_f32_16x16x32_bf16 v[34:37], v[236:239], v[188:191], v[34:37]
	v_mfma_f32_16x16x32_bf16 v[22:25], v[228:231], v[200:203], v[22:25]
	v_mfma_f32_16x16x32_bf16 v[18:21], v[236:239], v[200:203], v[18:21]
	v_mfma_f32_16x16x32_bf16 v[6:9], v[228:231], v[220:223], v[6:9]
	v_mfma_f32_16x16x32_bf16 v[2:5], v[236:239], v[220:223], v[2:5]
	v_mfma_f32_16x16x32_bf16 v[54:57], v[232:235], v[184:187], v[54:57]
	v_mfma_f32_16x16x32_bf16 v[50:53], v[246:249], v[184:187], v[50:53]
	v_mfma_f32_16x16x32_bf16 v[38:41], v[232:235], v[192:195], v[38:41]
	v_mfma_f32_16x16x32_bf16 v[34:37], v[246:249], v[192:195], v[34:37]
	v_mfma_f32_16x16x32_bf16 v[22:25], v[232:235], v[216:219], v[22:25]
	v_mfma_f32_16x16x32_bf16 v[18:21], v[246:249], v[216:219], v[18:21]
	v_mfma_f32_16x16x32_bf16 v[6:9], v[232:235], v[224:227], v[6:9]
	v_mfma_f32_16x16x32_bf16 v[2:5], v[246:249], v[224:227], v[2:5]
	s_add_i32 s76, s76, 2
	s_add_u32 s6, s6, 0x100
	s_addc_u32 s7, s7, 0
	s_add_u32 s34, s34, 0x100
	s_addc_u32 s35, s35, 0
	s_cmp_gt_u32 s76, 13
	s_barrier
	s_cbranch_scc0 .LBB0_566
	s_ashr_i32 s6, s8, 3
	s_ashr_i32 s7, s6, 31
	s_lshl_b32 s9, s8, 8
	s_lshl_b64 s[6:7], s[6:7], 12
	s_and_b32 s9, s9, 0x700
	s_or_b32 s6, s6, s9
	s_or_b64 s[88:89], s[6:7], s[12:13]
	s_cmp_lt_i32 s63, 16
	s_cselect_b64 s[6:7], -1, 0
	s_cmp_gt_i32 s63, 15
	s_cselect_b64 s[56:57], -1, 0
	s_cmp_gt_i32 s63, 11
	s_cselect_b64 s[10:11], -1, 0
	v_lshl_add_u64 v[162:163], s[88:89], 0, v[138:139]
	s_mov_b64 s[34:35], -1
	s_and_b64 vcc, exec, s[56:57]
	s_cbranch_vccz .LBB0_571
	s_and_saveexec_b64 s[34:35], s[2:3]
	s_cbranch_execz .LBB0_570
	v_lshlrev_b64 v[164:165], 6, v[162:163]
	v_lshl_add_u64 v[164:165], v[156:157], 0, v[164:165]
	global_store_dwordx4 v[164:165], v[126:129], off
	global_store_dwordx4 v[164:165], v[122:125], off offset:16

; template <class Epi, class Sched>
; __device__ __forceinline__ void gemm_phase(PG8_LAS unsigned char* lds, const Gemm g, const Sched& S, const Epi& E, const int tid) {
;     ...
;         const bool has_next = S.next(ui + 1, nxt);
;         const char* nA = has_next ? (const char*)g.A + a_tile_row(g, nxt.pm) * (size_t)K * 2 : cA; const char* nB = has_next ? (const char*)g.Bt + (size_t)nxt.pn * tstep : cB;
;         for (int t = 0; t < nt; t += 2) {
;             const bool last = (t == nt - 2);
;             const char* a1 = cA + (size_t)(t + 1) * kstep;
;             const char* a2 = last ? nA : cA + (size_t)(t + 2) * kstep; const char* b2 = last ? nB : cB + (size_t)(t + 2) * kstep;
;     ...
; #pragma unroll
;         for (int a = 0; a < 2; ++a)
; #pragma unroll
;             for (int b = 0; b < 2; ++b)
; #pragma unroll
;                 for (int m = 0; m < 4; ++m)
; #pragma unroll
;                     for (int n = 0; n < 2; ++n) acc[a][b][m][n] = (f32x4){0.f, 0.f, 0.f, 0.f};
.LBB0_700:
	s_ashr_i32 s13, s12, 31
	v_mov_b64_e32 v[2:3], 0x480
	s_lshl_b64 s[0:1], s[12:13], 19
	v_cmp_lt_i64_e32 vcc, s[14:15], v[2:3]
	s_add_u32 s14, s82, s0
	s_addc_u32 s15, s83, s1
	s_and_b64 s[0:1], vcc, exec
	s_cselect_b32 s0, s15, s7
	s_cselect_b32 s1, s14, s6
	s_ashr_i32 s11, s10, 31
	s_lshl_b64 s[18:19], s[10:11], 19
	s_add_u32 s18, s35, s18
	s_addc_u32 s19, s76, s19
	s_and_b64 s[56:57], vcc, exec
	s_cselect_b32 s11, s19, s9
	s_cselect_b32 s13, s18, s8
	s_add_u32 s6, s6, 0x40080
	s_addc_u32 s7, s7, 0
	s_add_u32 s62, s8, 0x100
	v_mov_b32_e32 v2, 0
	s_addc_u32 s63, s9, 0
	s_mov_b32 s65, -2
	v_mov_b32_e32 v3, v2
	v_mov_b32_e32 v4, v2
	v_mov_b32_e32 v5, v2
	v_mov_b32_e32 v6, v2
	v_mov_b32_e32 v7, v2
	v_mov_b32_e32 v8, v2
	v_mov_b32_e32 v9, v2
	v_mov_b32_e32 v18, v2
	v_mov_b32_e32 v19, v2
	v_mov_b32_e32 v20, v2
	v_mov_b32_e32 v21, v2
	v_mov_b32_e32 v22, v2
	v_mov_b32_e32 v23, v2
	v_mov_b32_e32 v24, v2
	v_mov_b32_e32 v25, v2
	v_mov_b32_e32 v34, v2
	v_mov_b32_e32 v35, v2
	v_mov_b32_e32 v36, v2
	v_mov_b32_e32 v37, v2
	v_mov_b32_e32 v38, v2
	v_mov_b32_e32 v39, v2
	v_mov_b32_e32 v40, v2
	v_mov_b32_e32 v41, v2
	v_mov_b32_e32 v50, v2
	v_mov_b32_e32 v51, v2
	v_mov_b32_e32 v52, v2
	v_mov_b32_e32 v53, v2
	v_mov_b32_e32 v54, v2
	v_mov_b32_e32 v55, v2
	v_mov_b32_e32 v56, v2
	v_mov_b32_e32 v57, v2
	v_mov_b32_e32 v10, v2
	v_mov_b32_e32 v11, v2
	v_mov_b32_e32 v12, v2
	v_mov_b32_e32 v13, v2
	v_mov_b32_e32 v14, v2
	v_mov_b32_e32 v15, v2
	s_waitcnt lgkmcnt(0)
	v_mov_b32_e32 v16, v2
	v_mov_b32_e32 v17, v2
	v_mov_b32_e32 v26, v2
	v_mov_b32_e32 v27, v2
	v_mov_b32_e32 v28, v2
	v_mov_b32_e32 v29, v2
	v_mov_b32_e32 v30, v2
	v_mov_b32_e32 v31, v2
	v_mov_b32_e32 v32, v2
	v_mov_b32_e32 v33, v2
	v_mov_b32_e32 v42, v2
	v_mov_b32_e32 v43, v2
	v_mov_b32_e32 v44, v2
	v_mov_b32_e32 v45, v2
	v_mov_b32_e32 v46, v2
	v_mov_b32_e32 v47, v2
	v_mov_b32_e32 v48, v2
	v_mov_b32_e32 v49, v2
	v_mov_b32_e32 v58, v2
	v_mov_b32_e32 v59, v2
	v_mov_b32_e32 v60, v2
	v_mov_b32_e32 v61, v2
	v_mov_b32_e32 v62, v2
	v_mov_b32_e32 v63, v2
	v_mov_b32_e32 v64, v2
	v_mov_b32_e32 v65, v2
	v_mov_b32_e32 v66, v2
	v_mov_b32_e32 v67, v2
	v_mov_b32_e32 v68, v2
	v_mov_b32_e32 v69, v2
	v_mov_b32_e32 v70, v2
	v_mov_b32_e32 v71, v2
	v_mov_b32_e32 v72, v2
	v_mov_b32_e32 v73, v2
	v_mov_b32_e32 v82, v2
	v_mov_b32_e32 v83, v2
	v_mov_b32_e32 v84, v2
	v_mov_b32_e32 v85, v2
	v_mov_b32_e32 v86, v2
	v_mov_b32_e32 v87, v2
	v_mov_b32_e32 v88, v2
	v_mov_b32_e32 v89, v2
	v_mov_b32_e32 v98, v2
	v_mov_b32_e32 v99, v2
	v_mov_b32_e32 v100, v2
	v_mov_b32_e32 v101, v2
	v_mov_b32_e32 v102, v2
	v_mov_b32_e32 v103, v2
	v_mov_b32_e32 v104, v2
	v_mov_b32_e32 v105, v2
	v_mov_b32_e32 v114, v2
	v_mov_b32_e32 v115, v2
	v_mov_b32_e32 v116, v2
	v_mov_b32_e32 v117, v2
	v_mov_b32_e32 v118, v2
	v_mov_b32_e32 v119, v2
	v_mov_b32_e32 v120, v2
	v_mov_b32_e32 v121, v2
	v_mov_b32_e32 v74, v2
	v_mov_b32_e32 v75, v2
	v_mov_b32_e32 v76, v2
	v_mov_b32_e32 v77, v2
	v_mov_b32_e32 v78, v2
	v_mov_b32_e32 v79, v2
	v_mov_b32_e32 v80, v2
	v_mov_b32_e32 v81, v2
	v_mov_b32_e32 v90, v2
	v_mov_b32_e32 v91, v2
	v_mov_b32_e32 v92, v2
	v_mov_b32_e32 v93, v2
	v_mov_b32_e32 v94, v2
	v_mov_b32_e32 v95, v2
	v_mov_b32_e32 v96, v2
	v_mov_b32_e32 v97, v2
	v_mov_b32_e32 v106, v2
	v_mov_b32_e32 v107, v2
	v_mov_b32_e32 v108, v2
	v_mov_b32_e32 v109, v2
	v_mov_b32_e32 v110, v2
	v_mov_b32_e32 v111, v2
	v_mov_b32_e32 v112, v2
	v_mov_b32_e32 v113, v2
	v_mov_b32_e32 v122, v2
	v_mov_b32_e32 v123, v2
	v_mov_b32_e32 v124, v2
	v_mov_b32_e32 v125, v2
	v_mov_b32_e32 v126, v2
	v_mov_b32_e32 v127, v2
	v_mov_b32_e32 v128, v2
	v_mov_b32_e32 v129, v2
	v_readlane_b32 s101, v254, 14
	s_bitcmp1_b32 s101, 0
	s_cbranch_scc0 .Lprio_skip4
	s_setprio 1

; #define PG8_STAGE(bufoff, gbase, voff) do { _Pragma("unroll") for (int _i = 0; _i < 2; ++_i) \
;         __builtin_amdgcn_global_load_lds((const unsigned*)((const char*)(gbase) + (voff)[_i]), (PG8_LAS unsigned*)(lds + (bufoff) + ldsw + _i * 8192), 16, 0, 0); } while (0)
; #define PG8_LDA(dst, b, h) do { _Pragma("unroll") for (int m = 0; m < 4; ++m) _Pragma("unroll") for (int k = 0; k < 2; ++k) dst[m][k] = *(const PG8_LAS bf16x8*)(lds + PG8_SA(b, h) + aoff + m * 2048 + k * 1024); } while (0)
; #define PG8_LDB(dst, b, h) do { _Pragma("unroll") for (int n = 0; n < 2; ++n) _Pragma("unroll") for (int k = 0; k < 2; ++k) dst[n][k] = *(const PG8_LAS bf16x8*)(lds + PG8_SB(b, h) + boff + n * 2048 + k * 1024); } while (0)
; #define PG8_MMA(ai, bj, At, Bt) do { __builtin_amdgcn_s_setprio(1); _Pragma("unroll") for (int m = 0; m < 4; ++m) _Pragma("unroll") for (int n = 0; n < 2; ++n) _Pragma("unroll") for (int k = 0; k < 2; ++k) \
;         acc[ai][bj][m][n] = __builtin_amdgcn_mfma_f32_16x16x32_bf16(Bt[n][k], At[m][k], acc[ai][bj][m][n], 0, 0, 0); __builtin_amdgcn_s_setprio(0); } while (0)
; #define PG8_WAIT_V(n) asm volatile("s_waitcnt vmcnt(" #n ")" ::: "memory")
; #define PG8_WAIT_L(n) asm volatile("s_waitcnt lgkmcnt(" #n ")" ::: "memory")
; #define PG8_BAR __builtin_amdgcn_s_barrier()
; #define PG8_SCHED __builtin_amdgcn_sched_barrier(0)
; template <class Epi, class Sched>
; __device__ __forceinline__ void gemm_phase(PG8_LAS unsigned char* lds, const Gemm g, const Sched& S, const Epi& E, const int tid) {
;     ...
;             PG8_LDB(B0, 0, 0); PG8_SCHED; PG8_LDA(At, 0, 0); PG8_STAGE(PG8_SA(1, 1), a1 + hstep, voffA);
;             PG8_WAIT_L(8); PG8_BAR; PG8_WAIT_L(0); PG8_MMA(0, 0, At, B0); PG8_BAR; PG8_SCHED;
;             PG8_LDB(B1, 0, 1); PG8_STAGE(PG8_SB(0, 0), b2, voffB);
;             PG8_BAR; PG8_WAIT_L(0); PG8_MMA(0, 1, At, B1); PG8_BAR;
;             PG8_LDA(At, 0, 1); PG8_STAGE(PG8_SA(0, 0), a2, voffA);
;             PG8_BAR; PG8_WAIT_L(0); PG8_MMA(1, 0, At, B0); PG8_BAR; PG8_SCHED;
;             PG8_STAGE(PG8_SB(0, 1), b2 + hstep, voffB);
;             PG8_WAIT_V(6); PG8_BAR; PG8_MMA(1, 1, At, B1); PG8_BAR;
.LBB0_701:
	s_add_u32 s8, s6, 0xfffc0080
	s_addc_u32 s9, s7, -1
	s_add_i32 s89, 0, 0x10000
	v_add_u32_e32 v154, s89, v167
	ds_read_b128 v[142:145], v154
	ds_read_b128 v[146:149], v154 offset:1024
	ds_read_b128 v[150:153], v154 offset:2048
	ds_read_b128 v[154:157], v154 offset:3072
	s_cmp_eq_u32 s65, 12
	s_cselect_b32 s57, s0, s9
	s_cselect_b32 s56, s1, s8
	s_cselect_b32 s9, s11, s63
	s_cselect_b32 s8, s13, s62
	v_lshl_add_u64 v[192:193], s[6:7], 0, v[138:139]
	s_add_i32 m0, s69, 0xc000
	ds_read_b128 v[158:161], v171
	ds_read_b128 v[162:165], v171 offset:1024
	ds_read_b128 v[172:175], v171 offset:2048
	ds_read_b128 v[176:179], v171 offset:3072
	ds_read_b128 v[180:183], v171 offset:4096
	ds_read_b128 v[184:187], v171 offset:5120
	ds_read_b128 v[188:191], v171 offset:6144
	ds_read_b128 v[200:203], v171 offset:7168
	global_load_lds_dwordx4 v[192:193], off
	v_lshl_add_u64 v[192:193], s[6:7], 0, v[140:141]
	s_add_i32 m0, s69, 0xe000
	s_nop 0
	global_load_lds_dwordx4 v[192:193], off
	s_waitcnt lgkmcnt(8)
	s_barrier
	s_waitcnt lgkmcnt(0)
	s_waitcnt lgkmcnt(0)
	v_mfma_f32_16x16x32_bf16 v[126:129], v[142:145], v[158:161], v[126:129]
	v_mfma_f32_16x16x32_bf16 v[122:125], v[150:153], v[158:161], v[122:125]
	v_mfma_f32_16x16x32_bf16 v[110:113], v[142:145], v[172:175], v[110:113]
	v_mfma_f32_16x16x32_bf16 v[106:109], v[150:153], v[172:175], v[106:109]
	v_mfma_f32_16x16x32_bf16 v[94:97], v[142:145], v[180:183], v[94:97]
	v_mfma_f32_16x16x32_bf16 v[90:93], v[150:153], v[180:183], v[90:93]
	v_mfma_f32_16x16x32_bf16 v[78:81], v[142:145], v[188:191], v[78:81]
	v_mfma_f32_16x16x32_bf16 v[74:77], v[150:153], v[188:191], v[74:77]
	v_mfma_f32_16x16x32_bf16 v[126:129], v[146:149], v[162:165], v[126:129]
	v_mfma_f32_16x16x32_bf16 v[122:125], v[154:157], v[162:165], v[122:125]
	v_mfma_f32_16x16x32_bf16 v[110:113], v[146:149], v[176:179], v[110:113]
	v_mfma_f32_16x16x32_bf16 v[106:109], v[154:157], v[176:179], v[106:109]
	v_mfma_f32_16x16x32_bf16 v[94:97], v[146:149], v[184:187], v[94:97]
	v_mfma_f32_16x16x32_bf16 v[90:93], v[154:157], v[184:187], v[90:93]
	v_mfma_f32_16x16x32_bf16 v[78:81], v[146:149], v[200:203], v[78:81]
	v_mfma_f32_16x16x32_bf16 v[74:77], v[154:157], v[200:203], v[74:77]
	s_barrier
	s_add_i32 s94, 0, 0x14000
	v_add_u32_e32 v192, s94, v167
	s_add_i32 s89, s89, s77
	ds_read_b128 v[216:219], v192
	ds_read_b128 v[220:223], v192 offset:1024
	ds_read_b128 v[224:227], v192 offset:2048
	ds_read_b128 v[228:231], v192 offset:3072
	v_lshl_add_u64 v[192:193], s[8:9], 0, v[132:133]
	s_mov_b32 m0, s89
	v_lshl_add_u64 v[194:195], s[8:9], 0, v[136:137]
	global_load_lds_dwordx4 v[192:193], off
	s_add_i32 m0, s89, 0x2000
	s_nop 0
	global_load_lds_dwordx4 v[194:195], off
	s_barrier
	s_waitcnt lgkmcnt(0)
	s_waitcnt lgkmcnt(0)
	v_mfma_f32_16x16x32_bf16 v[118:121], v[216:219], v[158:161], v[118:121]
	v_mfma_f32_16x16x32_bf16 v[114:117], v[224:227], v[158:161], v[114:117]
	v_mfma_f32_16x16x32_bf16 v[102:105], v[216:219], v[172:175], v[102:105]
	v_mfma_f32_16x16x32_bf16 v[98:101], v[224:227], v[172:175], v[98:101]
	v_mfma_f32_16x16x32_bf16 v[86:89], v[216:219], v[180:183], v[86:89]
	v_mfma_f32_16x16x32_bf16 v[82:85], v[224:227], v[180:183], v[82:85]
	v_mfma_f32_16x16x32_bf16 v[70:73], v[216:219], v[188:191], v[70:73]
	v_mfma_f32_16x16x32_bf16 v[66:69], v[224:227], v[188:191], v[66:69]
	v_mfma_f32_16x16x32_bf16 v[118:121], v[220:223], v[162:165], v[118:121]
	v_mfma_f32_16x16x32_bf16 v[114:117], v[228:231], v[162:165], v[114:117]
	v_mfma_f32_16x16x32_bf16 v[102:105], v[220:223], v[176:179], v[102:105]
	v_mfma_f32_16x16x32_bf16 v[98:101], v[228:231], v[176:179], v[98:101]
	v_mfma_f32_16x16x32_bf16 v[86:89], v[220:223], v[184:187], v[86:89]
	v_mfma_f32_16x16x32_bf16 v[82:85], v[228:231], v[184:187], v[82:85]
	v_mfma_f32_16x16x32_bf16 v[70:73], v[220:223], v[200:203], v[70:73]
	v_mfma_f32_16x16x32_bf16 v[66:69], v[228:231], v[200:203], v[66:69]
	s_mov_b32 m0, s69
	v_lshl_add_u64 v[232:233], s[56:57], 0, v[130:131]
	s_barrier
	ds_read_b128 v[158:161], v171 offset:16384
	ds_read_b128 v[162:165], v171 offset:17408
	ds_read_b128 v[172:175], v171 offset:18432
	ds_read_b128 v[176:179], v171 offset:19456
	ds_read_b128 v[180:183], v171 offset:20480
	ds_read_b128 v[184:187], v171 offset:21504
	ds_read_b128 v[188:191], v171 offset:22528
	ds_read_b128 v[200:203], v171 offset:23552
	global_load_lds_dwordx4 v[232:233], off
	v_lshl_add_u64 v[234:235], s[56:57], 0, v[134:135]
	s_mov_b32 m0, s73
	s_nop 0
	global_load_lds_dwordx4 v[234:235], off
	s_barrier
	s_waitcnt lgkmcnt(0)
	s_waitcnt lgkmcnt(0)
	v_mfma_f32_16x16x32_bf16 v[62:65], v[142:145], v[158:161], v[62:65]
	v_mfma_f32_16x16x32_bf16 v[58:61], v[150:153], v[158:161], v[58:61]
	v_mfma_f32_16x16x32_bf16 v[46:49], v[142:145], v[172:175], v[46:49]
	v_mfma_f32_16x16x32_bf16 v[42:45], v[150:153], v[172:175], v[42:45]
	v_mfma_f32_16x16x32_bf16 v[30:33], v[142:145], v[180:183], v[30:33]
	v_mfma_f32_16x16x32_bf16 v[26:29], v[150:153], v[180:183], v[26:29]
	v_mfma_f32_16x16x32_bf16 v[14:17], v[142:145], v[188:191], v[14:17]
	v_mfma_f32_16x16x32_bf16 v[10:13], v[150:153], v[188:191], v[10:13]
	v_mfma_f32_16x16x32_bf16 v[62:65], v[146:149], v[162:165], v[62:65]
	v_mfma_f32_16x16x32_bf16 v[58:61], v[154:157], v[162:165], v[58:61]
	v_mfma_f32_16x16x32_bf16 v[46:49], v[146:149], v[176:179], v[46:49]
	v_mfma_f32_16x16x32_bf16 v[42:45], v[154:157], v[176:179], v[42:45]
	v_mfma_f32_16x16x32_bf16 v[30:33], v[146:149], v[184:187], v[30:33]
	v_mfma_f32_16x16x32_bf16 v[26:29], v[154:157], v[184:187], v[26:29]
	v_mfma_f32_16x16x32_bf16 v[14:17], v[146:149], v[200:203], v[14:17]
	v_mfma_f32_16x16x32_bf16 v[10:13], v[154:157], v[200:203], v[10:13]
	s_barrier
; #define PG8_STAGE(bufoff, gbase, voff) do { _Pragma("unroll") for (int _i = 0; _i < 2; ++_i) \
;         __builtin_amdgcn_global_load_lds((const unsigned*)((const char*)(gbase) + (voff)[_i]), (PG8_LAS unsigned*)(lds + (bufoff) + ldsw + _i * 8192), 16, 0, 0); } while (0)
; #define PG8_LDA(dst, b, h) do { _Pragma("unroll") for (int m = 0; m < 4; ++m) _Pragma("unroll") for (int k = 0; k < 2; ++k) dst[m][k] = *(const PG8_LAS bf16x8*)(lds + PG8_SA(b, h) + aoff + m * 2048 + k * 1024); } while (0)
; #define PG8_LDB(dst, b, h) do { _Pragma("unroll") for (int n = 0; n < 2; ++n) _Pragma("unroll") for (int k = 0; k < 2; ++k) dst[n][k] = *(const PG8_LAS bf16x8*)(lds + PG8_SB(b, h) + boff + n * 2048 + k * 1024); } while (0)
; #define PG8_MMA(ai, bj, At, Bt) do { __builtin_amdgcn_s_setprio(1); _Pragma("unroll") for (int m = 0; m < 4; ++m) _Pragma("unroll") for (int n = 0; n < 2; ++n) _Pragma("unroll") for (int k = 0; k < 2; ++k) \
;         acc[ai][bj][m][n] = __builtin_amdgcn_mfma_f32_16x16x32_bf16(Bt[n][k], At[m][k], acc[ai][bj][m][n], 0, 0, 0); __builtin_amdgcn_s_setprio(0); } while (0)
; #define PG8_WAIT_V(n) asm volatile("s_waitcnt vmcnt(" #n ")" ::: "memory")
; #define PG8_WAIT_L(n) asm volatile("s_waitcnt lgkmcnt(" #n ")" ::: "memory")
; #define PG8_BAR __builtin_amdgcn_s_barrier()
; #define PG8_SCHED __builtin_amdgcn_sched_barrier(0)
; template <class Epi, class Sched>
; __device__ __forceinline__ void gemm_phase(PG8_LAS unsigned char* lds, const Gemm g, const Sched& S, const Epi& E, const int tid) {
;     ...
;             PG8_WAIT_V(6); PG8_BAR; PG8_MMA(1, 1, At, B1); PG8_BAR;
;             PG8_LDB(B0, 1, 0); PG8_SCHED; PG8_LDA(At, 1, 0); PG8_STAGE(PG8_SA(0, 1), a2 + hstep, voffA);
;             PG8_WAIT_L(8); PG8_BAR; PG8_WAIT_L(0); PG8_MMA(0, 0, At, B0); PG8_BAR; PG8_SCHED;
;             PG8_LDB(B1, 1, 1); PG8_STAGE(PG8_SB(1, 0), b3, voffB);
;             PG8_BAR; PG8_WAIT_L(0); PG8_MMA(0, 1, At, B1); PG8_BAR;
;             PG8_LDA(At, 1, 1); PG8_STAGE(PG8_SA(1, 0), a3, voffA);
;             PG8_BAR; PG8_WAIT_L(0); PG8_MMA(1, 0, At, B0); PG8_BAR; PG8_SCHED;
	s_add_u32 s90, s8, 0x40000
	s_addc_u32 s91, s9, 0
	s_add_i32 s89, s94, s77
	v_lshl_add_u64 v[142:143], s[90:91], 0, v[132:133]
	s_mov_b32 m0, s89
	s_nop 0
	global_load_lds_dwordx4 v[142:143], off
	v_lshl_add_u64 v[142:143], s[90:91], 0, v[136:137]
	s_add_i32 m0, s89, 0x2000
	s_nop 0
	global_load_lds_dwordx4 v[142:143], off
	s_waitcnt vmcnt(6)
	s_barrier
	v_mfma_f32_16x16x32_bf16 v[54:57], v[216:219], v[158:161], v[54:57]
	v_mfma_f32_16x16x32_bf16 v[50:53], v[224:227], v[158:161], v[50:53]
	v_mfma_f32_16x16x32_bf16 v[38:41], v[216:219], v[172:175], v[38:41]
	v_mfma_f32_16x16x32_bf16 v[34:37], v[224:227], v[172:175], v[34:37]
	v_mfma_f32_16x16x32_bf16 v[22:25], v[216:219], v[180:183], v[22:25]
	v_mfma_f32_16x16x32_bf16 v[18:21], v[224:227], v[180:183], v[18:21]
	v_mfma_f32_16x16x32_bf16 v[6:9], v[216:219], v[188:191], v[6:9]
	v_mfma_f32_16x16x32_bf16 v[2:5], v[224:227], v[188:191], v[2:5]
	v_mfma_f32_16x16x32_bf16 v[54:57], v[220:223], v[162:165], v[54:57]
	v_mfma_f32_16x16x32_bf16 v[50:53], v[228:231], v[162:165], v[50:53]
	v_mfma_f32_16x16x32_bf16 v[38:41], v[220:223], v[176:179], v[38:41]
	v_mfma_f32_16x16x32_bf16 v[34:37], v[228:231], v[176:179], v[34:37]
	v_mfma_f32_16x16x32_bf16 v[22:25], v[220:223], v[184:187], v[22:25]
	v_mfma_f32_16x16x32_bf16 v[18:21], v[228:231], v[184:187], v[18:21]
	v_mfma_f32_16x16x32_bf16 v[6:9], v[220:223], v[200:203], v[6:9]
	v_mfma_f32_16x16x32_bf16 v[2:5], v[228:231], v[200:203], v[2:5]
	s_add_i32 s89, 0, 0x18000
	v_add_u32_e32 v154, s89, v167
	s_barrier
	ds_read_b128 v[142:145], v154
	ds_read_b128 v[146:149], v154 offset:1024
	ds_read_b128 v[150:153], v154 offset:2048
	ds_read_b128 v[154:157], v154 offset:3072
	s_add_u32 s56, s56, 0x40000
	s_addc_u32 s57, s57, 0
	s_mov_b32 m0, s84
	v_lshl_add_u64 v[216:217], s[56:57], 0, v[130:131]
	ds_read_b128 v[158:161], v171 offset:32768
	ds_read_b128 v[162:165], v171 offset:33792
	ds_read_b128 v[172:175], v171 offset:34816
	ds_read_b128 v[176:179], v171 offset:35840
	ds_read_b128 v[180:183], v171 offset:36864
	ds_read_b128 v[184:187], v171 offset:37888
	ds_read_b128 v[188:191], v171 offset:38912
	ds_read_b128 v[200:203], v171 offset:39936
	global_load_lds_dwordx4 v[216:217], off
	v_lshl_add_u64 v[216:217], s[56:57], 0, v[134:135]
	s_mov_b32 m0, s88
	s_nop 0
	global_load_lds_dwordx4 v[216:217], off
	s_waitcnt lgkmcnt(8)
	s_barrier
	s_waitcnt lgkmcnt(0)
	s_waitcnt lgkmcnt(0)
	v_mfma_f32_16x16x32_bf16 v[126:129], v[142:145], v[158:161], v[126:129]
	v_mfma_f32_16x16x32_bf16 v[122:125], v[150:153], v[158:161], v[122:125]
	v_mfma_f32_16x16x32_bf16 v[110:113], v[142:145], v[172:175], v[110:113]
	v_mfma_f32_16x16x32_bf16 v[106:109], v[150:153], v[172:175], v[106:109]
	v_mfma_f32_16x16x32_bf16 v[94:97], v[142:145], v[180:183], v[94:97]
	v_mfma_f32_16x16x32_bf16 v[90:93], v[150:153], v[180:183], v[90:93]
	v_mfma_f32_16x16x32_bf16 v[78:81], v[142:145], v[188:191], v[78:81]
	v_mfma_f32_16x16x32_bf16 v[74:77], v[150:153], v[188:191], v[74:77]
	v_mfma_f32_16x16x32_bf16 v[126:129], v[146:149], v[162:165], v[126:129]
	v_mfma_f32_16x16x32_bf16 v[122:125], v[154:157], v[162:165], v[122:125]
	v_mfma_f32_16x16x32_bf16 v[110:113], v[146:149], v[176:179], v[110:113]
	v_mfma_f32_16x16x32_bf16 v[106:109], v[154:157], v[176:179], v[106:109]
	v_mfma_f32_16x16x32_bf16 v[94:97], v[146:149], v[184:187], v[94:97]
	v_mfma_f32_16x16x32_bf16 v[90:93], v[154:157], v[184:187], v[90:93]
	v_mfma_f32_16x16x32_bf16 v[78:81], v[146:149], v[200:203], v[78:81]
	v_mfma_f32_16x16x32_bf16 v[74:77], v[154:157], v[200:203], v[74:77]
	s_barrier
	s_add_i32 s56, 0, 0x1c000
	s_add_i32 s57, s89, s77
	v_add_u32_e32 v196, s56, v167
	v_lshl_add_u64 v[192:193], v[192:193], 0, s[92:93]
	s_mov_b32 m0, s57
	ds_read_b128 v[216:219], v196
	ds_read_b128 v[220:223], v196 offset:1024
	ds_read_b128 v[224:227], v196 offset:2048
	ds_read_b128 v[228:231], v196 offset:3072
	global_load_lds_dwordx4 v[192:193], off
	v_lshl_add_u64 v[192:193], v[194:195], 0, s[92:93]
	s_add_i32 m0, s57, 0x2000
	s_nop 0
	global_load_lds_dwordx4 v[192:193], off
	s_barrier
	s_waitcnt lgkmcnt(0)
	s_waitcnt lgkmcnt(0)
	v_mfma_f32_16x16x32_bf16 v[118:121], v[216:219], v[158:161], v[118:121]
	v_mfma_f32_16x16x32_bf16 v[114:117], v[224:227], v[158:161], v[114:117]
	v_mfma_f32_16x16x32_bf16 v[102:105], v[216:219], v[172:175], v[102:105]
	v_mfma_f32_16x16x32_bf16 v[98:101], v[224:227], v[172:175], v[98:101]
	v_mfma_f32_16x16x32_bf16 v[86:89], v[216:219], v[180:183], v[86:89]
	v_mfma_f32_16x16x32_bf16 v[82:85], v[224:227], v[180:183], v[82:85]
	v_mfma_f32_16x16x32_bf16 v[70:73], v[216:219], v[188:191], v[70:73]
	v_mfma_f32_16x16x32_bf16 v[66:69], v[224:227], v[188:191], v[66:69]
	v_mfma_f32_16x16x32_bf16 v[118:121], v[220:223], v[162:165], v[118:121]
	v_mfma_f32_16x16x32_bf16 v[114:117], v[228:231], v[162:165], v[114:117]
	v_mfma_f32_16x16x32_bf16 v[102:105], v[220:223], v[176:179], v[102:105]
	v_mfma_f32_16x16x32_bf16 v[98:101], v[228:231], v[176:179], v[98:101]
	v_mfma_f32_16x16x32_bf16 v[86:89], v[220:223], v[184:187], v[86:89]
	v_mfma_f32_16x16x32_bf16 v[82:85], v[228:231], v[184:187], v[82:85]
	v_mfma_f32_16x16x32_bf16 v[70:73], v[220:223], v[200:203], v[70:73]
	v_mfma_f32_16x16x32_bf16 v[66:69], v[228:231], v[200:203], v[66:69]
	s_mov_b32 m0, s44
	v_lshl_add_u64 v[192:193], v[232:233], 0, s[92:93]
	s_barrier
	ds_read_b128 v[158:161], v171 offset:49152
	ds_read_b128 v[162:165], v171 offset:50176
	ds_read_b128 v[172:175], v171 offset:51200
	ds_read_b128 v[176:179], v171 offset:52224
	ds_read_b128 v[180:183], v171 offset:53248
	ds_read_b128 v[184:187], v171 offset:54272
	ds_read_b128 v[188:191], v171 offset:55296
	ds_read_b128 v[200:203], v171 offset:56320
	global_load_lds_dwordx4 v[192:193], off
	v_lshl_add_u64 v[192:193], v[234:235], 0, s[92:93]
	s_mov_b32 m0, s45
	s_nop 0
	global_load_lds_dwordx4 v[192:193], off
	s_barrier
; DI float shx(float v, int m) { return __int_as_float(__builtin_amdgcn_ds_bpermute((lane_now() ^ m) << 2, __float_as_int(v))); }
; DI int shx(int v, int m) { return __builtin_amdgcn_ds_bpermute((lane_now() ^ m) << 2, v); }
; #define PG8_STAGE(bufoff, gbase, voff) do { _Pragma("unroll") for (int _i = 0; _i < 2; ++_i) \
;         __builtin_amdgcn_global_load_lds((const unsigned*)((const char*)(gbase) + (voff)[_i]), (PG8_LAS unsigned*)(lds + (bufoff) + ldsw + _i * 8192), 16, 0, 0); } while (0)
; #define PG8_MMA(ai, bj, At, Bt) do { __builtin_amdgcn_s_setprio(1); _Pragma("unroll") for (int m = 0; m < 4; ++m) _Pragma("unroll") for (int n = 0; n < 2; ++n) _Pragma("unroll") for (int k = 0; k < 2; ++k) \
;         acc[ai][bj][m][n] = __builtin_amdgcn_mfma_f32_16x16x32_bf16(Bt[n][k], At[m][k], acc[ai][bj][m][n], 0, 0, 0); __builtin_amdgcn_s_setprio(0); } while (0)
; #define PG8_WAIT_V(n) asm volatile("s_waitcnt vmcnt(" #n ")" ::: "memory")
; #define PG8_WAIT_L(n) asm volatile("s_waitcnt lgkmcnt(" #n ")" ::: "memory")
; #define PG8_BAR __builtin_amdgcn_s_barrier()
; #define PG8_SCHED __builtin_amdgcn_sched_barrier(0)
; template <class Epi, class Sched>
; __device__ __forceinline__ void gemm_phase(PG8_LAS unsigned char* lds, const Gemm g, const Sched& S, const Epi& E, const int tid) {
;     ...
;             PG8_BAR; PG8_WAIT_L(0); PG8_MMA(1, 0, At, B0); PG8_BAR; PG8_SCHED;
;             PG8_STAGE(PG8_SB(1, 1), b3 + hstep, voffB);
;             PG8_WAIT_V(6); PG8_BAR; PG8_MMA(1, 1, At, B1); PG8_BAR;
;     __device__ __forceinline__ void operator()(const f32x4 (&acc)[2][2][4][2], const Unit& u, int wr, int wc, int fr, int fq) const {
;         const int row0 = u.pm * BM + wr * 64 + fr, col0 = u.pn * BM + wc * 32 + 8 * fq;
;         const bool hn = u.pn * BM < ncols_norm;
;         float part[2][4][2];
;         if (hn) {
; #pragma unroll
;             for (int ai = 0; ai < 2; ++ai)
; #pragma unroll
;                 for (int m = 0; m < 4; ++m)
; #pragma unroll
;                     for (int bj = 0; bj < 2; ++bj) { const f32x4 a = acc[ai][bj][m][0], b = acc[ai][bj][m][1];
;                         float sq = a[0] * a[0] + a[1] * a[1] + a[2] * a[2] + a[3] * a[3] + b[0] * b[0] + b[1] * b[1] + b[2] * b[2] + b[3] * b[3];
;                         sq += shx(sq, 16); sq += shx(sq, 32); part[ai][m][bj] = sq; }
	s_waitcnt lgkmcnt(0)
	s_waitcnt lgkmcnt(0)
	v_mfma_f32_16x16x32_bf16 v[62:65], v[142:145], v[158:161], v[62:65]
	v_mfma_f32_16x16x32_bf16 v[58:61], v[150:153], v[158:161], v[58:61]
	v_mfma_f32_16x16x32_bf16 v[46:49], v[142:145], v[172:175], v[46:49]
	v_mfma_f32_16x16x32_bf16 v[42:45], v[150:153], v[172:175], v[42:45]
	v_mfma_f32_16x16x32_bf16 v[30:33], v[142:145], v[180:183], v[30:33]
	v_mfma_f32_16x16x32_bf16 v[26:29], v[150:153], v[180:183], v[26:29]
	v_mfma_f32_16x16x32_bf16 v[14:17], v[142:145], v[188:191], v[14:17]
	v_mfma_f32_16x16x32_bf16 v[10:13], v[150:153], v[188:191], v[10:13]
	v_mfma_f32_16x16x32_bf16 v[62:65], v[146:149], v[162:165], v[62:65]
	v_mfma_f32_16x16x32_bf16 v[58:61], v[154:157], v[162:165], v[58:61]
	v_mfma_f32_16x16x32_bf16 v[46:49], v[146:149], v[176:179], v[46:49]
	v_mfma_f32_16x16x32_bf16 v[42:45], v[154:157], v[176:179], v[42:45]
	v_mfma_f32_16x16x32_bf16 v[30:33], v[146:149], v[184:187], v[30:33]
	v_mfma_f32_16x16x32_bf16 v[26:29], v[154:157], v[184:187], v[26:29]
	v_mfma_f32_16x16x32_bf16 v[14:17], v[146:149], v[200:203], v[14:17]
	v_mfma_f32_16x16x32_bf16 v[10:13], v[154:157], v[200:203], v[10:13]
	s_barrier
	s_add_u32 s8, s8, 0x40080
	s_addc_u32 s9, s9, 0
	s_add_i32 s56, s56, s77
	v_lshl_add_u64 v[142:143], s[8:9], 0, v[132:133]
	s_mov_b32 m0, s56
	s_nop 0
	global_load_lds_dwordx4 v[142:143], off
	v_lshl_add_u64 v[142:143], s[8:9], 0, v[136:137]
	s_add_i32 m0, s56, 0x2000
	s_nop 0
	global_load_lds_dwordx4 v[142:143], off
	s_waitcnt vmcnt(6)
	s_barrier
	v_mfma_f32_16x16x32_bf16 v[54:57], v[216:219], v[158:161], v[54:57]
	v_mfma_f32_16x16x32_bf16 v[50:53], v[224:227], v[158:161], v[50:53]
	v_mfma_f32_16x16x32_bf16 v[38:41], v[216:219], v[172:175], v[38:41]
	v_mfma_f32_16x16x32_bf16 v[34:37], v[224:227], v[172:175], v[34:37]
	v_mfma_f32_16x16x32_bf16 v[22:25], v[216:219], v[180:183], v[22:25]
	v_mfma_f32_16x16x32_bf16 v[18:21], v[224:227], v[180:183], v[18:21]
	v_mfma_f32_16x16x32_bf16 v[6:9], v[216:219], v[188:191], v[6:9]
	v_mfma_f32_16x16x32_bf16 v[2:5], v[224:227], v[188:191], v[2:5]
	v_mfma_f32_16x16x32_bf16 v[54:57], v[220:223], v[162:165], v[54:57]
	v_mfma_f32_16x16x32_bf16 v[50:53], v[228:231], v[162:165], v[50:53]
	v_mfma_f32_16x16x32_bf16 v[38:41], v[220:223], v[176:179], v[38:41]
	v_mfma_f32_16x16x32_bf16 v[34:37], v[228:231], v[176:179], v[34:37]
	v_mfma_f32_16x16x32_bf16 v[22:25], v[220:223], v[184:187], v[22:25]
	v_mfma_f32_16x16x32_bf16 v[18:21], v[228:231], v[184:187], v[18:21]
	v_mfma_f32_16x16x32_bf16 v[6:9], v[220:223], v[200:203], v[6:9]
	v_mfma_f32_16x16x32_bf16 v[2:5], v[228:231], v[200:203], v[2:5]
	s_add_i32 s65, s65, 2
	s_add_u32 s6, s6, 0x100
	s_addc_u32 s7, s7, 0
	s_add_u32 s62, s62, 0x100
	s_addc_u32 s63, s63, 0
	s_cmp_gt_u32 s65, 13
	s_barrier
	s_cbranch_scc0 .LBB0_701
	s_cmp_lt_i32 s68, 5
	v_mov_b32_e32 v161, 0x7fc00000
	s_cselect_b64 s[6:7], -1, 0
	s_cmp_gt_i32 s68, 4
	v_mov_b32_e32 v160, 0x7fc00000
	v_mov_b32_e32 v159, 0x7fc00000
	v_mov_b32_e32 v158, 0x7fc00000
	v_mov_b32_e32 v157, 0x7fc00000
	v_mov_b32_e32 v156, 0x7fc00000
	v_mov_b32_e32 v155, 0x7fc00000
	v_mov_b32_e32 v154, 0x7fc00000
	v_mov_b32_e32 v149, 0x7fc00000
	v_mov_b32_e32 v148, 0x7fc00000
	v_mov_b32_e32 v147, 0x7fc00000
	v_mov_b32_e32 v146, 0x7fc00000
	v_mov_b32_e32 v145, 0x7fc00000
	v_mov_b32_e32 v144, 0x7fc00000
	v_mov_b32_e32 v143, 0x7fc00000
	v_mov_b32_e32 v142, 0x7fc00000
	s_cbranch_scc1 .LBB0_706
	v_mov_b32_e32 v142, v204
	v_mov_b32_e32 v144, v119
	v_lshlrev_b32_e32 v142, 2, v142
	v_xor_b32_e32 v146, 64, v142
	v_mov_b32_e32 v142, v204
	v_mov_b32_e32 v145, v127
	v_lshlrev_b32_e32 v142, 2, v142
	v_xor_b32_e32 v147, 0x80, v142
	v_mov_b32_e32 v142, v118
	v_mov_b32_e32 v143, v126
	v_pk_mul_f32 v[144:145], v[144:145], v[144:145]
	v_mov_b32_e32 v148, v204
	v_pk_fma_f32 v[142:143], v[142:143], v[142:143], v[144:145]
	v_mov_b32_e32 v144, v120
	v_mov_b32_e32 v145, v128
	v_pk_fma_f32 v[142:143], v[144:145], v[144:145], v[142:143]
	v_mov_b32_e32 v144, v121
	v_mov_b32_e32 v145, v129
	v_pk_fma_f32 v[142:143], v[144:145], v[144:145], v[142:143]
	v_mov_b32_e32 v144, v114
	v_mov_b32_e32 v145, v122
	v_pk_fma_f32 v[142:143], v[144:145], v[144:145], v[142:143]
	v_mov_b32_e32 v144, v115
	v_mov_b32_e32 v145, v123
	v_pk_fma_f32 v[142:143], v[144:145], v[144:145], v[142:143]
	v_mov_b32_e32 v144, v116
	v_mov_b32_e32 v145, v124
	v_lshlrev_b32_e32 v148, 2, v148
	v_pk_fma_f32 v[142:143], v[144:145], v[144:145], v[142:143]
	v_mov_b32_e32 v144, v117
	v_mov_b32_e32 v145, v125
	v_xor_b32_e32 v148, 64, v148
	v_pk_fma_f32 v[142:143], v[144:145], v[144:145], v[142:143]
	ds_bpermute_b32 v145, v146, v143
	ds_bpermute_b32 v144, v148, v142
	v_mov_b32_e32 v149, v204
	v_mov_b32_e32 v146, v103
	v_lshlrev_b32_e32 v149, 2, v149
	v_xor_b32_e32 v149, 0x80, v149
	s_waitcnt lgkmcnt(0)
	v_pk_add_f32 v[142:143], v[142:143], v[144:145]
	ds_bpermute_b32 v145, v147, v143
	ds_bpermute_b32 v144, v149, v142
	v_mov_b32_e32 v147, v111
	v_pk_mul_f32 v[146:147], v[146:147], v[146:147]
	v_mov_b32_e32 v150, v204
	v_mov_b32_e32 v151, v204
	s_waitcnt lgkmcnt(0)
; DI float shx(float v, int m) { return __int_as_float(__builtin_amdgcn_ds_bpermute((lane_now() ^ m) << 2, __float_as_int(v))); }
; DI int shx(int v, int m) { return __builtin_amdgcn_ds_bpermute((lane_now() ^ m) << 2, v); }
;     __device__ __forceinline__ void operator()(const f32x4 (&acc)[2][2][4][2], const Unit& u, int wr, int wc, int fr, int fq) const {
;     ...
;                     for (int bj = 0; bj < 2; ++bj) { const f32x4 a = acc[ai][bj][m][0], b = acc[ai][bj][m][1];
;                         float sq = a[0] * a[0] + a[1] * a[1] + a[2] * a[2] + a[3] * a[3] + b[0] * b[0] + b[1] * b[1] + b[2] * b[2] + b[3] * b[3];
;                         sq += shx(sq, 16); sq += shx(sq, 32); part[ai][m][bj] = sq; }
	v_pk_add_f32 v[142:143], v[142:143], v[144:145]
	v_mov_b32_e32 v144, v204
	v_mov_b32_e32 v145, v110
	v_lshlrev_b32_e32 v144, 2, v144
	v_xor_b32_e32 v148, 64, v144
	v_mov_b32_e32 v144, v204
	v_mov_b32_e32 v152, v204
	v_lshlrev_b32_e32 v144, 2, v144
	v_xor_b32_e32 v149, 0x80, v144
	v_mov_b32_e32 v144, v102
	v_pk_fma_f32 v[144:145], v[144:145], v[144:145], v[146:147]
	v_mov_b32_e32 v146, v104
	v_mov_b32_e32 v147, v112
	v_pk_fma_f32 v[144:145], v[146:147], v[146:147], v[144:145]
	v_mov_b32_e32 v146, v105
	v_mov_b32_e32 v147, v113
	v_pk_fma_f32 v[144:145], v[146:147], v[146:147], v[144:145]
	v_mov_b32_e32 v146, v98
	v_mov_b32_e32 v147, v106
	v_pk_fma_f32 v[144:145], v[146:147], v[146:147], v[144:145]
	v_mov_b32_e32 v146, v99
	v_mov_b32_e32 v147, v107
	v_pk_fma_f32 v[144:145], v[146:147], v[146:147], v[144:145]
	v_mov_b32_e32 v146, v100
	v_mov_b32_e32 v147, v108
	v_lshlrev_b32_e32 v150, 2, v150
	v_pk_fma_f32 v[144:145], v[146:147], v[146:147], v[144:145]
	v_mov_b32_e32 v146, v101
	v_mov_b32_e32 v147, v109
	v_xor_b32_e32 v150, 64, v150
	v_pk_fma_f32 v[144:145], v[146:147], v[146:147], v[144:145]
	ds_bpermute_b32 v147, v148, v145
	ds_bpermute_b32 v146, v150, v144
	v_lshlrev_b32_e32 v151, 2, v151
	v_xor_b32_e32 v151, 0x80, v151
	v_mov_b32_e32 v148, v87
	v_mov_b32_e32 v153, v204
	s_waitcnt lgkmcnt(0)
	v_pk_add_f32 v[144:145], v[144:145], v[146:147]
	ds_bpermute_b32 v147, v149, v145
	ds_bpermute_b32 v146, v151, v144
	v_mov_b32_e32 v149, v95
	v_pk_mul_f32 v[148:149], v[148:149], v[148:149]
	v_mov_b32_e32 v154, v204
	v_mov_b32_e32 v155, v204
	s_waitcnt lgkmcnt(0)
	v_pk_add_f32 v[144:145], v[144:145], v[146:147]
	v_mov_b32_e32 v146, v204
	v_mov_b32_e32 v147, v94
	v_lshlrev_b32_e32 v146, 2, v146
	v_xor_b32_e32 v150, 64, v146
	v_mov_b32_e32 v146, v204
	v_mov_b32_e32 v156, v204
	v_lshlrev_b32_e32 v146, 2, v146
	v_xor_b32_e32 v151, 0x80, v146
	v_mov_b32_e32 v146, v86
	v_pk_fma_f32 v[146:147], v[146:147], v[146:147], v[148:149]
	v_mov_b32_e32 v148, v88
	v_mov_b32_e32 v149, v96
	v_pk_fma_f32 v[146:147], v[148:149], v[148:149], v[146:147]
	v_mov_b32_e32 v148, v89
	v_mov_b32_e32 v149, v97
	v_pk_fma_f32 v[146:147], v[148:149], v[148:149], v[146:147]
	v_mov_b32_e32 v148, v82
	v_mov_b32_e32 v149, v90
	v_pk_fma_f32 v[146:147], v[148:149], v[148:149], v[146:147]
	v_mov_b32_e32 v148, v83
	v_mov_b32_e32 v149, v91
	v_pk_fma_f32 v[146:147], v[148:149], v[148:149], v[146:147]
	v_mov_b32_e32 v148, v84
	v_mov_b32_e32 v149, v92
	v_lshlrev_b32_e32 v152, 2, v152
	v_pk_fma_f32 v[146:147], v[148:149], v[148:149], v[146:147]
	v_mov_b32_e32 v148, v85
	v_mov_b32_e32 v149, v93
	v_xor_b32_e32 v152, 64, v152
	v_pk_fma_f32 v[146:147], v[148:149], v[148:149], v[146:147]
	ds_bpermute_b32 v149, v150, v147
	ds_bpermute_b32 v148, v152, v146
	v_lshlrev_b32_e32 v153, 2, v153
	v_xor_b32_e32 v153, 0x80, v153
	v_mov_b32_e32 v150, v71
	v_mov_b32_e32 v157, v204
	s_waitcnt lgkmcnt(0)
	v_pk_add_f32 v[146:147], v[146:147], v[148:149]
	ds_bpermute_b32 v149, v151, v147
	ds_bpermute_b32 v148, v153, v146
	v_mov_b32_e32 v151, v79
	v_pk_mul_f32 v[150:151], v[150:151], v[150:151]
	v_mov_b32_e32 v158, v204
	v_mov_b32_e32 v159, v204
	s_waitcnt lgkmcnt(0)
	v_pk_add_f32 v[146:147], v[146:147], v[148:149]
	v_mov_b32_e32 v148, v204
	v_mov_b32_e32 v149, v78
	v_lshlrev_b32_e32 v148, 2, v148
	v_xor_b32_e32 v152, 64, v148
	v_mov_b32_e32 v148, v204
	v_mov_b32_e32 v160, v204
	v_lshlrev_b32_e32 v148, 2, v148
	v_xor_b32_e32 v153, 0x80, v148
	v_mov_b32_e32 v148, v70
	v_pk_fma_f32 v[148:149], v[148:149], v[148:149], v[150:151]
	v_mov_b32_e32 v150, v72
	v_mov_b32_e32 v151, v80
	v_pk_fma_f32 v[148:149], v[150:151], v[150:151], v[148:149]
	v_mov_b32_e32 v150, v73
	v_mov_b32_e32 v151, v81
	v_pk_fma_f32 v[148:149], v[150:151], v[150:151], v[148:149]
	v_mov_b32_e32 v150, v66
	v_mov_b32_e32 v151, v74
	v_pk_fma_f32 v[148:149], v[150:151], v[150:151], v[148:149]
	v_mov_b32_e32 v150, v67
	v_mov_b32_e32 v151, v75
	v_pk_fma_f32 v[148:149], v[150:151], v[150:151], v[148:149]
	v_mov_b32_e32 v150, v68
	v_mov_b32_e32 v151, v76
	v_lshlrev_b32_e32 v154, 2, v154
	v_pk_fma_f32 v[148:149], v[150:151], v[150:151], v[148:149]
	v_mov_b32_e32 v150, v69
	v_mov_b32_e32 v151, v77
	v_xor_b32_e32 v154, 64, v154
	v_pk_fma_f32 v[148:149], v[150:151], v[150:151], v[148:149]
	ds_bpermute_b32 v151, v152, v149
	ds_bpermute_b32 v150, v154, v148
	v_lshlrev_b32_e32 v155, 2, v155
	v_xor_b32_e32 v155, 0x80, v155
	v_mov_b32_e32 v152, v55
	v_mov_b32_e32 v161, v204
	s_waitcnt lgkmcnt(0)
	v_pk_add_f32 v[148:149], v[148:149], v[150:151]
	ds_bpermute_b32 v151, v153, v149
	ds_bpermute_b32 v150, v155, v148
	v_mov_b32_e32 v153, v63
	v_pk_mul_f32 v[152:153], v[152:153], v[152:153]
	s_waitcnt lgkmcnt(0)
	v_pk_add_f32 v[148:149], v[148:149], v[150:151]
	v_mov_b32_e32 v150, v204
	v_mov_b32_e32 v151, v62
	v_lshlrev_b32_e32 v150, 2, v150
	v_xor_b32_e32 v154, 64, v150
	v_mov_b32_e32 v150, v204
	s_nop 0
	v_lshlrev_b32_e32 v150, 2, v150
	v_xor_b32_e32 v155, 0x80, v150
	v_mov_b32_e32 v150, v54
	v_pk_fma_f32 v[150:151], v[150:151], v[150:151], v[152:153]
	v_mov_b32_e32 v152, v56
	v_mov_b32_e32 v153, v64
	v_pk_fma_f32 v[150:151], v[152:153], v[152:153], v[150:151]
	v_mov_b32_e32 v152, v57
	v_mov_b32_e32 v153, v65
	v_pk_fma_f32 v[150:151], v[152:153], v[152:153], v[150:151]
	v_mov_b32_e32 v152, v50
	v_mov_b32_e32 v153, v58
	v_pk_fma_f32 v[150:151], v[152:153], v[152:153], v[150:151]
	v_mov_b32_e32 v152, v51
	v_mov_b32_e32 v153, v59
	v_pk_fma_f32 v[150:151], v[152:153], v[152:153], v[150:151]
	v_mov_b32_e32 v152, v52
	v_mov_b32_e32 v153, v60
	v_lshlrev_b32_e32 v156, 2, v156
	v_pk_fma_f32 v[150:151], v[152:153], v[152:153], v[150:151]
	v_mov_b32_e32 v152, v53
	v_mov_b32_e32 v153, v61
	v_xor_b32_e32 v156, 64, v156
	v_pk_fma_f32 v[150:151], v[152:153], v[152:153], v[150:151]
	ds_bpermute_b32 v153, v154, v151
	ds_bpermute_b32 v152, v156, v150
	v_lshlrev_b32_e32 v157, 2, v157
	v_xor_b32_e32 v157, 0x80, v157
	v_mov_b32_e32 v154, v39
	s_waitcnt lgkmcnt(0)
; DI float shx(float v, int m) { return __int_as_float(__builtin_amdgcn_ds_bpermute((lane_now() ^ m) << 2, __float_as_int(v))); }
; DI int shx(int v, int m) { return __builtin_amdgcn_ds_bpermute((lane_now() ^ m) << 2, v); }
; #define PG8_LAS __attribute__((address_space(3)))
;     __device__ __forceinline__ void operator()(const f32x4 (&acc)[2][2][4][2], const Unit& u, int wr, int wc, int fr, int fq) const {
;     ...
;                     for (int bj = 0; bj < 2; ++bj) { const f32x4 a = acc[ai][bj][m][0], b = acc[ai][bj][m][1];
;                         float sq = a[0] * a[0] + a[1] * a[1] + a[2] * a[2] + a[3] * a[3] + b[0] * b[0] + b[1] * b[1] + b[2] * b[2] + b[3] * b[3];
;                         sq += shx(sq, 16); sq += shx(sq, 32); part[ai][m][bj] = sq; }
;             PG8_LAS float* mine = T + ((wr * 4 + wc) * 16) * 16 + fr;
;             if (fq == 0) {
; #pragma unroll
;                 for (int ai = 0; ai < 2; ++ai)
; #pragma unroll
;                     for (int m = 0; m < 4; ++m)
; #pragma unroll
;                         for (int bj = 0; bj < 2; ++bj) mine[((ai * 4 + m) * 2 + bj) * 16] = part[ai][m][bj];
;             }
	v_pk_add_f32 v[150:151], v[150:151], v[152:153]
	ds_bpermute_b32 v153, v155, v151
	ds_bpermute_b32 v152, v157, v150
	v_mov_b32_e32 v155, v47
	v_pk_mul_f32 v[154:155], v[154:155], v[154:155]
	s_waitcnt lgkmcnt(0)
	v_pk_add_f32 v[150:151], v[150:151], v[152:153]
	v_mov_b32_e32 v152, v204
	v_mov_b32_e32 v153, v46
	v_lshlrev_b32_e32 v152, 2, v152
	v_xor_b32_e32 v156, 64, v152
	v_mov_b32_e32 v152, v204
	s_nop 0
	v_lshlrev_b32_e32 v152, 2, v152
	v_xor_b32_e32 v157, 0x80, v152
	v_mov_b32_e32 v152, v38
	v_pk_fma_f32 v[152:153], v[152:153], v[152:153], v[154:155]
	v_mov_b32_e32 v154, v40
	v_mov_b32_e32 v155, v48
	v_pk_fma_f32 v[152:153], v[154:155], v[154:155], v[152:153]
	v_mov_b32_e32 v154, v41
	v_mov_b32_e32 v155, v49
	v_pk_fma_f32 v[152:153], v[154:155], v[154:155], v[152:153]
	v_mov_b32_e32 v154, v34
	v_mov_b32_e32 v155, v42
	v_pk_fma_f32 v[152:153], v[154:155], v[154:155], v[152:153]
	v_mov_b32_e32 v154, v35
	v_mov_b32_e32 v155, v43
	v_pk_fma_f32 v[152:153], v[154:155], v[154:155], v[152:153]
	v_mov_b32_e32 v154, v36
	v_mov_b32_e32 v155, v44
	v_lshlrev_b32_e32 v158, 2, v158
	v_pk_fma_f32 v[152:153], v[154:155], v[154:155], v[152:153]
	v_mov_b32_e32 v154, v37
	v_mov_b32_e32 v155, v45
	v_xor_b32_e32 v158, 64, v158
	v_pk_fma_f32 v[152:153], v[154:155], v[154:155], v[152:153]
	ds_bpermute_b32 v155, v156, v153
	ds_bpermute_b32 v154, v158, v152
	v_lshlrev_b32_e32 v159, 2, v159
	v_xor_b32_e32 v159, 0x80, v159
	v_mov_b32_e32 v156, v23
	s_waitcnt lgkmcnt(0)
	v_pk_add_f32 v[152:153], v[152:153], v[154:155]
	ds_bpermute_b32 v155, v157, v153
	ds_bpermute_b32 v154, v159, v152
	v_mov_b32_e32 v157, v31
	v_pk_mul_f32 v[156:157], v[156:157], v[156:157]
	s_waitcnt lgkmcnt(0)
	v_pk_add_f32 v[152:153], v[152:153], v[154:155]
	v_mov_b32_e32 v154, v204
	v_mov_b32_e32 v155, v30
	v_lshlrev_b32_e32 v154, 2, v154
	v_xor_b32_e32 v158, 64, v154
	v_mov_b32_e32 v154, v204
	s_nop 0
	v_lshlrev_b32_e32 v154, 2, v154
	v_xor_b32_e32 v159, 0x80, v154
	v_mov_b32_e32 v154, v22
	v_pk_fma_f32 v[154:155], v[154:155], v[154:155], v[156:157]
	v_mov_b32_e32 v156, v24
	v_mov_b32_e32 v157, v32
	v_pk_fma_f32 v[154:155], v[156:157], v[156:157], v[154:155]
	v_mov_b32_e32 v156, v25
	v_mov_b32_e32 v157, v33
	v_pk_fma_f32 v[154:155], v[156:157], v[156:157], v[154:155]
	v_mov_b32_e32 v156, v18
	v_mov_b32_e32 v157, v26
	v_pk_fma_f32 v[154:155], v[156:157], v[156:157], v[154:155]
	v_mov_b32_e32 v156, v19
	v_mov_b32_e32 v157, v27
	v_pk_fma_f32 v[154:155], v[156:157], v[156:157], v[154:155]
	v_mov_b32_e32 v156, v20
	v_mov_b32_e32 v157, v28
	v_lshlrev_b32_e32 v160, 2, v160
	v_pk_fma_f32 v[154:155], v[156:157], v[156:157], v[154:155]
	v_mov_b32_e32 v156, v21
	v_mov_b32_e32 v157, v29
	v_xor_b32_e32 v160, 64, v160
	v_pk_fma_f32 v[154:155], v[156:157], v[156:157], v[154:155]
	ds_bpermute_b32 v157, v158, v155
	ds_bpermute_b32 v156, v160, v154
	v_lshlrev_b32_e32 v161, 2, v161
	v_xor_b32_e32 v161, 0x80, v161
	v_mov_b32_e32 v160, v204
	s_waitcnt lgkmcnt(0)
	v_pk_add_f32 v[154:155], v[154:155], v[156:157]
	ds_bpermute_b32 v157, v159, v155
	ds_bpermute_b32 v156, v161, v154
	v_mov_b32_e32 v161, v204
	s_waitcnt lgkmcnt(0)
	v_pk_add_f32 v[162:163], v[154:155], v[156:157]
	v_mov_b32_e32 v154, v204
	v_mov_b32_e32 v156, v7
	v_lshlrev_b32_e32 v154, 2, v154
	v_xor_b32_e32 v158, 64, v154
	v_mov_b32_e32 v154, v204
	v_mov_b32_e32 v157, v15
	v_lshlrev_b32_e32 v154, 2, v154
	v_xor_b32_e32 v159, 0x80, v154
	v_mov_b32_e32 v154, v6
	v_mov_b32_e32 v155, v14
	v_pk_mul_f32 v[156:157], v[156:157], v[156:157]
	s_nop 0
	v_pk_fma_f32 v[154:155], v[154:155], v[154:155], v[156:157]
	v_mov_b32_e32 v156, v8
	v_mov_b32_e32 v157, v16
	v_pk_fma_f32 v[154:155], v[156:157], v[156:157], v[154:155]
	v_mov_b32_e32 v156, v9
	v_mov_b32_e32 v157, v17
	v_pk_fma_f32 v[154:155], v[156:157], v[156:157], v[154:155]
	v_mov_b32_e32 v156, v2
	v_mov_b32_e32 v157, v10
	v_pk_fma_f32 v[154:155], v[156:157], v[156:157], v[154:155]
	v_mov_b32_e32 v156, v3
	v_mov_b32_e32 v157, v11
	v_pk_fma_f32 v[154:155], v[156:157], v[156:157], v[154:155]
	v_mov_b32_e32 v156, v4
	v_mov_b32_e32 v157, v12
	v_lshlrev_b32_e32 v160, 2, v160
	v_pk_fma_f32 v[154:155], v[156:157], v[156:157], v[154:155]
	v_mov_b32_e32 v156, v5
	v_mov_b32_e32 v157, v13
	v_xor_b32_e32 v160, 64, v160
	v_pk_fma_f32 v[154:155], v[156:157], v[156:157], v[154:155]
	ds_bpermute_b32 v157, v158, v155
	ds_bpermute_b32 v156, v160, v154
	v_lshlrev_b32_e32 v161, 2, v161
	v_xor_b32_e32 v161, 0x80, v161
	s_waitcnt lgkmcnt(0)
	v_pk_add_f32 v[154:155], v[154:155], v[156:157]
	ds_bpermute_b32 v157, v159, v155
	ds_bpermute_b32 v156, v161, v154
	s_waitcnt lgkmcnt(0)
	v_pk_add_f32 v[164:165], v[154:155], v[156:157]
	s_and_saveexec_b64 s[8:9], s[2:3]
	s_cbranch_execz .LBB0_705
	ds_write2_b32 v168, v143, v142 offset1:16
	ds_write2_b32 v168, v145, v144 offset0:32 offset1:48
	ds_write2_b32 v168, v147, v146 offset0:64 offset1:80
	ds_write2_b32 v168, v149, v148 offset0:96 offset1:112
	ds_write2_b32 v168, v151, v150 offset0:128 offset1:144
	ds_write2_b32 v168, v153, v152 offset0:160 offset1:176
	ds_write2_b32 v168, v163, v162 offset0:192 offset1:208
	ds_write2_b32 v168, v165, v164 offset0:224 offset1:240

; template <class Epi, class Sched>
; __device__ __forceinline__ void gemm_phase(PG8_LAS unsigned char* lds, const Gemm g, const Sched& S, const Epi& E, const int tid) {
;     ...
;         const bool has_next = S.next(ui + 1, nxt);
;         const char* nA = has_next ? (const char*)g.A + a_tile_row(g, nxt.pm) * (size_t)K * 2 : cA; const char* nB = has_next ? (const char*)g.Bt + (size_t)nxt.pn * tstep : cB;
;         for (int t = 0; t < nt; t += 2) {
;             const bool last = (t == nt - 2);
;             const char* a1 = cA + (size_t)(t + 1) * kstep;
;             const char* a2 = last ? nA : cA + (size_t)(t + 2) * kstep; const char* b2 = last ? nB : cB + (size_t)(t + 2) * kstep;
;     ...
; #pragma unroll
;         for (int a = 0; a < 2; ++a)
; #pragma unroll
;             for (int b = 0; b < 2; ++b)
; #pragma unroll
;                 for (int m = 0; m < 4; ++m)
; #pragma unroll
;                     for (int n = 0; n < 2; ++n) acc[a][b][m][n] = (f32x4){0.f, 0.f, 0.f, 0.f};
.LBB0_737:
	s_ashr_i32 s13, s12, 31
	v_mov_b64_e32 v[2:3], 0x900
	s_lshl_b64 s[0:1], s[12:13], 19
	v_cmp_lt_i64_e32 vcc, s[14:15], v[2:3]
	s_add_u32 s14, s82, s0
	s_addc_u32 s15, s83, s1
	s_and_b64 s[0:1], vcc, exec
	s_cselect_b32 s0, s15, s7
	s_cselect_b32 s1, s14, s6
	s_ashr_i32 s11, s10, 31
	s_lshl_b64 s[18:19], s[10:11], 19
	s_add_u32 s18, s35, s18
	s_addc_u32 s19, s76, s19
	s_and_b64 s[56:57], vcc, exec
	s_cselect_b32 s11, s19, s9
	s_cselect_b32 s13, s18, s8
	s_add_u32 s6, s6, 0x40080
	s_addc_u32 s7, s7, 0
	s_add_u32 s62, s8, 0x100
	v_mov_b32_e32 v2, 0
	s_addc_u32 s63, s9, 0
	s_mov_b32 s89, -2
	v_mov_b32_e32 v3, v2
	v_mov_b32_e32 v4, v2
	v_mov_b32_e32 v5, v2
	v_mov_b32_e32 v6, v2
	v_mov_b32_e32 v7, v2
	v_mov_b32_e32 v8, v2
	v_mov_b32_e32 v9, v2
	v_mov_b32_e32 v18, v2
	v_mov_b32_e32 v19, v2
	v_mov_b32_e32 v20, v2
	v_mov_b32_e32 v21, v2
	v_mov_b32_e32 v22, v2
	v_mov_b32_e32 v23, v2
	v_mov_b32_e32 v24, v2
	v_mov_b32_e32 v25, v2
	v_mov_b32_e32 v34, v2
	v_mov_b32_e32 v35, v2
	v_mov_b32_e32 v36, v2
	v_mov_b32_e32 v37, v2
	v_mov_b32_e32 v38, v2
	v_mov_b32_e32 v39, v2
	v_mov_b32_e32 v40, v2
	v_mov_b32_e32 v41, v2
	v_mov_b32_e32 v50, v2
	v_mov_b32_e32 v51, v2
	v_mov_b32_e32 v52, v2
	v_mov_b32_e32 v53, v2
	v_mov_b32_e32 v54, v2
	v_mov_b32_e32 v55, v2
	v_mov_b32_e32 v56, v2
	v_mov_b32_e32 v57, v2
	v_mov_b32_e32 v10, v2
	v_mov_b32_e32 v11, v2
	v_mov_b32_e32 v12, v2
	v_mov_b32_e32 v13, v2
	v_mov_b32_e32 v14, v2
	v_mov_b32_e32 v15, v2
	s_waitcnt lgkmcnt(0)
	v_mov_b32_e32 v16, v2
	v_mov_b32_e32 v17, v2
	v_mov_b32_e32 v26, v2
	v_mov_b32_e32 v27, v2
	v_mov_b32_e32 v28, v2
	v_mov_b32_e32 v29, v2
	v_mov_b32_e32 v30, v2
	v_mov_b32_e32 v31, v2
	v_mov_b32_e32 v32, v2
	v_mov_b32_e32 v33, v2
	v_mov_b32_e32 v42, v2
	v_mov_b32_e32 v43, v2
	v_mov_b32_e32 v44, v2
	v_mov_b32_e32 v45, v2
	v_mov_b32_e32 v46, v2
	v_mov_b32_e32 v47, v2
	v_mov_b32_e32 v48, v2
	v_mov_b32_e32 v49, v2
	v_mov_b32_e32 v58, v2
	v_mov_b32_e32 v59, v2
	v_mov_b32_e32 v60, v2
	v_mov_b32_e32 v61, v2
	v_mov_b32_e32 v62, v2
	v_mov_b32_e32 v63, v2
	v_mov_b32_e32 v64, v2
	v_mov_b32_e32 v65, v2
	v_mov_b32_e32 v66, v2
	v_mov_b32_e32 v67, v2
	v_mov_b32_e32 v68, v2
	v_mov_b32_e32 v69, v2
	v_mov_b32_e32 v70, v2
	v_mov_b32_e32 v71, v2
	v_mov_b32_e32 v72, v2
	v_mov_b32_e32 v73, v2
	v_mov_b32_e32 v82, v2
	v_mov_b32_e32 v83, v2
	v_mov_b32_e32 v84, v2
	v_mov_b32_e32 v85, v2
	v_mov_b32_e32 v86, v2
	v_mov_b32_e32 v87, v2
	v_mov_b32_e32 v88, v2
	v_mov_b32_e32 v89, v2
	v_mov_b32_e32 v98, v2
	v_mov_b32_e32 v99, v2
	v_mov_b32_e32 v100, v2
	v_mov_b32_e32 v101, v2
	v_mov_b32_e32 v102, v2
	v_mov_b32_e32 v103, v2
	v_mov_b32_e32 v104, v2
	v_mov_b32_e32 v105, v2
	v_mov_b32_e32 v114, v2
	v_mov_b32_e32 v115, v2
	v_mov_b32_e32 v116, v2
	v_mov_b32_e32 v117, v2
	v_mov_b32_e32 v118, v2
	v_mov_b32_e32 v119, v2
	v_mov_b32_e32 v120, v2
	v_mov_b32_e32 v121, v2
	v_mov_b32_e32 v74, v2
	v_mov_b32_e32 v75, v2
	v_mov_b32_e32 v76, v2
	v_mov_b32_e32 v77, v2
	v_mov_b32_e32 v78, v2
	v_mov_b32_e32 v79, v2
	v_mov_b32_e32 v80, v2
	v_mov_b32_e32 v81, v2
	v_mov_b32_e32 v90, v2
	v_mov_b32_e32 v91, v2
	v_mov_b32_e32 v92, v2
	v_mov_b32_e32 v93, v2
	v_mov_b32_e32 v94, v2
	v_mov_b32_e32 v95, v2
	v_mov_b32_e32 v96, v2
	v_mov_b32_e32 v97, v2
	v_mov_b32_e32 v106, v2
	v_mov_b32_e32 v107, v2
	v_mov_b32_e32 v108, v2
	v_mov_b32_e32 v109, v2
	v_mov_b32_e32 v110, v2
	v_mov_b32_e32 v111, v2
	v_mov_b32_e32 v112, v2
	v_mov_b32_e32 v113, v2
	v_mov_b32_e32 v122, v2
	v_mov_b32_e32 v123, v2
	v_mov_b32_e32 v124, v2
	v_mov_b32_e32 v125, v2
	v_mov_b32_e32 v126, v2
	v_mov_b32_e32 v127, v2
	v_mov_b32_e32 v128, v2
	v_mov_b32_e32 v129, v2
	v_readlane_b32 s101, v254, 14
	s_bitcmp1_b32 s101, 0
	s_cbranch_scc0 .Lprio_skip5
	s_setprio 1

; #define PG8_STAGE(bufoff, gbase, voff) do { _Pragma("unroll") for (int _i = 0; _i < 2; ++_i) \
;         __builtin_amdgcn_global_load_lds((const unsigned*)((const char*)(gbase) + (voff)[_i]), (PG8_LAS unsigned*)(lds + (bufoff) + ldsw + _i * 8192), 16, 0, 0); } while (0)
; #define PG8_LDA(dst, b, h) do { _Pragma("unroll") for (int m = 0; m < 4; ++m) _Pragma("unroll") for (int k = 0; k < 2; ++k) dst[m][k] = *(const PG8_LAS bf16x8*)(lds + PG8_SA(b, h) + aoff + m * 2048 + k * 1024); } while (0)
; #define PG8_LDB(dst, b, h) do { _Pragma("unroll") for (int n = 0; n < 2; ++n) _Pragma("unroll") for (int k = 0; k < 2; ++k) dst[n][k] = *(const PG8_LAS bf16x8*)(lds + PG8_SB(b, h) + boff + n * 2048 + k * 1024); } while (0)
; #define PG8_MMA(ai, bj, At, Bt) do { __builtin_amdgcn_s_setprio(1); _Pragma("unroll") for (int m = 0; m < 4; ++m) _Pragma("unroll") for (int n = 0; n < 2; ++n) _Pragma("unroll") for (int k = 0; k < 2; ++k) \
;         acc[ai][bj][m][n] = __builtin_amdgcn_mfma_f32_16x16x32_bf16(Bt[n][k], At[m][k], acc[ai][bj][m][n], 0, 0, 0); __builtin_amdgcn_s_setprio(0); } while (0)
; #define PG8_WAIT_L(n) asm volatile("s_waitcnt lgkmcnt(" #n ")" ::: "memory")
; #define PG8_BAR __builtin_amdgcn_s_barrier()
; #define PG8_SCHED __builtin_amdgcn_sched_barrier(0)
; template <class Epi, class Sched>
; __device__ __forceinline__ void gemm_phase(PG8_LAS unsigned char* lds, const Gemm g, const Sched& S, const Epi& E, const int tid) {
;     ...
;         for (int t = 0; t < nt; t += 2) {
;             const bool last = (t == nt - 2);
;             const char* a1 = cA + (size_t)(t + 1) * kstep;
;             const char* a2 = last ? nA : cA + (size_t)(t + 2) * kstep; const char* b2 = last ? nB : cB + (size_t)(t + 2) * kstep;
;             const char* a3 = a2 + kstep; const char* b3 = b2 + kstep;
;             if (last && has_next) S.a_ready(nxt);
;             PG8_LDB(B0, 0, 0); PG8_SCHED; PG8_LDA(At, 0, 0); PG8_STAGE(PG8_SA(1, 1), a1 + hstep, voffA);
;             PG8_WAIT_L(8); PG8_BAR; PG8_WAIT_L(0); PG8_MMA(0, 0, At, B0); PG8_BAR; PG8_SCHED;
;             PG8_LDB(B1, 0, 1); PG8_STAGE(PG8_SB(0, 0), b2, voffB);
;             PG8_BAR; PG8_WAIT_L(0); PG8_MMA(0, 1, At, B1); PG8_BAR;
;             PG8_LDA(At, 0, 1); PG8_STAGE(PG8_SA(0, 0), a2, voffA);
;             PG8_BAR; PG8_WAIT_L(0); PG8_MMA(1, 0, At, B0); PG8_BAR; PG8_SCHED;
.LBB0_738:
	s_add_u32 s8, s6, 0xfffc0080
	s_addc_u32 s9, s7, -1
	s_add_i32 s90, 0, 0x10000
	v_add_u32_e32 v154, s90, v167
	ds_read_b128 v[142:145], v154
	ds_read_b128 v[146:149], v154 offset:1024
	ds_read_b128 v[150:153], v154 offset:2048
	ds_read_b128 v[154:157], v154 offset:3072
	s_cmp_eq_u32 s89, 12
	s_cselect_b32 s57, s0, s9
	s_cselect_b32 s56, s1, s8
	s_cselect_b32 s9, s11, s63
	s_cselect_b32 s8, s13, s62
	v_lshl_add_u64 v[192:193], s[6:7], 0, v[138:139]
	s_add_i32 m0, s69, 0xc000
	ds_read_b128 v[158:161], v171
	ds_read_b128 v[162:165], v171 offset:1024
	ds_read_b128 v[172:175], v171 offset:2048
	ds_read_b128 v[176:179], v171 offset:3072
	ds_read_b128 v[180:183], v171 offset:4096
	ds_read_b128 v[184:187], v171 offset:5120
	ds_read_b128 v[188:191], v171 offset:6144
	ds_read_b128 v[200:203], v171 offset:7168
	global_load_lds_dwordx4 v[192:193], off
	v_lshl_add_u64 v[192:193], s[6:7], 0, v[140:141]
	s_add_i32 m0, s69, 0xe000
	s_nop 0
	global_load_lds_dwordx4 v[192:193], off
	s_waitcnt lgkmcnt(8)
	s_barrier
	s_waitcnt lgkmcnt(0)
	s_waitcnt lgkmcnt(0)
	v_mfma_f32_16x16x32_bf16 v[126:129], v[142:145], v[158:161], v[126:129]
	v_mfma_f32_16x16x32_bf16 v[122:125], v[150:153], v[158:161], v[122:125]
	v_mfma_f32_16x16x32_bf16 v[110:113], v[142:145], v[172:175], v[110:113]
	v_mfma_f32_16x16x32_bf16 v[106:109], v[150:153], v[172:175], v[106:109]
	v_mfma_f32_16x16x32_bf16 v[94:97], v[142:145], v[180:183], v[94:97]
	v_mfma_f32_16x16x32_bf16 v[90:93], v[150:153], v[180:183], v[90:93]
	v_mfma_f32_16x16x32_bf16 v[78:81], v[142:145], v[188:191], v[78:81]
	v_mfma_f32_16x16x32_bf16 v[74:77], v[150:153], v[188:191], v[74:77]
	v_mfma_f32_16x16x32_bf16 v[126:129], v[146:149], v[162:165], v[126:129]
	v_mfma_f32_16x16x32_bf16 v[122:125], v[154:157], v[162:165], v[122:125]
	v_mfma_f32_16x16x32_bf16 v[110:113], v[146:149], v[176:179], v[110:113]
	v_mfma_f32_16x16x32_bf16 v[106:109], v[154:157], v[176:179], v[106:109]
	v_mfma_f32_16x16x32_bf16 v[94:97], v[146:149], v[184:187], v[94:97]
	v_mfma_f32_16x16x32_bf16 v[90:93], v[154:157], v[184:187], v[90:93]
	v_mfma_f32_16x16x32_bf16 v[78:81], v[146:149], v[200:203], v[78:81]
	v_mfma_f32_16x16x32_bf16 v[74:77], v[154:157], v[200:203], v[74:77]
	s_barrier
	s_add_i32 s94, 0, 0x14000
	v_add_u32_e32 v192, s94, v167
	s_add_i32 s90, s90, s77
	ds_read_b128 v[216:219], v192
	ds_read_b128 v[220:223], v192 offset:1024
	ds_read_b128 v[224:227], v192 offset:2048
	ds_read_b128 v[228:231], v192 offset:3072
	v_lshl_add_u64 v[192:193], s[8:9], 0, v[132:133]
	s_mov_b32 m0, s90
	v_lshl_add_u64 v[194:195], s[8:9], 0, v[136:137]
	global_load_lds_dwordx4 v[192:193], off
	s_add_i32 m0, s90, 0x2000
	s_nop 0
	global_load_lds_dwordx4 v[194:195], off
	s_barrier
	s_waitcnt lgkmcnt(0)
	s_waitcnt lgkmcnt(0)
	v_mfma_f32_16x16x32_bf16 v[118:121], v[216:219], v[158:161], v[118:121]
	v_mfma_f32_16x16x32_bf16 v[114:117], v[224:227], v[158:161], v[114:117]
	v_mfma_f32_16x16x32_bf16 v[102:105], v[216:219], v[172:175], v[102:105]
	v_mfma_f32_16x16x32_bf16 v[98:101], v[224:227], v[172:175], v[98:101]
	v_mfma_f32_16x16x32_bf16 v[86:89], v[216:219], v[180:183], v[86:89]
	v_mfma_f32_16x16x32_bf16 v[82:85], v[224:227], v[180:183], v[82:85]
	v_mfma_f32_16x16x32_bf16 v[70:73], v[216:219], v[188:191], v[70:73]
	v_mfma_f32_16x16x32_bf16 v[66:69], v[224:227], v[188:191], v[66:69]
	v_mfma_f32_16x16x32_bf16 v[118:121], v[220:223], v[162:165], v[118:121]
	v_mfma_f32_16x16x32_bf16 v[114:117], v[228:231], v[162:165], v[114:117]
	v_mfma_f32_16x16x32_bf16 v[102:105], v[220:223], v[176:179], v[102:105]
	v_mfma_f32_16x16x32_bf16 v[98:101], v[228:231], v[176:179], v[98:101]
	v_mfma_f32_16x16x32_bf16 v[86:89], v[220:223], v[184:187], v[86:89]
	v_mfma_f32_16x16x32_bf16 v[82:85], v[228:231], v[184:187], v[82:85]
	v_mfma_f32_16x16x32_bf16 v[70:73], v[220:223], v[200:203], v[70:73]
	v_mfma_f32_16x16x32_bf16 v[66:69], v[228:231], v[200:203], v[66:69]
	s_mov_b32 m0, s69
	v_lshl_add_u64 v[232:233], s[56:57], 0, v[130:131]
	s_barrier
	ds_read_b128 v[158:161], v171 offset:16384
	ds_read_b128 v[162:165], v171 offset:17408
	ds_read_b128 v[172:175], v171 offset:18432
	ds_read_b128 v[176:179], v171 offset:19456
	ds_read_b128 v[180:183], v171 offset:20480
	ds_read_b128 v[184:187], v171 offset:21504
	ds_read_b128 v[188:191], v171 offset:22528
	ds_read_b128 v[200:203], v171 offset:23552
	global_load_lds_dwordx4 v[232:233], off
	v_lshl_add_u64 v[234:235], s[56:57], 0, v[134:135]
	s_mov_b32 m0, s73
	s_nop 0
	global_load_lds_dwordx4 v[234:235], off
	s_barrier
	s_waitcnt lgkmcnt(0)
	s_waitcnt lgkmcnt(0)
	v_mfma_f32_16x16x32_bf16 v[62:65], v[142:145], v[158:161], v[62:65]
	v_mfma_f32_16x16x32_bf16 v[58:61], v[150:153], v[158:161], v[58:61]
	v_mfma_f32_16x16x32_bf16 v[46:49], v[142:145], v[172:175], v[46:49]
	v_mfma_f32_16x16x32_bf16 v[42:45], v[150:153], v[172:175], v[42:45]
	v_mfma_f32_16x16x32_bf16 v[30:33], v[142:145], v[180:183], v[30:33]
	v_mfma_f32_16x16x32_bf16 v[26:29], v[150:153], v[180:183], v[26:29]
	v_mfma_f32_16x16x32_bf16 v[14:17], v[142:145], v[188:191], v[14:17]
	v_mfma_f32_16x16x32_bf16 v[10:13], v[150:153], v[188:191], v[10:13]
	v_mfma_f32_16x16x32_bf16 v[62:65], v[146:149], v[162:165], v[62:65]
	v_mfma_f32_16x16x32_bf16 v[58:61], v[154:157], v[162:165], v[58:61]
	v_mfma_f32_16x16x32_bf16 v[46:49], v[146:149], v[176:179], v[46:49]
	v_mfma_f32_16x16x32_bf16 v[42:45], v[154:157], v[176:179], v[42:45]
	v_mfma_f32_16x16x32_bf16 v[30:33], v[146:149], v[184:187], v[30:33]
	v_mfma_f32_16x16x32_bf16 v[26:29], v[154:157], v[184:187], v[26:29]
	v_mfma_f32_16x16x32_bf16 v[14:17], v[146:149], v[200:203], v[14:17]
	v_mfma_f32_16x16x32_bf16 v[10:13], v[154:157], v[200:203], v[10:13]
	s_barrier
; #define PG8_STAGE(bufoff, gbase, voff) do { _Pragma("unroll") for (int _i = 0; _i < 2; ++_i) \
;         __builtin_amdgcn_global_load_lds((const unsigned*)((const char*)(gbase) + (voff)[_i]), (PG8_LAS unsigned*)(lds + (bufoff) + ldsw + _i * 8192), 16, 0, 0); } while (0)
; #define PG8_LDA(dst, b, h) do { _Pragma("unroll") for (int m = 0; m < 4; ++m) _Pragma("unroll") for (int k = 0; k < 2; ++k) dst[m][k] = *(const PG8_LAS bf16x8*)(lds + PG8_SA(b, h) + aoff + m * 2048 + k * 1024); } while (0)
; #define PG8_LDB(dst, b, h) do { _Pragma("unroll") for (int n = 0; n < 2; ++n) _Pragma("unroll") for (int k = 0; k < 2; ++k) dst[n][k] = *(const PG8_LAS bf16x8*)(lds + PG8_SB(b, h) + boff + n * 2048 + k * 1024); } while (0)
; #define PG8_MMA(ai, bj, At, Bt) do { __builtin_amdgcn_s_setprio(1); _Pragma("unroll") for (int m = 0; m < 4; ++m) _Pragma("unroll") for (int n = 0; n < 2; ++n) _Pragma("unroll") for (int k = 0; k < 2; ++k) \
;         acc[ai][bj][m][n] = __builtin_amdgcn_mfma_f32_16x16x32_bf16(Bt[n][k], At[m][k], acc[ai][bj][m][n], 0, 0, 0); __builtin_amdgcn_s_setprio(0); } while (0)
; #define PG8_WAIT_V(n) asm volatile("s_waitcnt vmcnt(" #n ")" ::: "memory")
; #define PG8_WAIT_L(n) asm volatile("s_waitcnt lgkmcnt(" #n ")" ::: "memory")
; #define PG8_BAR __builtin_amdgcn_s_barrier()
; #define PG8_SCHED __builtin_amdgcn_sched_barrier(0)
; template <class Epi, class Sched>
; __device__ __forceinline__ void gemm_phase(PG8_LAS unsigned char* lds, const Gemm g, const Sched& S, const Epi& E, const int tid) {
;     ...
;             PG8_STAGE(PG8_SB(0, 1), b2 + hstep, voffB);
;             PG8_WAIT_V(6); PG8_BAR; PG8_MMA(1, 1, At, B1); PG8_BAR;
;             PG8_LDB(B0, 1, 0); PG8_SCHED; PG8_LDA(At, 1, 0); PG8_STAGE(PG8_SA(0, 1), a2 + hstep, voffA);
;             PG8_WAIT_L(8); PG8_BAR; PG8_WAIT_L(0); PG8_MMA(0, 0, At, B0); PG8_BAR; PG8_SCHED;
;             PG8_LDB(B1, 1, 1); PG8_STAGE(PG8_SB(1, 0), b3, voffB);
;             PG8_BAR; PG8_WAIT_L(0); PG8_MMA(0, 1, At, B1); PG8_BAR;
;             PG8_LDA(At, 1, 1); PG8_STAGE(PG8_SA(1, 0), a3, voffA);
	s_add_u32 s90, s8, 0x40000
	s_addc_u32 s91, s9, 0
	s_add_i32 s94, s94, s77
	v_lshl_add_u64 v[142:143], s[90:91], 0, v[132:133]
	s_mov_b32 m0, s94
	s_nop 0
	global_load_lds_dwordx4 v[142:143], off
	v_lshl_add_u64 v[142:143], s[90:91], 0, v[136:137]
	s_add_i32 m0, s94, 0x2000
	s_nop 0
	global_load_lds_dwordx4 v[142:143], off
	s_waitcnt vmcnt(6)
	s_barrier
	v_mfma_f32_16x16x32_bf16 v[54:57], v[216:219], v[158:161], v[54:57]
	v_mfma_f32_16x16x32_bf16 v[50:53], v[224:227], v[158:161], v[50:53]
	v_mfma_f32_16x16x32_bf16 v[38:41], v[216:219], v[172:175], v[38:41]
	v_mfma_f32_16x16x32_bf16 v[34:37], v[224:227], v[172:175], v[34:37]
	v_mfma_f32_16x16x32_bf16 v[22:25], v[216:219], v[180:183], v[22:25]
	v_mfma_f32_16x16x32_bf16 v[18:21], v[224:227], v[180:183], v[18:21]
	v_mfma_f32_16x16x32_bf16 v[6:9], v[216:219], v[188:191], v[6:9]
	v_mfma_f32_16x16x32_bf16 v[2:5], v[224:227], v[188:191], v[2:5]
	v_mfma_f32_16x16x32_bf16 v[54:57], v[220:223], v[162:165], v[54:57]
	v_mfma_f32_16x16x32_bf16 v[50:53], v[228:231], v[162:165], v[50:53]
	v_mfma_f32_16x16x32_bf16 v[38:41], v[220:223], v[176:179], v[38:41]
	v_mfma_f32_16x16x32_bf16 v[34:37], v[228:231], v[176:179], v[34:37]
	v_mfma_f32_16x16x32_bf16 v[22:25], v[220:223], v[184:187], v[22:25]
	v_mfma_f32_16x16x32_bf16 v[18:21], v[228:231], v[184:187], v[18:21]
	v_mfma_f32_16x16x32_bf16 v[6:9], v[220:223], v[200:203], v[6:9]
	v_mfma_f32_16x16x32_bf16 v[2:5], v[228:231], v[200:203], v[2:5]
	s_add_i32 s90, 0, 0x18000
	v_add_u32_e32 v154, s90, v167
	s_barrier
	ds_read_b128 v[142:145], v154
	ds_read_b128 v[146:149], v154 offset:1024
	ds_read_b128 v[150:153], v154 offset:2048
	ds_read_b128 v[154:157], v154 offset:3072
	s_add_u32 s56, s56, 0x40000
	s_addc_u32 s57, s57, 0
	s_mov_b32 m0, s84
	v_lshl_add_u64 v[216:217], s[56:57], 0, v[130:131]
	ds_read_b128 v[158:161], v171 offset:32768
	ds_read_b128 v[162:165], v171 offset:33792
	ds_read_b128 v[172:175], v171 offset:34816
	ds_read_b128 v[176:179], v171 offset:35840
	ds_read_b128 v[180:183], v171 offset:36864
	ds_read_b128 v[184:187], v171 offset:37888
	ds_read_b128 v[188:191], v171 offset:38912
	ds_read_b128 v[200:203], v171 offset:39936
	global_load_lds_dwordx4 v[216:217], off
	v_lshl_add_u64 v[216:217], s[56:57], 0, v[134:135]
	s_mov_b32 m0, s88
	s_nop 0
	global_load_lds_dwordx4 v[216:217], off
	s_waitcnt lgkmcnt(8)
	s_barrier
	s_waitcnt lgkmcnt(0)
	s_waitcnt lgkmcnt(0)
	v_mfma_f32_16x16x32_bf16 v[126:129], v[142:145], v[158:161], v[126:129]
	v_mfma_f32_16x16x32_bf16 v[122:125], v[150:153], v[158:161], v[122:125]
	v_mfma_f32_16x16x32_bf16 v[110:113], v[142:145], v[172:175], v[110:113]
	v_mfma_f32_16x16x32_bf16 v[106:109], v[150:153], v[172:175], v[106:109]
	v_mfma_f32_16x16x32_bf16 v[94:97], v[142:145], v[180:183], v[94:97]
	v_mfma_f32_16x16x32_bf16 v[90:93], v[150:153], v[180:183], v[90:93]
	v_mfma_f32_16x16x32_bf16 v[78:81], v[142:145], v[188:191], v[78:81]
	v_mfma_f32_16x16x32_bf16 v[74:77], v[150:153], v[188:191], v[74:77]
	v_mfma_f32_16x16x32_bf16 v[126:129], v[146:149], v[162:165], v[126:129]
	v_mfma_f32_16x16x32_bf16 v[122:125], v[154:157], v[162:165], v[122:125]
	v_mfma_f32_16x16x32_bf16 v[110:113], v[146:149], v[176:179], v[110:113]
	v_mfma_f32_16x16x32_bf16 v[106:109], v[154:157], v[176:179], v[106:109]
	v_mfma_f32_16x16x32_bf16 v[94:97], v[146:149], v[184:187], v[94:97]
	v_mfma_f32_16x16x32_bf16 v[90:93], v[154:157], v[184:187], v[90:93]
	v_mfma_f32_16x16x32_bf16 v[78:81], v[146:149], v[200:203], v[78:81]
	v_mfma_f32_16x16x32_bf16 v[74:77], v[154:157], v[200:203], v[74:77]
	s_barrier
	s_add_i32 s56, 0, 0x1c000
	s_add_i32 s57, s90, s77
	v_add_u32_e32 v196, s56, v167
	v_lshl_add_u64 v[192:193], v[192:193], 0, s[92:93]
	s_mov_b32 m0, s57
	ds_read_b128 v[216:219], v196
	ds_read_b128 v[220:223], v196 offset:1024
	ds_read_b128 v[224:227], v196 offset:2048
	ds_read_b128 v[228:231], v196 offset:3072
	global_load_lds_dwordx4 v[192:193], off
	v_lshl_add_u64 v[192:193], v[194:195], 0, s[92:93]
	s_add_i32 m0, s57, 0x2000
	s_nop 0
	global_load_lds_dwordx4 v[192:193], off
	s_barrier
	s_waitcnt lgkmcnt(0)
	s_waitcnt lgkmcnt(0)
	v_mfma_f32_16x16x32_bf16 v[118:121], v[216:219], v[158:161], v[118:121]
	v_mfma_f32_16x16x32_bf16 v[114:117], v[224:227], v[158:161], v[114:117]
	v_mfma_f32_16x16x32_bf16 v[102:105], v[216:219], v[172:175], v[102:105]
	v_mfma_f32_16x16x32_bf16 v[98:101], v[224:227], v[172:175], v[98:101]
	v_mfma_f32_16x16x32_bf16 v[86:89], v[216:219], v[180:183], v[86:89]
	v_mfma_f32_16x16x32_bf16 v[82:85], v[224:227], v[180:183], v[82:85]
	v_mfma_f32_16x16x32_bf16 v[70:73], v[216:219], v[188:191], v[70:73]
	v_mfma_f32_16x16x32_bf16 v[66:69], v[224:227], v[188:191], v[66:69]
	v_mfma_f32_16x16x32_bf16 v[118:121], v[220:223], v[162:165], v[118:121]
	v_mfma_f32_16x16x32_bf16 v[114:117], v[228:231], v[162:165], v[114:117]
	v_mfma_f32_16x16x32_bf16 v[102:105], v[220:223], v[176:179], v[102:105]
	v_mfma_f32_16x16x32_bf16 v[98:101], v[228:231], v[176:179], v[98:101]
	v_mfma_f32_16x16x32_bf16 v[86:89], v[220:223], v[184:187], v[86:89]
	v_mfma_f32_16x16x32_bf16 v[82:85], v[228:231], v[184:187], v[82:85]
	v_mfma_f32_16x16x32_bf16 v[70:73], v[220:223], v[200:203], v[70:73]
	v_mfma_f32_16x16x32_bf16 v[66:69], v[228:231], v[200:203], v[66:69]
	s_mov_b32 m0, s44
	v_lshl_add_u64 v[192:193], v[232:233], 0, s[92:93]
	s_barrier
	ds_read_b128 v[158:161], v171 offset:49152
	ds_read_b128 v[162:165], v171 offset:50176
	ds_read_b128 v[172:175], v171 offset:51200
	ds_read_b128 v[176:179], v171 offset:52224
	ds_read_b128 v[180:183], v171 offset:53248
	ds_read_b128 v[184:187], v171 offset:54272
	ds_read_b128 v[188:191], v171 offset:55296
	ds_read_b128 v[200:203], v171 offset:56320
	global_load_lds_dwordx4 v[192:193], off
	v_lshl_add_u64 v[192:193], v[234:235], 0, s[92:93]
	s_mov_b32 m0, s45
	s_nop 0
	global_load_lds_dwordx4 v[192:193], off
	s_barrier
; DI float shx(float v, int m) { return __int_as_float(__builtin_amdgcn_ds_bpermute((lane_now() ^ m) << 2, __float_as_int(v))); }
; DI int shx(int v, int m) { return __builtin_amdgcn_ds_bpermute((lane_now() ^ m) << 2, v); }
; #define PG8_STAGE(bufoff, gbase, voff) do { _Pragma("unroll") for (int _i = 0; _i < 2; ++_i) \
;         __builtin_amdgcn_global_load_lds((const unsigned*)((const char*)(gbase) + (voff)[_i]), (PG8_LAS unsigned*)(lds + (bufoff) + ldsw + _i * 8192), 16, 0, 0); } while (0)
; #define PG8_MMA(ai, bj, At, Bt) do { __builtin_amdgcn_s_setprio(1); _Pragma("unroll") for (int m = 0; m < 4; ++m) _Pragma("unroll") for (int n = 0; n < 2; ++n) _Pragma("unroll") for (int k = 0; k < 2; ++k) \
;         acc[ai][bj][m][n] = __builtin_amdgcn_mfma_f32_16x16x32_bf16(Bt[n][k], At[m][k], acc[ai][bj][m][n], 0, 0, 0); __builtin_amdgcn_s_setprio(0); } while (0)
; #define PG8_WAIT_V(n) asm volatile("s_waitcnt vmcnt(" #n ")" ::: "memory")
; #define PG8_WAIT_L(n) asm volatile("s_waitcnt lgkmcnt(" #n ")" ::: "memory")
; #define PG8_BAR __builtin_amdgcn_s_barrier()
; #define PG8_SCHED __builtin_amdgcn_sched_barrier(0)
; template <class Epi, class Sched>
; __device__ __forceinline__ void gemm_phase(PG8_LAS unsigned char* lds, const Gemm g, const Sched& S, const Epi& E, const int tid) {
;     ...
;             PG8_BAR; PG8_WAIT_L(0); PG8_MMA(1, 0, At, B0); PG8_BAR; PG8_SCHED;
;             PG8_STAGE(PG8_SB(1, 1), b3 + hstep, voffB);
;             PG8_WAIT_V(6); PG8_BAR; PG8_MMA(1, 1, At, B1); PG8_BAR;
;     __device__ __forceinline__ void operator()(const f32x4 (&acc)[2][2][4][2], const Unit& u, int wr, int wc, int fr, int fq) const {
;         const int row0 = u.pm * BM + wr * 64 + fr, col0 = u.pn * BM + wc * 32 + 8 * fq;
;         const bool hn = u.pn * BM < ncols_norm;
;         float part[2][4][2];
;         if (hn) {
; #pragma unroll
;             for (int ai = 0; ai < 2; ++ai)
; #pragma unroll
;                 for (int m = 0; m < 4; ++m)
; #pragma unroll
;                     for (int bj = 0; bj < 2; ++bj) { const f32x4 a = acc[ai][bj][m][0], b = acc[ai][bj][m][1];
;                         float sq = a[0] * a[0] + a[1] * a[1] + a[2] * a[2] + a[3] * a[3] + b[0] * b[0] + b[1] * b[1] + b[2] * b[2] + b[3] * b[3];
;                         sq += shx(sq, 16); sq += shx(sq, 32); part[ai][m][bj] = sq; }
	s_waitcnt lgkmcnt(0)
	s_waitcnt lgkmcnt(0)
	v_mfma_f32_16x16x32_bf16 v[62:65], v[142:145], v[158:161], v[62:65]
	v_mfma_f32_16x16x32_bf16 v[58:61], v[150:153], v[158:161], v[58:61]
	v_mfma_f32_16x16x32_bf16 v[46:49], v[142:145], v[172:175], v[46:49]
	v_mfma_f32_16x16x32_bf16 v[42:45], v[150:153], v[172:175], v[42:45]
	v_mfma_f32_16x16x32_bf16 v[30:33], v[142:145], v[180:183], v[30:33]
	v_mfma_f32_16x16x32_bf16 v[26:29], v[150:153], v[180:183], v[26:29]
	v_mfma_f32_16x16x32_bf16 v[14:17], v[142:145], v[188:191], v[14:17]
	v_mfma_f32_16x16x32_bf16 v[10:13], v[150:153], v[188:191], v[10:13]
	v_mfma_f32_16x16x32_bf16 v[62:65], v[146:149], v[162:165], v[62:65]
	v_mfma_f32_16x16x32_bf16 v[58:61], v[154:157], v[162:165], v[58:61]
	v_mfma_f32_16x16x32_bf16 v[46:49], v[146:149], v[176:179], v[46:49]
	v_mfma_f32_16x16x32_bf16 v[42:45], v[154:157], v[176:179], v[42:45]
	v_mfma_f32_16x16x32_bf16 v[30:33], v[146:149], v[184:187], v[30:33]
	v_mfma_f32_16x16x32_bf16 v[26:29], v[154:157], v[184:187], v[26:29]
	v_mfma_f32_16x16x32_bf16 v[14:17], v[146:149], v[200:203], v[14:17]
	v_mfma_f32_16x16x32_bf16 v[10:13], v[154:157], v[200:203], v[10:13]
	s_barrier
	s_add_u32 s8, s8, 0x40080
	s_addc_u32 s9, s9, 0
	s_add_i32 s56, s56, s77
	v_lshl_add_u64 v[142:143], s[8:9], 0, v[132:133]
	s_mov_b32 m0, s56
	s_nop 0
	global_load_lds_dwordx4 v[142:143], off
	v_lshl_add_u64 v[142:143], s[8:9], 0, v[136:137]
	s_add_i32 m0, s56, 0x2000
	s_nop 0
	global_load_lds_dwordx4 v[142:143], off
	s_waitcnt vmcnt(6)
	s_barrier
	v_mfma_f32_16x16x32_bf16 v[54:57], v[216:219], v[158:161], v[54:57]
	v_mfma_f32_16x16x32_bf16 v[50:53], v[224:227], v[158:161], v[50:53]
	v_mfma_f32_16x16x32_bf16 v[38:41], v[216:219], v[172:175], v[38:41]
	v_mfma_f32_16x16x32_bf16 v[34:37], v[224:227], v[172:175], v[34:37]
	v_mfma_f32_16x16x32_bf16 v[22:25], v[216:219], v[180:183], v[22:25]
	v_mfma_f32_16x16x32_bf16 v[18:21], v[224:227], v[180:183], v[18:21]
	v_mfma_f32_16x16x32_bf16 v[6:9], v[216:219], v[188:191], v[6:9]
	v_mfma_f32_16x16x32_bf16 v[2:5], v[224:227], v[188:191], v[2:5]
	v_mfma_f32_16x16x32_bf16 v[54:57], v[220:223], v[162:165], v[54:57]
	v_mfma_f32_16x16x32_bf16 v[50:53], v[228:231], v[162:165], v[50:53]
	v_mfma_f32_16x16x32_bf16 v[38:41], v[220:223], v[176:179], v[38:41]
	v_mfma_f32_16x16x32_bf16 v[34:37], v[228:231], v[176:179], v[34:37]
	v_mfma_f32_16x16x32_bf16 v[22:25], v[220:223], v[184:187], v[22:25]
	v_mfma_f32_16x16x32_bf16 v[18:21], v[228:231], v[184:187], v[18:21]
	v_mfma_f32_16x16x32_bf16 v[6:9], v[220:223], v[200:203], v[6:9]
	v_mfma_f32_16x16x32_bf16 v[2:5], v[228:231], v[200:203], v[2:5]
	s_add_i32 s89, s89, 2
	s_add_u32 s6, s6, 0x100
	s_addc_u32 s7, s7, 0
	s_add_u32 s62, s62, 0x100
	s_addc_u32 s63, s63, 0
	s_cmp_gt_u32 s89, 13
	s_barrier
	s_cbranch_scc0 .LBB0_738
	s_cmp_lt_i32 s68, 12
	v_mov_b32_e32 v161, 0x7fc00000
	s_cselect_b64 s[6:7], -1, 0
	s_cmp_gt_i32 s68, 11
	v_mov_b32_e32 v160, 0x7fc00000
	v_mov_b32_e32 v159, 0x7fc00000
	v_mov_b32_e32 v158, 0x7fc00000
	v_mov_b32_e32 v157, 0x7fc00000
	v_mov_b32_e32 v156, 0x7fc00000
	v_mov_b32_e32 v155, 0x7fc00000
	v_mov_b32_e32 v154, 0x7fc00000
	v_mov_b32_e32 v149, 0x7fc00000
	v_mov_b32_e32 v148, 0x7fc00000
	v_mov_b32_e32 v147, 0x7fc00000
	v_mov_b32_e32 v146, 0x7fc00000
	v_mov_b32_e32 v145, 0x7fc00000
	v_mov_b32_e32 v144, 0x7fc00000
	v_mov_b32_e32 v143, 0x7fc00000
	v_mov_b32_e32 v142, 0x7fc00000
	s_cbranch_scc1 .LBB0_743
	v_mov_b32_e32 v142, v204
	v_mov_b32_e32 v144, v119
	v_lshlrev_b32_e32 v142, 2, v142
	v_xor_b32_e32 v146, 64, v142
	v_mov_b32_e32 v142, v204
	v_mov_b32_e32 v145, v127
	v_lshlrev_b32_e32 v142, 2, v142
	v_xor_b32_e32 v147, 0x80, v142
	v_mov_b32_e32 v142, v118
	v_mov_b32_e32 v143, v126
	v_pk_mul_f32 v[144:145], v[144:145], v[144:145]
	v_mov_b32_e32 v148, v204
	v_pk_fma_f32 v[142:143], v[142:143], v[142:143], v[144:145]
	v_mov_b32_e32 v144, v120
	v_mov_b32_e32 v145, v128
	v_pk_fma_f32 v[142:143], v[144:145], v[144:145], v[142:143]
	v_mov_b32_e32 v144, v121
	v_mov_b32_e32 v145, v129
	v_pk_fma_f32 v[142:143], v[144:145], v[144:145], v[142:143]
	v_mov_b32_e32 v144, v114
	v_mov_b32_e32 v145, v122
	v_pk_fma_f32 v[142:143], v[144:145], v[144:145], v[142:143]
	v_mov_b32_e32 v144, v115
	v_mov_b32_e32 v145, v123
	v_pk_fma_f32 v[142:143], v[144:145], v[144:145], v[142:143]
	v_mov_b32_e32 v144, v116
	v_mov_b32_e32 v145, v124
	v_lshlrev_b32_e32 v148, 2, v148
	v_pk_fma_f32 v[142:143], v[144:145], v[144:145], v[142:143]
	v_mov_b32_e32 v144, v117
	v_mov_b32_e32 v145, v125
	v_xor_b32_e32 v148, 64, v148
	v_pk_fma_f32 v[142:143], v[144:145], v[144:145], v[142:143]
	ds_bpermute_b32 v145, v146, v143
	ds_bpermute_b32 v144, v148, v142
	v_mov_b32_e32 v149, v204
	v_mov_b32_e32 v146, v103
	v_lshlrev_b32_e32 v149, 2, v149
	v_xor_b32_e32 v149, 0x80, v149
	s_waitcnt lgkmcnt(0)
	v_pk_add_f32 v[142:143], v[142:143], v[144:145]
	ds_bpermute_b32 v145, v147, v143
	ds_bpermute_b32 v144, v149, v142
	v_mov_b32_e32 v147, v111
	v_pk_mul_f32 v[146:147], v[146:147], v[146:147]
	v_mov_b32_e32 v150, v204
	v_mov_b32_e32 v151, v204
	s_waitcnt lgkmcnt(0)
; DI float shx(float v, int m) { return __int_as_float(__builtin_amdgcn_ds_bpermute((lane_now() ^ m) << 2, __float_as_int(v))); }
; DI int shx(int v, int m) { return __builtin_amdgcn_ds_bpermute((lane_now() ^ m) << 2, v); }
;     __device__ __forceinline__ void operator()(const f32x4 (&acc)[2][2][4][2], const Unit& u, int wr, int wc, int fr, int fq) const {
;     ...
;                     for (int bj = 0; bj < 2; ++bj) { const f32x4 a = acc[ai][bj][m][0], b = acc[ai][bj][m][1];
;                         float sq = a[0] * a[0] + a[1] * a[1] + a[2] * a[2] + a[3] * a[3] + b[0] * b[0] + b[1] * b[1] + b[2] * b[2] + b[3] * b[3];
;                         sq += shx(sq, 16); sq += shx(sq, 32); part[ai][m][bj] = sq; }
	v_pk_add_f32 v[142:143], v[142:143], v[144:145]
	v_mov_b32_e32 v144, v204
	v_mov_b32_e32 v145, v110
	v_lshlrev_b32_e32 v144, 2, v144
	v_xor_b32_e32 v148, 64, v144
	v_mov_b32_e32 v144, v204
	v_mov_b32_e32 v152, v204
	v_lshlrev_b32_e32 v144, 2, v144
	v_xor_b32_e32 v149, 0x80, v144
	v_mov_b32_e32 v144, v102
	v_pk_fma_f32 v[144:145], v[144:145], v[144:145], v[146:147]
	v_mov_b32_e32 v146, v104
	v_mov_b32_e32 v147, v112
	v_pk_fma_f32 v[144:145], v[146:147], v[146:147], v[144:145]
	v_mov_b32_e32 v146, v105
	v_mov_b32_e32 v147, v113
	v_pk_fma_f32 v[144:145], v[146:147], v[146:147], v[144:145]
	v_mov_b32_e32 v146, v98
	v_mov_b32_e32 v147, v106
	v_pk_fma_f32 v[144:145], v[146:147], v[146:147], v[144:145]
	v_mov_b32_e32 v146, v99
	v_mov_b32_e32 v147, v107
	v_pk_fma_f32 v[144:145], v[146:147], v[146:147], v[144:145]
	v_mov_b32_e32 v146, v100
	v_mov_b32_e32 v147, v108
	v_lshlrev_b32_e32 v150, 2, v150
	v_pk_fma_f32 v[144:145], v[146:147], v[146:147], v[144:145]
	v_mov_b32_e32 v146, v101
	v_mov_b32_e32 v147, v109
	v_xor_b32_e32 v150, 64, v150
	v_pk_fma_f32 v[144:145], v[146:147], v[146:147], v[144:145]
	ds_bpermute_b32 v147, v148, v145
	ds_bpermute_b32 v146, v150, v144
	v_lshlrev_b32_e32 v151, 2, v151
	v_xor_b32_e32 v151, 0x80, v151
	v_mov_b32_e32 v148, v87
	v_mov_b32_e32 v153, v204
	s_waitcnt lgkmcnt(0)
	v_pk_add_f32 v[144:145], v[144:145], v[146:147]
	ds_bpermute_b32 v147, v149, v145
	ds_bpermute_b32 v146, v151, v144
	v_mov_b32_e32 v149, v95
	v_pk_mul_f32 v[148:149], v[148:149], v[148:149]
	v_mov_b32_e32 v154, v204
	v_mov_b32_e32 v155, v204
	s_waitcnt lgkmcnt(0)
	v_pk_add_f32 v[144:145], v[144:145], v[146:147]
	v_mov_b32_e32 v146, v204
	v_mov_b32_e32 v147, v94
	v_lshlrev_b32_e32 v146, 2, v146
	v_xor_b32_e32 v150, 64, v146
	v_mov_b32_e32 v146, v204
	v_mov_b32_e32 v156, v204
	v_lshlrev_b32_e32 v146, 2, v146
	v_xor_b32_e32 v151, 0x80, v146
	v_mov_b32_e32 v146, v86
	v_pk_fma_f32 v[146:147], v[146:147], v[146:147], v[148:149]
	v_mov_b32_e32 v148, v88
	v_mov_b32_e32 v149, v96
	v_pk_fma_f32 v[146:147], v[148:149], v[148:149], v[146:147]
	v_mov_b32_e32 v148, v89
	v_mov_b32_e32 v149, v97
	v_pk_fma_f32 v[146:147], v[148:149], v[148:149], v[146:147]
	v_mov_b32_e32 v148, v82
	v_mov_b32_e32 v149, v90
	v_pk_fma_f32 v[146:147], v[148:149], v[148:149], v[146:147]
	v_mov_b32_e32 v148, v83
	v_mov_b32_e32 v149, v91
	v_pk_fma_f32 v[146:147], v[148:149], v[148:149], v[146:147]
	v_mov_b32_e32 v148, v84
	v_mov_b32_e32 v149, v92
	v_lshlrev_b32_e32 v152, 2, v152
	v_pk_fma_f32 v[146:147], v[148:149], v[148:149], v[146:147]
	v_mov_b32_e32 v148, v85
	v_mov_b32_e32 v149, v93
	v_xor_b32_e32 v152, 64, v152
	v_pk_fma_f32 v[146:147], v[148:149], v[148:149], v[146:147]
	ds_bpermute_b32 v149, v150, v147
	ds_bpermute_b32 v148, v152, v146
	v_lshlrev_b32_e32 v153, 2, v153
	v_xor_b32_e32 v153, 0x80, v153
	v_mov_b32_e32 v150, v71
	v_mov_b32_e32 v157, v204
	s_waitcnt lgkmcnt(0)
	v_pk_add_f32 v[146:147], v[146:147], v[148:149]
	ds_bpermute_b32 v149, v151, v147
	ds_bpermute_b32 v148, v153, v146
	v_mov_b32_e32 v151, v79
	v_pk_mul_f32 v[150:151], v[150:151], v[150:151]
	v_mov_b32_e32 v158, v204
	v_mov_b32_e32 v159, v204
	s_waitcnt lgkmcnt(0)
	v_pk_add_f32 v[146:147], v[146:147], v[148:149]
	v_mov_b32_e32 v148, v204
	v_mov_b32_e32 v149, v78
	v_lshlrev_b32_e32 v148, 2, v148
	v_xor_b32_e32 v152, 64, v148
	v_mov_b32_e32 v148, v204
	v_mov_b32_e32 v160, v204
	v_lshlrev_b32_e32 v148, 2, v148
	v_xor_b32_e32 v153, 0x80, v148
	v_mov_b32_e32 v148, v70
	v_pk_fma_f32 v[148:149], v[148:149], v[148:149], v[150:151]
	v_mov_b32_e32 v150, v72
	v_mov_b32_e32 v151, v80
	v_pk_fma_f32 v[148:149], v[150:151], v[150:151], v[148:149]
	v_mov_b32_e32 v150, v73
	v_mov_b32_e32 v151, v81
	v_pk_fma_f32 v[148:149], v[150:151], v[150:151], v[148:149]
	v_mov_b32_e32 v150, v66
	v_mov_b32_e32 v151, v74
	v_pk_fma_f32 v[148:149], v[150:151], v[150:151], v[148:149]
	v_mov_b32_e32 v150, v67
	v_mov_b32_e32 v151, v75
	v_pk_fma_f32 v[148:149], v[150:151], v[150:151], v[148:149]
	v_mov_b32_e32 v150, v68
	v_mov_b32_e32 v151, v76
	v_lshlrev_b32_e32 v154, 2, v154
	v_pk_fma_f32 v[148:149], v[150:151], v[150:151], v[148:149]
	v_mov_b32_e32 v150, v69
	v_mov_b32_e32 v151, v77
	v_xor_b32_e32 v154, 64, v154
	v_pk_fma_f32 v[148:149], v[150:151], v[150:151], v[148:149]
	ds_bpermute_b32 v151, v152, v149
	ds_bpermute_b32 v150, v154, v148
	v_lshlrev_b32_e32 v155, 2, v155
	v_xor_b32_e32 v155, 0x80, v155
	v_mov_b32_e32 v152, v55
	v_mov_b32_e32 v161, v204
	s_waitcnt lgkmcnt(0)
	v_pk_add_f32 v[148:149], v[148:149], v[150:151]
	ds_bpermute_b32 v151, v153, v149
	ds_bpermute_b32 v150, v155, v148
	v_mov_b32_e32 v153, v63
	v_pk_mul_f32 v[152:153], v[152:153], v[152:153]
	s_waitcnt lgkmcnt(0)
	v_pk_add_f32 v[148:149], v[148:149], v[150:151]
	v_mov_b32_e32 v150, v204
	v_mov_b32_e32 v151, v62
	v_lshlrev_b32_e32 v150, 2, v150
	v_xor_b32_e32 v154, 64, v150
	v_mov_b32_e32 v150, v204
	s_nop 0
	v_lshlrev_b32_e32 v150, 2, v150
	v_xor_b32_e32 v155, 0x80, v150
	v_mov_b32_e32 v150, v54
	v_pk_fma_f32 v[150:151], v[150:151], v[150:151], v[152:153]
	v_mov_b32_e32 v152, v56
	v_mov_b32_e32 v153, v64
	v_pk_fma_f32 v[150:151], v[152:153], v[152:153], v[150:151]
	v_mov_b32_e32 v152, v57
	v_mov_b32_e32 v153, v65
	v_pk_fma_f32 v[150:151], v[152:153], v[152:153], v[150:151]
	v_mov_b32_e32 v152, v50
	v_mov_b32_e32 v153, v58
	v_pk_fma_f32 v[150:151], v[152:153], v[152:153], v[150:151]
	v_mov_b32_e32 v152, v51
	v_mov_b32_e32 v153, v59
	v_pk_fma_f32 v[150:151], v[152:153], v[152:153], v[150:151]
	v_mov_b32_e32 v152, v52
	v_mov_b32_e32 v153, v60
	v_lshlrev_b32_e32 v156, 2, v156
	v_pk_fma_f32 v[150:151], v[152:153], v[152:153], v[150:151]
	v_mov_b32_e32 v152, v53
	v_mov_b32_e32 v153, v61
	v_xor_b32_e32 v156, 64, v156
	v_pk_fma_f32 v[150:151], v[152:153], v[152:153], v[150:151]
	ds_bpermute_b32 v153, v154, v151
	ds_bpermute_b32 v152, v156, v150
	v_lshlrev_b32_e32 v157, 2, v157
	v_xor_b32_e32 v157, 0x80, v157
	v_mov_b32_e32 v154, v39
	s_waitcnt lgkmcnt(0)
; DI float shx(float v, int m) { return __int_as_float(__builtin_amdgcn_ds_bpermute((lane_now() ^ m) << 2, __float_as_int(v))); }
; DI int shx(int v, int m) { return __builtin_amdgcn_ds_bpermute((lane_now() ^ m) << 2, v); }
; #define PG8_LAS __attribute__((address_space(3)))
;     __device__ __forceinline__ void operator()(const f32x4 (&acc)[2][2][4][2], const Unit& u, int wr, int wc, int fr, int fq) const {
;     ...
;                     for (int bj = 0; bj < 2; ++bj) { const f32x4 a = acc[ai][bj][m][0], b = acc[ai][bj][m][1];
;                         float sq = a[0] * a[0] + a[1] * a[1] + a[2] * a[2] + a[3] * a[3] + b[0] * b[0] + b[1] * b[1] + b[2] * b[2] + b[3] * b[3];
;                         sq += shx(sq, 16); sq += shx(sq, 32); part[ai][m][bj] = sq; }
;             PG8_LAS float* mine = T + ((wr * 4 + wc) * 16) * 16 + fr;
;             if (fq == 0) {
; #pragma unroll
;                 for (int ai = 0; ai < 2; ++ai)
; #pragma unroll
;                     for (int m = 0; m < 4; ++m)
; #pragma unroll
;                         for (int bj = 0; bj < 2; ++bj) mine[((ai * 4 + m) * 2 + bj) * 16] = part[ai][m][bj];
;             }
	v_pk_add_f32 v[150:151], v[150:151], v[152:153]
	ds_bpermute_b32 v153, v155, v151
	ds_bpermute_b32 v152, v157, v150
	v_mov_b32_e32 v155, v47
	v_pk_mul_f32 v[154:155], v[154:155], v[154:155]
	s_waitcnt lgkmcnt(0)
	v_pk_add_f32 v[150:151], v[150:151], v[152:153]
	v_mov_b32_e32 v152, v204
	v_mov_b32_e32 v153, v46
	v_lshlrev_b32_e32 v152, 2, v152
	v_xor_b32_e32 v156, 64, v152
	v_mov_b32_e32 v152, v204
	s_nop 0
	v_lshlrev_b32_e32 v152, 2, v152
	v_xor_b32_e32 v157, 0x80, v152
	v_mov_b32_e32 v152, v38
	v_pk_fma_f32 v[152:153], v[152:153], v[152:153], v[154:155]
	v_mov_b32_e32 v154, v40
	v_mov_b32_e32 v155, v48
	v_pk_fma_f32 v[152:153], v[154:155], v[154:155], v[152:153]
	v_mov_b32_e32 v154, v41
	v_mov_b32_e32 v155, v49
	v_pk_fma_f32 v[152:153], v[154:155], v[154:155], v[152:153]
	v_mov_b32_e32 v154, v34
	v_mov_b32_e32 v155, v42
	v_pk_fma_f32 v[152:153], v[154:155], v[154:155], v[152:153]
	v_mov_b32_e32 v154, v35
	v_mov_b32_e32 v155, v43
	v_pk_fma_f32 v[152:153], v[154:155], v[154:155], v[152:153]
	v_mov_b32_e32 v154, v36
	v_mov_b32_e32 v155, v44
	v_lshlrev_b32_e32 v158, 2, v158
	v_pk_fma_f32 v[152:153], v[154:155], v[154:155], v[152:153]
	v_mov_b32_e32 v154, v37
	v_mov_b32_e32 v155, v45
	v_xor_b32_e32 v158, 64, v158
	v_pk_fma_f32 v[152:153], v[154:155], v[154:155], v[152:153]
	ds_bpermute_b32 v155, v156, v153
	ds_bpermute_b32 v154, v158, v152
	v_lshlrev_b32_e32 v159, 2, v159
	v_xor_b32_e32 v159, 0x80, v159
	v_mov_b32_e32 v156, v23
	s_waitcnt lgkmcnt(0)
	v_pk_add_f32 v[152:153], v[152:153], v[154:155]
	ds_bpermute_b32 v155, v157, v153
	ds_bpermute_b32 v154, v159, v152
	v_mov_b32_e32 v157, v31
	v_pk_mul_f32 v[156:157], v[156:157], v[156:157]
	s_waitcnt lgkmcnt(0)
	v_pk_add_f32 v[152:153], v[152:153], v[154:155]
	v_mov_b32_e32 v154, v204
	v_mov_b32_e32 v155, v30
	v_lshlrev_b32_e32 v154, 2, v154
	v_xor_b32_e32 v158, 64, v154
	v_mov_b32_e32 v154, v204
	s_nop 0
	v_lshlrev_b32_e32 v154, 2, v154
	v_xor_b32_e32 v159, 0x80, v154
	v_mov_b32_e32 v154, v22
	v_pk_fma_f32 v[154:155], v[154:155], v[154:155], v[156:157]
	v_mov_b32_e32 v156, v24
	v_mov_b32_e32 v157, v32
	v_pk_fma_f32 v[154:155], v[156:157], v[156:157], v[154:155]
	v_mov_b32_e32 v156, v25
	v_mov_b32_e32 v157, v33
	v_pk_fma_f32 v[154:155], v[156:157], v[156:157], v[154:155]
	v_mov_b32_e32 v156, v18
	v_mov_b32_e32 v157, v26
	v_pk_fma_f32 v[154:155], v[156:157], v[156:157], v[154:155]
	v_mov_b32_e32 v156, v19
	v_mov_b32_e32 v157, v27
	v_pk_fma_f32 v[154:155], v[156:157], v[156:157], v[154:155]
	v_mov_b32_e32 v156, v20
	v_mov_b32_e32 v157, v28
	v_lshlrev_b32_e32 v160, 2, v160
	v_pk_fma_f32 v[154:155], v[156:157], v[156:157], v[154:155]
	v_mov_b32_e32 v156, v21
	v_mov_b32_e32 v157, v29
	v_xor_b32_e32 v160, 64, v160
	v_pk_fma_f32 v[154:155], v[156:157], v[156:157], v[154:155]
	ds_bpermute_b32 v157, v158, v155
	ds_bpermute_b32 v156, v160, v154
	v_lshlrev_b32_e32 v161, 2, v161
	v_xor_b32_e32 v161, 0x80, v161
	v_mov_b32_e32 v160, v204
	s_waitcnt lgkmcnt(0)
	v_pk_add_f32 v[154:155], v[154:155], v[156:157]
	ds_bpermute_b32 v157, v159, v155
	ds_bpermute_b32 v156, v161, v154
	v_mov_b32_e32 v161, v204
	s_waitcnt lgkmcnt(0)
	v_pk_add_f32 v[162:163], v[154:155], v[156:157]
	v_mov_b32_e32 v154, v204
	v_mov_b32_e32 v156, v7
	v_lshlrev_b32_e32 v154, 2, v154
	v_xor_b32_e32 v158, 64, v154
	v_mov_b32_e32 v154, v204
	v_mov_b32_e32 v157, v15
	v_lshlrev_b32_e32 v154, 2, v154
	v_xor_b32_e32 v159, 0x80, v154
	v_mov_b32_e32 v154, v6
	v_mov_b32_e32 v155, v14
	v_pk_mul_f32 v[156:157], v[156:157], v[156:157]
	s_nop 0
	v_pk_fma_f32 v[154:155], v[154:155], v[154:155], v[156:157]
	v_mov_b32_e32 v156, v8
	v_mov_b32_e32 v157, v16
	v_pk_fma_f32 v[154:155], v[156:157], v[156:157], v[154:155]
	v_mov_b32_e32 v156, v9
	v_mov_b32_e32 v157, v17
	v_pk_fma_f32 v[154:155], v[156:157], v[156:157], v[154:155]
	v_mov_b32_e32 v156, v2
	v_mov_b32_e32 v157, v10
	v_pk_fma_f32 v[154:155], v[156:157], v[156:157], v[154:155]
	v_mov_b32_e32 v156, v3
	v_mov_b32_e32 v157, v11
	v_pk_fma_f32 v[154:155], v[156:157], v[156:157], v[154:155]
	v_mov_b32_e32 v156, v4
	v_mov_b32_e32 v157, v12
	v_lshlrev_b32_e32 v160, 2, v160
	v_pk_fma_f32 v[154:155], v[156:157], v[156:157], v[154:155]
	v_mov_b32_e32 v156, v5
	v_mov_b32_e32 v157, v13
	v_xor_b32_e32 v160, 64, v160
	v_pk_fma_f32 v[154:155], v[156:157], v[156:157], v[154:155]
	ds_bpermute_b32 v157, v158, v155
	ds_bpermute_b32 v156, v160, v154
	v_lshlrev_b32_e32 v161, 2, v161
	v_xor_b32_e32 v161, 0x80, v161
	s_waitcnt lgkmcnt(0)
	v_pk_add_f32 v[154:155], v[154:155], v[156:157]
	ds_bpermute_b32 v157, v159, v155
	ds_bpermute_b32 v156, v161, v154
	s_waitcnt lgkmcnt(0)
	v_pk_add_f32 v[164:165], v[154:155], v[156:157]
	s_and_saveexec_b64 s[8:9], s[2:3]
	s_cbranch_execz .LBB0_742
	ds_write2_b32 v168, v143, v142 offset1:16
	ds_write2_b32 v168, v145, v144 offset0:32 offset1:48
	ds_write2_b32 v168, v147, v146 offset0:64 offset1:80
	ds_write2_b32 v168, v149, v148 offset0:96 offset1:112
	ds_write2_b32 v168, v151, v150 offset0:128 offset1:144
	ds_write2_b32 v168, v153, v152 offset0:160 offset1:176
	ds_write2_b32 v168, v163, v162 offset0:192 offset1:208
	ds_write2_b32 v168, v165, v164 offset0:224 offset1:240

; __global__ void __launch_bounds__(512, 2) mega(Params pp) {
;     ...
;   for (int ph = pp.ph0; ph < pp.ph1; ++ph) {
;     ...
;     const bool noseam = (op == OP_CONVERT) && half;
;     if (ph + 1 < pp.ph1 && !noseam) xcd_barrier(ws_, smem0, tidx(wv8_) == 0);
;   }
.LBB0_848:
	s_setprio 0
	s_cmp_eq_u32 s23, 0
	v_readlane_b32 s2, v255, 1
	s_cselect_b64 s[0:1], -1, 0
	s_cmp_lg_u32 s2, 0
	s_cselect_b64 s[2:3], -1, 0
	v_readlane_b32 s64, v255, 0
	s_and_b64 s[0:1], s[0:1], s[2:3]
	s_add_i32 s64, s64, 1
	v_readlane_b32 s2, v252, 1
	s_cmp_ge_i32 s64, s2
	s_cselect_b64 s[2:3], -1, 0
	s_or_b64 s[0:1], s[0:1], s[2:3]
	v_readlane_b32 s70, v254, 60
	s_and_b64 vcc, exec, s[0:1]
	v_readlane_b32 s62, v254, 46
	v_readlane_b32 s44, v254, 48
	v_readlane_b32 s68, v254, 50
	v_readlane_b32 s18, v254, 52
	v_readlane_b32 s54, v254, 54
	v_readlane_b32 s0, v254, 56
	v_readlane_b32 s71, v254, 61
	v_readlane_b32 s63, v254, 47
	v_readlane_b32 s45, v254, 49
	v_readlane_b32 s69, v254, 51
	v_readlane_b32 s19, v254, 53
	v_readlane_b32 s55, v254, 55
	v_readlane_b32 s1, v254, 57
	s_cbranch_vccz .LBB0_849
	s_getpc_b64 s[98:99]
